# scan step: removed the unneeded wait-state nop between the two state-update halves (on top of the staging and attention V-read trims)
# speedup vs baseline: 1.0096x; 1.0096x over previous
; #define LAS __attribute__((address_space(3)))
; __device__ __forceinline__ float red8(float x) { x += dpp_mov<0xB1>(x); x += dpp_mov<0x4E>(x); x += dpp_mov<0x141>(x); return x; }
; __device__ __forceinline__ void scan_phase(const KP& P, LAS unsigned char* lds, const int tid, const int bx, const int G) {
;     ...
;         for (int c = 0; c < NCH; ++c) {
;             if (c + 1 < NCH) SC_LOAD(c + 1);
;             const LAS float* cb = buf + (c & 1) * 12288 + kc * 8;
; #pragma unroll 16
;             for (int s = 0; s < 32; ++s) {
;                 const LAS float* p = cb + s * 384;
;                 const f32x4 w0 = *(const LAS f32x4*)(p), w1 = *(const LAS f32x4*)(p + 4);
;                 const f32x4 k0 = *(const LAS f32x4*)(p + 64), k1 = *(const LAS f32x4*)(p + 68);
;                 const f32x4 a0 = *(const LAS f32x4*)(p + 128), a1 = *(const LAS f32x4*)(p + 132);
;                 const f32x4 b0 = *(const LAS f32x4*)(p + 192), b1 = *(const LAS f32x4*)(p + 196);
;                 const f32x4 r0 = *(const LAS f32x4*)(p + 256), r1 = *(const LAS f32x4*)(p + 260);
;                 const float vv = buf[(c & 1) * 12288 + s * 384 + 320 + v];
;                 f32x2 sa2 = S[0] * (f32x2){a0.x, a0.y};
;                 sa2 += S[1] * (f32x2){a0.z, a0.w}; sa2 += S[2] * (f32x2){a1.x, a1.y}; sa2 += S[3] * (f32x2){a1.z, a1.w};
;                 const float sa = red8(sa2.x + sa2.y);
;                 const f32x2 sav = {sa, sa}, vv2 = {vv, vv};
;                 S[0] = S[0] * (f32x2){w0.x, w0.y} + sav * (f32x2){b0.x, b0.y} + vv2 * (f32x2){k0.x, k0.y};
;                 S[1] = S[1] * (f32x2){w0.z, w0.w} + sav * (f32x2){b0.z, b0.w} + vv2 * (f32x2){k0.z, k0.w};
;                 S[2] = S[2] * (f32x2){w1.x, w1.y} + sav * (f32x2){b1.x, b1.y} + vv2 * (f32x2){k1.x, k1.y};
;                 S[3] = S[3] * (f32x2){w1.z, w1.w} + sav * (f32x2){b1.z, b1.w} + vv2 * (f32x2){k1.z, k1.w};
;                 f32x2 y2 = S[0] * (f32x2){r0.x, r0.y};
;                 y2 += S[1] * (f32x2){r0.z, r0.w}; y2 += S[2] * (f32x2){r1.x, r1.y}; y2 += S[3] * (f32x2){r1.z, r1.w};
;                 const float y = red8(y2.x + y2.y);
;                 if (kc == 0) ybuf[s * 64 + v] = y;
;             }
.Lscan_compute:
	s_bitcmp1_b32 s3, 0
	s_cselect_b32 s0, 0xc000, 0
	v_lshlrev_b32_e32 v45, 1, v58
	v_or_b32_e32 v44, s0, v56
	v_add_u32_e32 v46, s0, v45
	v_add_u32_e32 v46, 0x500, v46
	v_bfe_u32 v47, v166, 2, 1
	v_lshl_add_u32 v45, v47, 8, v45
	v_add_u32_e32 v45, 0x18000, v45
	v_and_b32_e32 v47, 3, v166
	v_cmp_eq_u32_e64 s[86:87], 0, v47
	s_mov_b64 s[0:1], exec
	ds_read_b128 v[148:151], v44 offset:512
	ds_read_b128 v[152:155], v44 offset:528
	ds_read_b128 v[156:159], v44 offset:2048
	ds_read_b128 v[160:163], v44 offset:2064
	ds_read_b128 v[120:123], v44 offset:256
	ds_read_b128 v[124:127], v44 offset:272
	ds_read_b128 v[128:131], v44 offset:768
	ds_read_b128 v[132:135], v44 offset:784
	ds_read_b128 v[136:139], v44 offset:1024
	ds_read_b128 v[140:143], v44 offset:1040
	ds_read_b64 v[144:145], v46 offset:0
	ds_read_b128 v[112:115], v44 offset:47616
	ds_read_b128 v[116:119], v44 offset:47632
	ds_read_b128 v[62:65], v44 offset:3584
	ds_read_b128 v[66:69], v44 offset:3600
	ds_read_b128 v[70:73], v44 offset:1792
	ds_read_b128 v[74:77], v44 offset:1808
	ds_read_b128 v[78:81], v44 offset:2304
	ds_read_b128 v[82:85], v44 offset:2320
	ds_read_b128 v[86:89], v44 offset:2560
	ds_read_b128 v[90:93], v44 offset:2576
	ds_read_b64 v[146:147], v46 offset:1536
	s_waitcnt lgkmcnt(15)
	v_pk_mul_f32 v[50:51], v[96:97], v[148:149] op_sel:[0,0] op_sel_hi:[1,0]
	s_nop 0
	v_pk_fma_f32 v[50:51], v[98:99], v[148:149], v[50:51] op_sel:[0,1,0] op_sel_hi:[1,1,1]
	s_nop 0
	v_pk_fma_f32 v[50:51], v[100:101], v[150:151], v[50:51] op_sel:[0,0,0] op_sel_hi:[1,0,1]
	s_nop 0
	v_pk_fma_f32 v[50:51], v[102:103], v[150:151], v[50:51] op_sel:[0,1,0] op_sel_hi:[1,1,1]
	s_nop 0
	v_pk_fma_f32 v[50:51], v[104:105], v[152:153], v[50:51] op_sel:[0,0,0] op_sel_hi:[1,0,1]
	s_nop 0
	v_pk_fma_f32 v[50:51], v[106:107], v[152:153], v[50:51] op_sel:[0,1,0] op_sel_hi:[1,1,1]
	s_nop 0
	v_pk_fma_f32 v[50:51], v[108:109], v[154:155], v[50:51] op_sel:[0,0,0] op_sel_hi:[1,0,1]
	s_nop 0
	v_pk_fma_f32 v[50:51], v[110:111], v[154:155], v[50:51] op_sel:[0,1,0] op_sel_hi:[1,1,1]
	s_nop 0
	s_waitcnt lgkmcnt(9)
	ds_read_b128 v[168:171], v44 offset:3328
	ds_read_b128 v[172:175], v44 offset:3344
	ds_read_b128 v[176:179], v44 offset:3840
	ds_read_b128 v[180:183], v44 offset:3856
	ds_read_b128 v[184:187], v44 offset:4096
	ds_read_b128 v[188:191], v44 offset:4112
	ds_read_b64 v[192:193], v46 offset:3072
	ds_read_b128 v[148:151], v44 offset:5120
	ds_read_b128 v[152:155], v44 offset:5136
	v_add_f32_dpp v50, v50, v50 quad_perm:[1,0,3,2] row_mask:0xf bank_mask:0xf bound_ctrl:1
	v_add_f32_dpp v51, v51, v51 quad_perm:[1,0,3,2] row_mask:0xf bank_mask:0xf bound_ctrl:1
	v_pk_fma_f32 v[96:97], v[144:145], v[120:121], v[96:97] op_sel:[0,0,0] op_sel_hi:[1,0,1]
	v_pk_fma_f32 v[98:99], v[144:145], v[120:121], v[98:99] op_sel:[0,1,0] op_sel_hi:[1,1,1]
	v_pk_fma_f32 v[100:101], v[144:145], v[122:123], v[100:101] op_sel:[0,0,0] op_sel_hi:[1,0,1]
	v_add_f32_dpp v50, v50, v50 quad_perm:[2,3,0,1] row_mask:0xf bank_mask:0xf bound_ctrl:1
	v_add_f32_dpp v51, v51, v51 quad_perm:[2,3,0,1] row_mask:0xf bank_mask:0xf bound_ctrl:1
	v_pk_fma_f32 v[102:103], v[144:145], v[122:123], v[102:103] op_sel:[0,1,0] op_sel_hi:[1,1,1]
	v_pk_fma_f32 v[104:105], v[144:145], v[124:125], v[104:105] op_sel:[0,0,0] op_sel_hi:[1,0,1]
	v_pk_fma_f32 v[106:107], v[144:145], v[124:125], v[106:107] op_sel:[0,1,0] op_sel_hi:[1,1,1]
	v_add_f32_dpp v50, v50, v50 row_half_mirror row_mask:0xf bank_mask:0xf bound_ctrl:1
	v_add_f32_dpp v51, v51, v51 row_half_mirror row_mask:0xf bank_mask:0xf bound_ctrl:1
	v_pk_fma_f32 v[108:109], v[144:145], v[126:127], v[108:109] op_sel:[0,0,0] op_sel_hi:[1,0,1]
	v_pk_fma_f32 v[110:111], v[144:145], v[126:127], v[110:111] op_sel:[0,1,0] op_sel_hi:[1,1,1]
	v_pk_fma_f32 v[96:97], v[50:51], v[128:129], v[96:97] op_sel:[0,0,0] op_sel_hi:[1,0,1]
	v_pk_fma_f32 v[98:99], v[50:51], v[128:129], v[98:99] op_sel:[0,1,0] op_sel_hi:[1,1,1]
	v_pk_fma_f32 v[100:101], v[50:51], v[130:131], v[100:101] op_sel:[0,0,0] op_sel_hi:[1,0,1]
	v_pk_fma_f32 v[102:103], v[50:51], v[130:131], v[102:103] op_sel:[0,1,0] op_sel_hi:[1,1,1]
	v_pk_fma_f32 v[104:105], v[50:51], v[132:133], v[104:105] op_sel:[0,0,0] op_sel_hi:[1,0,1]
	v_pk_fma_f32 v[106:107], v[50:51], v[132:133], v[106:107] op_sel:[0,1,0] op_sel_hi:[1,1,1]
	v_pk_fma_f32 v[108:109], v[50:51], v[134:135], v[108:109] op_sel:[0,0,0] op_sel_hi:[1,0,1]
	v_pk_fma_f32 v[110:111], v[50:51], v[134:135], v[110:111] op_sel:[0,1,0] op_sel_hi:[1,1,1]
	v_pk_mul_f32 v[48:49], v[96:97], v[136:137] op_sel:[0,0] op_sel_hi:[1,0]
	v_pk_mul_f32 v[50:51], v[96:97], v[156:157] op_sel:[0,0] op_sel_hi:[1,0]
	v_pk_fma_f32 v[48:49], v[98:99], v[136:137], v[48:49] op_sel:[0,1,0] op_sel_hi:[1,1,1]
	v_pk_fma_f32 v[50:51], v[98:99], v[156:157], v[50:51] op_sel:[0,1,0] op_sel_hi:[1,1,1]
	v_pk_fma_f32 v[48:49], v[100:101], v[138:139], v[48:49] op_sel:[0,0,0] op_sel_hi:[1,0,1]
	v_pk_fma_f32 v[50:51], v[100:101], v[158:159], v[50:51] op_sel:[0,0,0] op_sel_hi:[1,0,1]
	v_pk_fma_f32 v[48:49], v[102:103], v[138:139], v[48:49] op_sel:[0,1,0] op_sel_hi:[1,1,1]
	v_pk_fma_f32 v[50:51], v[102:103], v[158:159], v[50:51] op_sel:[0,1,0] op_sel_hi:[1,1,1]
	v_pk_fma_f32 v[48:49], v[104:105], v[140:141], v[48:49] op_sel:[0,0,0] op_sel_hi:[1,0,1]
	v_pk_fma_f32 v[50:51], v[104:105], v[160:161], v[50:51] op_sel:[0,0,0] op_sel_hi:[1,0,1]
	v_pk_fma_f32 v[48:49], v[106:107], v[140:141], v[48:49] op_sel:[0,1,0] op_sel_hi:[1,1,1]
	v_pk_fma_f32 v[50:51], v[106:107], v[160:161], v[50:51] op_sel:[0,1,0] op_sel_hi:[1,1,1]
	v_pk_fma_f32 v[48:49], v[108:109], v[142:143], v[48:49] op_sel:[0,0,0] op_sel_hi:[1,0,1]
	v_pk_fma_f32 v[50:51], v[108:109], v[162:163], v[50:51] op_sel:[0,0,0] op_sel_hi:[1,0,1]
	v_pk_fma_f32 v[48:49], v[110:111], v[142:143], v[48:49] op_sel:[0,1,0] op_sel_hi:[1,1,1]
	v_pk_fma_f32 v[50:51], v[110:111], v[162:163], v[50:51] op_sel:[0,1,0] op_sel_hi:[1,1,1]
	s_waitcnt lgkmcnt(9)
; #define LAS __attribute__((address_space(3)))
; __device__ __forceinline__ float red8(float x) { x += dpp_mov<0xB1>(x); x += dpp_mov<0x4E>(x); x += dpp_mov<0x141>(x); return x; }
; __device__ __forceinline__ void scan_phase(const KP& P, LAS unsigned char* lds, const int tid, const int bx, const int G) {
;     ...
;             for (int s = 0; s < 32; ++s) {
;                 const LAS float* p = cb + s * 384;
;                 const f32x4 w0 = *(const LAS f32x4*)(p), w1 = *(const LAS f32x4*)(p + 4);
;                 const f32x4 k0 = *(const LAS f32x4*)(p + 64), k1 = *(const LAS f32x4*)(p + 68);
;                 const f32x4 a0 = *(const LAS f32x4*)(p + 128), a1 = *(const LAS f32x4*)(p + 132);
;                 const f32x4 b0 = *(const LAS f32x4*)(p + 192), b1 = *(const LAS f32x4*)(p + 196);
;                 const f32x4 r0 = *(const LAS f32x4*)(p + 256), r1 = *(const LAS f32x4*)(p + 260);
;                 const float vv = buf[(c & 1) * 12288 + s * 384 + 320 + v];
;                 f32x2 sa2 = S[0] * (f32x2){a0.x, a0.y};
;                 sa2 += S[1] * (f32x2){a0.z, a0.w}; sa2 += S[2] * (f32x2){a1.x, a1.y}; sa2 += S[3] * (f32x2){a1.z, a1.w};
;                 const float sa = red8(sa2.x + sa2.y);
;                 const f32x2 sav = {sa, sa}, vv2 = {vv, vv};
;                 S[0] = S[0] * (f32x2){w0.x, w0.y} + sav * (f32x2){b0.x, b0.y} + vv2 * (f32x2){k0.x, k0.y};
;                 S[1] = S[1] * (f32x2){w0.z, w0.w} + sav * (f32x2){b0.z, b0.w} + vv2 * (f32x2){k0.z, k0.w};
;                 S[2] = S[2] * (f32x2){w1.x, w1.y} + sav * (f32x2){b1.x, b1.y} + vv2 * (f32x2){k1.x, k1.y};
;                 S[3] = S[3] * (f32x2){w1.z, w1.w} + sav * (f32x2){b1.z, b1.w} + vv2 * (f32x2){k1.z, k1.w};
;                 f32x2 y2 = S[0] * (f32x2){r0.x, r0.y};
;                 y2 += S[1] * (f32x2){r0.z, r0.w}; y2 += S[2] * (f32x2){r1.x, r1.y}; y2 += S[3] * (f32x2){r1.z, r1.w};
;                 const float y = red8(y2.x + y2.y);
;                 if (kc == 0) ybuf[s * 64 + v] = y;
;             }
	ds_read_b128 v[120:123], v44 offset:4864
	ds_read_b128 v[124:127], v44 offset:4880
	ds_read_b128 v[128:131], v44 offset:5376
	ds_read_b128 v[132:135], v44 offset:5392
	ds_read_b128 v[136:139], v44 offset:5632
	ds_read_b128 v[140:143], v44 offset:5648
	ds_read_b64 v[144:145], v46 offset:4608
	ds_read_b128 v[156:159], v44 offset:6656
	ds_read_b128 v[160:163], v44 offset:6672
	v_add_f32_dpp v48, v48, v48 quad_perm:[1,0,3,2] row_mask:0xf bank_mask:0xf bound_ctrl:1
	v_add_f32_dpp v49, v49, v49 quad_perm:[1,0,3,2] row_mask:0xf bank_mask:0xf bound_ctrl:1
	v_add_f32_dpp v50, v50, v50 quad_perm:[1,0,3,2] row_mask:0xf bank_mask:0xf bound_ctrl:1
	v_add_f32_dpp v51, v51, v51 quad_perm:[1,0,3,2] row_mask:0xf bank_mask:0xf bound_ctrl:1
	v_pk_fma_f32 v[96:97], v[146:147], v[70:71], v[96:97] op_sel:[0,0,0] op_sel_hi:[1,0,1]
	v_pk_fma_f32 v[98:99], v[146:147], v[70:71], v[98:99] op_sel:[0,1,0] op_sel_hi:[1,1,1]
	v_pk_fma_f32 v[100:101], v[146:147], v[72:73], v[100:101] op_sel:[0,0,0] op_sel_hi:[1,0,1]
	v_add_f32_dpp v48, v48, v48 quad_perm:[2,3,0,1] row_mask:0xf bank_mask:0xf bound_ctrl:1
	v_add_f32_dpp v49, v49, v49 quad_perm:[2,3,0,1] row_mask:0xf bank_mask:0xf bound_ctrl:1
	v_add_f32_dpp v50, v50, v50 quad_perm:[2,3,0,1] row_mask:0xf bank_mask:0xf bound_ctrl:1
	v_add_f32_dpp v51, v51, v51 quad_perm:[2,3,0,1] row_mask:0xf bank_mask:0xf bound_ctrl:1
	v_pk_fma_f32 v[102:103], v[146:147], v[72:73], v[102:103] op_sel:[0,1,0] op_sel_hi:[1,1,1]
	v_pk_fma_f32 v[104:105], v[146:147], v[74:75], v[104:105] op_sel:[0,0,0] op_sel_hi:[1,0,1]
	v_pk_fma_f32 v[106:107], v[146:147], v[74:75], v[106:107] op_sel:[0,1,0] op_sel_hi:[1,1,1]
	v_add_f32_dpp v50, v50, v50 row_half_mirror row_mask:0xf bank_mask:0xf bound_ctrl:1
	v_add_f32_dpp v51, v51, v51 row_half_mirror row_mask:0xf bank_mask:0xf bound_ctrl:1
	v_pk_fma_f32 v[108:109], v[146:147], v[76:77], v[108:109] op_sel:[0,0,0] op_sel_hi:[1,0,1]
	s_mov_b64 exec, s[86:87]
	ds_write_b64 v45, v[48:49] offset:0
	s_mov_b64 exec, s[0:1]
	v_pk_fma_f32 v[110:111], v[146:147], v[76:77], v[110:111] op_sel:[0,1,0] op_sel_hi:[1,1,1]
	v_pk_fma_f32 v[96:97], v[50:51], v[78:79], v[96:97] op_sel:[0,0,0] op_sel_hi:[1,0,1]
	v_pk_fma_f32 v[98:99], v[50:51], v[78:79], v[98:99] op_sel:[0,1,0] op_sel_hi:[1,1,1]
	v_pk_fma_f32 v[100:101], v[50:51], v[80:81], v[100:101] op_sel:[0,0,0] op_sel_hi:[1,0,1]
	v_pk_fma_f32 v[102:103], v[50:51], v[80:81], v[102:103] op_sel:[0,1,0] op_sel_hi:[1,1,1]
	v_pk_fma_f32 v[104:105], v[50:51], v[82:83], v[104:105] op_sel:[0,0,0] op_sel_hi:[1,0,1]
	v_pk_fma_f32 v[106:107], v[50:51], v[82:83], v[106:107] op_sel:[0,1,0] op_sel_hi:[1,1,1]
	v_pk_fma_f32 v[108:109], v[50:51], v[84:85], v[108:109] op_sel:[0,0,0] op_sel_hi:[1,0,1]
	v_pk_fma_f32 v[110:111], v[50:51], v[84:85], v[110:111] op_sel:[0,1,0] op_sel_hi:[1,1,1]
	v_pk_mul_f32 v[48:49], v[96:97], v[86:87] op_sel:[0,0] op_sel_hi:[1,0]
	v_pk_mul_f32 v[50:51], v[96:97], v[62:63] op_sel:[0,0] op_sel_hi:[1,0]
	v_pk_fma_f32 v[48:49], v[98:99], v[86:87], v[48:49] op_sel:[0,1,0] op_sel_hi:[1,1,1]
	v_pk_fma_f32 v[50:51], v[98:99], v[62:63], v[50:51] op_sel:[0,1,0] op_sel_hi:[1,1,1]
	v_pk_fma_f32 v[48:49], v[100:101], v[88:89], v[48:49] op_sel:[0,0,0] op_sel_hi:[1,0,1]
	v_pk_fma_f32 v[50:51], v[100:101], v[64:65], v[50:51] op_sel:[0,0,0] op_sel_hi:[1,0,1]
	v_pk_fma_f32 v[48:49], v[102:103], v[88:89], v[48:49] op_sel:[0,1,0] op_sel_hi:[1,1,1]
	v_pk_fma_f32 v[50:51], v[102:103], v[64:65], v[50:51] op_sel:[0,1,0] op_sel_hi:[1,1,1]
	v_pk_fma_f32 v[48:49], v[104:105], v[90:91], v[48:49] op_sel:[0,0,0] op_sel_hi:[1,0,1]
	v_pk_fma_f32 v[50:51], v[104:105], v[66:67], v[50:51] op_sel:[0,0,0] op_sel_hi:[1,0,1]
	v_pk_fma_f32 v[48:49], v[106:107], v[90:91], v[48:49] op_sel:[0,1,0] op_sel_hi:[1,1,1]
	v_pk_fma_f32 v[50:51], v[106:107], v[66:67], v[50:51] op_sel:[0,1,0] op_sel_hi:[1,1,1]
	v_pk_fma_f32 v[48:49], v[108:109], v[92:93], v[48:49] op_sel:[0,0,0] op_sel_hi:[1,0,1]
	v_pk_fma_f32 v[50:51], v[108:109], v[68:69], v[50:51] op_sel:[0,0,0] op_sel_hi:[1,0,1]
	v_pk_fma_f32 v[48:49], v[110:111], v[92:93], v[48:49] op_sel:[0,1,0] op_sel_hi:[1,1,1]
	v_pk_fma_f32 v[50:51], v[110:111], v[68:69], v[50:51] op_sel:[0,1,0] op_sel_hi:[1,1,1]
	s_waitcnt lgkmcnt(10)
	ds_read_b128 v[70:73], v44 offset:6400
	ds_read_b128 v[74:77], v44 offset:6416
	ds_read_b128 v[78:81], v44 offset:6912
	ds_read_b128 v[82:85], v44 offset:6928
	ds_read_b128 v[86:89], v44 offset:7168
	ds_read_b128 v[90:93], v44 offset:7184
	ds_read_b64 v[146:147], v46 offset:6144
	ds_read_b128 v[62:65], v44 offset:8192
	ds_read_b128 v[66:69], v44 offset:8208
	v_add_f32_dpp v48, v48, v48 quad_perm:[1,0,3,2] row_mask:0xf bank_mask:0xf bound_ctrl:1
	v_add_f32_dpp v49, v49, v49 quad_perm:[1,0,3,2] row_mask:0xf bank_mask:0xf bound_ctrl:1
	v_add_f32_dpp v50, v50, v50 quad_perm:[1,0,3,2] row_mask:0xf bank_mask:0xf bound_ctrl:1
	v_add_f32_dpp v51, v51, v51 quad_perm:[1,0,3,2] row_mask:0xf bank_mask:0xf bound_ctrl:1
	v_pk_fma_f32 v[96:97], v[192:193], v[168:169], v[96:97] op_sel:[0,0,0] op_sel_hi:[1,0,1]
	v_pk_fma_f32 v[98:99], v[192:193], v[168:169], v[98:99] op_sel:[0,1,0] op_sel_hi:[1,1,1]
	v_pk_fma_f32 v[100:101], v[192:193], v[170:171], v[100:101] op_sel:[0,0,0] op_sel_hi:[1,0,1]
	v_add_f32_dpp v48, v48, v48 quad_perm:[2,3,0,1] row_mask:0xf bank_mask:0xf bound_ctrl:1
	v_add_f32_dpp v49, v49, v49 quad_perm:[2,3,0,1] row_mask:0xf bank_mask:0xf bound_ctrl:1
	v_add_f32_dpp v50, v50, v50 quad_perm:[2,3,0,1] row_mask:0xf bank_mask:0xf bound_ctrl:1
	v_add_f32_dpp v51, v51, v51 quad_perm:[2,3,0,1] row_mask:0xf bank_mask:0xf bound_ctrl:1
	v_pk_fma_f32 v[102:103], v[192:193], v[170:171], v[102:103] op_sel:[0,1,0] op_sel_hi:[1,1,1]
; #define LAS __attribute__((address_space(3)))
; __device__ __forceinline__ float red8(float x) { x += dpp_mov<0xB1>(x); x += dpp_mov<0x4E>(x); x += dpp_mov<0x141>(x); return x; }
; __device__ __forceinline__ void scan_phase(const KP& P, LAS unsigned char* lds, const int tid, const int bx, const int G) {
;     ...
;             for (int s = 0; s < 32; ++s) {
;                 const LAS float* p = cb + s * 384;
;                 const f32x4 w0 = *(const LAS f32x4*)(p), w1 = *(const LAS f32x4*)(p + 4);
;                 const f32x4 k0 = *(const LAS f32x4*)(p + 64), k1 = *(const LAS f32x4*)(p + 68);
;                 const f32x4 a0 = *(const LAS f32x4*)(p + 128), a1 = *(const LAS f32x4*)(p + 132);
;                 const f32x4 b0 = *(const LAS f32x4*)(p + 192), b1 = *(const LAS f32x4*)(p + 196);
;                 const f32x4 r0 = *(const LAS f32x4*)(p + 256), r1 = *(const LAS f32x4*)(p + 260);
;                 const float vv = buf[(c & 1) * 12288 + s * 384 + 320 + v];
;                 f32x2 sa2 = S[0] * (f32x2){a0.x, a0.y};
;                 sa2 += S[1] * (f32x2){a0.z, a0.w}; sa2 += S[2] * (f32x2){a1.x, a1.y}; sa2 += S[3] * (f32x2){a1.z, a1.w};
;                 const float sa = red8(sa2.x + sa2.y);
;                 const f32x2 sav = {sa, sa}, vv2 = {vv, vv};
;                 S[0] = S[0] * (f32x2){w0.x, w0.y} + sav * (f32x2){b0.x, b0.y} + vv2 * (f32x2){k0.x, k0.y};
;                 S[1] = S[1] * (f32x2){w0.z, w0.w} + sav * (f32x2){b0.z, b0.w} + vv2 * (f32x2){k0.z, k0.w};
;                 S[2] = S[2] * (f32x2){w1.x, w1.y} + sav * (f32x2){b1.x, b1.y} + vv2 * (f32x2){k1.x, k1.y};
;                 S[3] = S[3] * (f32x2){w1.z, w1.w} + sav * (f32x2){b1.z, b1.w} + vv2 * (f32x2){k1.z, k1.w};
;                 f32x2 y2 = S[0] * (f32x2){r0.x, r0.y};
;                 y2 += S[1] * (f32x2){r0.z, r0.w}; y2 += S[2] * (f32x2){r1.x, r1.y}; y2 += S[3] * (f32x2){r1.z, r1.w};
;                 const float y = red8(y2.x + y2.y);
;                 if (kc == 0) ybuf[s * 64 + v] = y;
;             }
	v_pk_fma_f32 v[104:105], v[192:193], v[172:173], v[104:105] op_sel:[0,0,0] op_sel_hi:[1,0,1]
	v_pk_fma_f32 v[106:107], v[192:193], v[172:173], v[106:107] op_sel:[0,1,0] op_sel_hi:[1,1,1]
	v_add_f32_dpp v50, v50, v50 row_half_mirror row_mask:0xf bank_mask:0xf bound_ctrl:1
	v_add_f32_dpp v51, v51, v51 row_half_mirror row_mask:0xf bank_mask:0xf bound_ctrl:1
	v_pk_fma_f32 v[108:109], v[192:193], v[174:175], v[108:109] op_sel:[0,0,0] op_sel_hi:[1,0,1]
	s_mov_b64 exec, s[86:87]
	ds_write_b64 v45, v[48:49] offset:512
	s_mov_b64 exec, s[0:1]
	v_pk_fma_f32 v[110:111], v[192:193], v[174:175], v[110:111] op_sel:[0,1,0] op_sel_hi:[1,1,1]
	v_pk_fma_f32 v[96:97], v[50:51], v[176:177], v[96:97] op_sel:[0,0,0] op_sel_hi:[1,0,1]
	v_pk_fma_f32 v[98:99], v[50:51], v[176:177], v[98:99] op_sel:[0,1,0] op_sel_hi:[1,1,1]
	v_pk_fma_f32 v[100:101], v[50:51], v[178:179], v[100:101] op_sel:[0,0,0] op_sel_hi:[1,0,1]
	v_pk_fma_f32 v[102:103], v[50:51], v[178:179], v[102:103] op_sel:[0,1,0] op_sel_hi:[1,1,1]
	v_pk_fma_f32 v[104:105], v[50:51], v[180:181], v[104:105] op_sel:[0,0,0] op_sel_hi:[1,0,1]
	v_pk_fma_f32 v[106:107], v[50:51], v[180:181], v[106:107] op_sel:[0,1,0] op_sel_hi:[1,1,1]
	v_pk_fma_f32 v[108:109], v[50:51], v[182:183], v[108:109] op_sel:[0,0,0] op_sel_hi:[1,0,1]
	v_pk_fma_f32 v[110:111], v[50:51], v[182:183], v[110:111] op_sel:[0,1,0] op_sel_hi:[1,1,1]
	v_pk_mul_f32 v[48:49], v[96:97], v[184:185] op_sel:[0,0] op_sel_hi:[1,0]
	v_pk_mul_f32 v[50:51], v[96:97], v[148:149] op_sel:[0,0] op_sel_hi:[1,0]
	v_pk_fma_f32 v[48:49], v[98:99], v[184:185], v[48:49] op_sel:[0,1,0] op_sel_hi:[1,1,1]
	v_pk_fma_f32 v[50:51], v[98:99], v[148:149], v[50:51] op_sel:[0,1,0] op_sel_hi:[1,1,1]
	v_pk_fma_f32 v[48:49], v[100:101], v[186:187], v[48:49] op_sel:[0,0,0] op_sel_hi:[1,0,1]
	v_pk_fma_f32 v[50:51], v[100:101], v[150:151], v[50:51] op_sel:[0,0,0] op_sel_hi:[1,0,1]
	v_pk_fma_f32 v[48:49], v[102:103], v[186:187], v[48:49] op_sel:[0,1,0] op_sel_hi:[1,1,1]
	v_pk_fma_f32 v[50:51], v[102:103], v[150:151], v[50:51] op_sel:[0,1,0] op_sel_hi:[1,1,1]
	v_pk_fma_f32 v[48:49], v[104:105], v[188:189], v[48:49] op_sel:[0,0,0] op_sel_hi:[1,0,1]
	v_pk_fma_f32 v[50:51], v[104:105], v[152:153], v[50:51] op_sel:[0,0,0] op_sel_hi:[1,0,1]
	v_pk_fma_f32 v[48:49], v[106:107], v[188:189], v[48:49] op_sel:[0,1,0] op_sel_hi:[1,1,1]
	v_pk_fma_f32 v[50:51], v[106:107], v[152:153], v[50:51] op_sel:[0,1,0] op_sel_hi:[1,1,1]
	v_pk_fma_f32 v[48:49], v[108:109], v[190:191], v[48:49] op_sel:[0,0,0] op_sel_hi:[1,0,1]
	v_pk_fma_f32 v[50:51], v[108:109], v[154:155], v[50:51] op_sel:[0,0,0] op_sel_hi:[1,0,1]
	v_pk_fma_f32 v[48:49], v[110:111], v[190:191], v[48:49] op_sel:[0,1,0] op_sel_hi:[1,1,1]
	v_pk_fma_f32 v[50:51], v[110:111], v[154:155], v[50:51] op_sel:[0,1,0] op_sel_hi:[1,1,1]
	s_waitcnt lgkmcnt(11)
	ds_read_b128 v[168:171], v44 offset:7936
	ds_read_b128 v[172:175], v44 offset:7952
	ds_read_b128 v[176:179], v44 offset:8448
	ds_read_b128 v[180:183], v44 offset:8464
	ds_read_b128 v[184:187], v44 offset:8704
	ds_read_b128 v[188:191], v44 offset:8720
	ds_read_b64 v[192:193], v46 offset:7680
	ds_read_b128 v[148:151], v44 offset:9728
	ds_read_b128 v[152:155], v44 offset:9744
	v_add_f32_dpp v48, v48, v48 quad_perm:[1,0,3,2] row_mask:0xf bank_mask:0xf bound_ctrl:1
	v_add_f32_dpp v49, v49, v49 quad_perm:[1,0,3,2] row_mask:0xf bank_mask:0xf bound_ctrl:1
	v_add_f32_dpp v50, v50, v50 quad_perm:[1,0,3,2] row_mask:0xf bank_mask:0xf bound_ctrl:1
	v_add_f32_dpp v51, v51, v51 quad_perm:[1,0,3,2] row_mask:0xf bank_mask:0xf bound_ctrl:1
	v_pk_fma_f32 v[96:97], v[144:145], v[120:121], v[96:97] op_sel:[0,0,0] op_sel_hi:[1,0,1]
	v_pk_fma_f32 v[98:99], v[144:145], v[120:121], v[98:99] op_sel:[0,1,0] op_sel_hi:[1,1,1]
	v_pk_fma_f32 v[100:101], v[144:145], v[122:123], v[100:101] op_sel:[0,0,0] op_sel_hi:[1,0,1]
	v_add_f32_dpp v48, v48, v48 quad_perm:[2,3,0,1] row_mask:0xf bank_mask:0xf bound_ctrl:1
	v_add_f32_dpp v49, v49, v49 quad_perm:[2,3,0,1] row_mask:0xf bank_mask:0xf bound_ctrl:1
	v_add_f32_dpp v50, v50, v50 quad_perm:[2,3,0,1] row_mask:0xf bank_mask:0xf bound_ctrl:1
	v_add_f32_dpp v51, v51, v51 quad_perm:[2,3,0,1] row_mask:0xf bank_mask:0xf bound_ctrl:1
	v_pk_fma_f32 v[102:103], v[144:145], v[122:123], v[102:103] op_sel:[0,1,0] op_sel_hi:[1,1,1]
	v_pk_fma_f32 v[104:105], v[144:145], v[124:125], v[104:105] op_sel:[0,0,0] op_sel_hi:[1,0,1]
	v_pk_fma_f32 v[106:107], v[144:145], v[124:125], v[106:107] op_sel:[0,1,0] op_sel_hi:[1,1,1]
	v_add_f32_dpp v50, v50, v50 row_half_mirror row_mask:0xf bank_mask:0xf bound_ctrl:1
	v_add_f32_dpp v51, v51, v51 row_half_mirror row_mask:0xf bank_mask:0xf bound_ctrl:1
	v_pk_fma_f32 v[108:109], v[144:145], v[126:127], v[108:109] op_sel:[0,0,0] op_sel_hi:[1,0,1]
	s_mov_b64 exec, s[86:87]
	ds_write_b64 v45, v[48:49] offset:1024
	s_mov_b64 exec, s[0:1]
	v_pk_fma_f32 v[110:111], v[144:145], v[126:127], v[110:111] op_sel:[0,1,0] op_sel_hi:[1,1,1]
	v_pk_fma_f32 v[96:97], v[50:51], v[128:129], v[96:97] op_sel:[0,0,0] op_sel_hi:[1,0,1]
	v_pk_fma_f32 v[98:99], v[50:51], v[128:129], v[98:99] op_sel:[0,1,0] op_sel_hi:[1,1,1]
	v_pk_fma_f32 v[100:101], v[50:51], v[130:131], v[100:101] op_sel:[0,0,0] op_sel_hi:[1,0,1]
	v_pk_fma_f32 v[102:103], v[50:51], v[130:131], v[102:103] op_sel:[0,1,0] op_sel_hi:[1,1,1]
	v_pk_fma_f32 v[104:105], v[50:51], v[132:133], v[104:105] op_sel:[0,0,0] op_sel_hi:[1,0,1]
	v_pk_fma_f32 v[106:107], v[50:51], v[132:133], v[106:107] op_sel:[0,1,0] op_sel_hi:[1,1,1]
	v_pk_fma_f32 v[108:109], v[50:51], v[134:135], v[108:109] op_sel:[0,0,0] op_sel_hi:[1,0,1]
	v_pk_fma_f32 v[110:111], v[50:51], v[134:135], v[110:111] op_sel:[0,1,0] op_sel_hi:[1,1,1]
	v_pk_mul_f32 v[48:49], v[96:97], v[136:137] op_sel:[0,0] op_sel_hi:[1,0]
	v_pk_mul_f32 v[50:51], v[96:97], v[156:157] op_sel:[0,0] op_sel_hi:[1,0]
	v_pk_fma_f32 v[48:49], v[98:99], v[136:137], v[48:49] op_sel:[0,1,0] op_sel_hi:[1,1,1]
	v_pk_fma_f32 v[50:51], v[98:99], v[156:157], v[50:51] op_sel:[0,1,0] op_sel_hi:[1,1,1]
	v_pk_fma_f32 v[48:49], v[100:101], v[138:139], v[48:49] op_sel:[0,0,0] op_sel_hi:[1,0,1]
	v_pk_fma_f32 v[50:51], v[100:101], v[158:159], v[50:51] op_sel:[0,0,0] op_sel_hi:[1,0,1]
	v_pk_fma_f32 v[48:49], v[102:103], v[138:139], v[48:49] op_sel:[0,1,0] op_sel_hi:[1,1,1]
	v_pk_fma_f32 v[50:51], v[102:103], v[158:159], v[50:51] op_sel:[0,1,0] op_sel_hi:[1,1,1]
	v_pk_fma_f32 v[48:49], v[104:105], v[140:141], v[48:49] op_sel:[0,0,0] op_sel_hi:[1,0,1]
	v_pk_fma_f32 v[50:51], v[104:105], v[160:161], v[50:51] op_sel:[0,0,0] op_sel_hi:[1,0,1]
	v_pk_fma_f32 v[48:49], v[106:107], v[140:141], v[48:49] op_sel:[0,1,0] op_sel_hi:[1,1,1]
	v_pk_fma_f32 v[50:51], v[106:107], v[160:161], v[50:51] op_sel:[0,1,0] op_sel_hi:[1,1,1]
	v_pk_fma_f32 v[48:49], v[108:109], v[142:143], v[48:49] op_sel:[0,0,0] op_sel_hi:[1,0,1]
	v_pk_fma_f32 v[50:51], v[108:109], v[162:163], v[50:51] op_sel:[0,0,0] op_sel_hi:[1,0,1]
	v_pk_fma_f32 v[48:49], v[110:111], v[142:143], v[48:49] op_sel:[0,1,0] op_sel_hi:[1,1,1]
	v_pk_fma_f32 v[50:51], v[110:111], v[162:163], v[50:51] op_sel:[0,1,0] op_sel_hi:[1,1,1]
	s_waitcnt lgkmcnt(11)
; #define LAS __attribute__((address_space(3)))
; __device__ __forceinline__ float red8(float x) { x += dpp_mov<0xB1>(x); x += dpp_mov<0x4E>(x); x += dpp_mov<0x141>(x); return x; }
; __device__ __forceinline__ void scan_phase(const KP& P, LAS unsigned char* lds, const int tid, const int bx, const int G) {
;     ...
;             for (int s = 0; s < 32; ++s) {
;                 const LAS float* p = cb + s * 384;
;                 const f32x4 w0 = *(const LAS f32x4*)(p), w1 = *(const LAS f32x4*)(p + 4);
;                 const f32x4 k0 = *(const LAS f32x4*)(p + 64), k1 = *(const LAS f32x4*)(p + 68);
;                 const f32x4 a0 = *(const LAS f32x4*)(p + 128), a1 = *(const LAS f32x4*)(p + 132);
;                 const f32x4 b0 = *(const LAS f32x4*)(p + 192), b1 = *(const LAS f32x4*)(p + 196);
;                 const f32x4 r0 = *(const LAS f32x4*)(p + 256), r1 = *(const LAS f32x4*)(p + 260);
;                 const float vv = buf[(c & 1) * 12288 + s * 384 + 320 + v];
;                 f32x2 sa2 = S[0] * (f32x2){a0.x, a0.y};
;                 sa2 += S[1] * (f32x2){a0.z, a0.w}; sa2 += S[2] * (f32x2){a1.x, a1.y}; sa2 += S[3] * (f32x2){a1.z, a1.w};
;                 const float sa = red8(sa2.x + sa2.y);
;                 const f32x2 sav = {sa, sa}, vv2 = {vv, vv};
;                 S[0] = S[0] * (f32x2){w0.x, w0.y} + sav * (f32x2){b0.x, b0.y} + vv2 * (f32x2){k0.x, k0.y};
;                 S[1] = S[1] * (f32x2){w0.z, w0.w} + sav * (f32x2){b0.z, b0.w} + vv2 * (f32x2){k0.z, k0.w};
;                 S[2] = S[2] * (f32x2){w1.x, w1.y} + sav * (f32x2){b1.x, b1.y} + vv2 * (f32x2){k1.x, k1.y};
;                 S[3] = S[3] * (f32x2){w1.z, w1.w} + sav * (f32x2){b1.z, b1.w} + vv2 * (f32x2){k1.z, k1.w};
;                 f32x2 y2 = S[0] * (f32x2){r0.x, r0.y};
;                 y2 += S[1] * (f32x2){r0.z, r0.w}; y2 += S[2] * (f32x2){r1.x, r1.y}; y2 += S[3] * (f32x2){r1.z, r1.w};
;                 const float y = red8(y2.x + y2.y);
;                 if (kc == 0) ybuf[s * 64 + v] = y;
;             }
	ds_read_b128 v[120:123], v44 offset:9472
	ds_read_b128 v[124:127], v44 offset:9488
	ds_read_b128 v[128:131], v44 offset:9984
	ds_read_b128 v[132:135], v44 offset:10000
	ds_read_b128 v[136:139], v44 offset:10240
	ds_read_b128 v[140:143], v44 offset:10256
	ds_read_b64 v[144:145], v46 offset:9216
	ds_read_b128 v[156:159], v44 offset:11264
	ds_read_b128 v[160:163], v44 offset:11280
	v_add_f32_dpp v48, v48, v48 quad_perm:[1,0,3,2] row_mask:0xf bank_mask:0xf bound_ctrl:1
	v_add_f32_dpp v49, v49, v49 quad_perm:[1,0,3,2] row_mask:0xf bank_mask:0xf bound_ctrl:1
	v_add_f32_dpp v50, v50, v50 quad_perm:[1,0,3,2] row_mask:0xf bank_mask:0xf bound_ctrl:1
	v_add_f32_dpp v51, v51, v51 quad_perm:[1,0,3,2] row_mask:0xf bank_mask:0xf bound_ctrl:1
	v_pk_fma_f32 v[96:97], v[146:147], v[70:71], v[96:97] op_sel:[0,0,0] op_sel_hi:[1,0,1]
	v_pk_fma_f32 v[98:99], v[146:147], v[70:71], v[98:99] op_sel:[0,1,0] op_sel_hi:[1,1,1]
	v_pk_fma_f32 v[100:101], v[146:147], v[72:73], v[100:101] op_sel:[0,0,0] op_sel_hi:[1,0,1]
	v_add_f32_dpp v48, v48, v48 quad_perm:[2,3,0,1] row_mask:0xf bank_mask:0xf bound_ctrl:1
	v_add_f32_dpp v49, v49, v49 quad_perm:[2,3,0,1] row_mask:0xf bank_mask:0xf bound_ctrl:1
	v_add_f32_dpp v50, v50, v50 quad_perm:[2,3,0,1] row_mask:0xf bank_mask:0xf bound_ctrl:1
	v_add_f32_dpp v51, v51, v51 quad_perm:[2,3,0,1] row_mask:0xf bank_mask:0xf bound_ctrl:1
	v_pk_fma_f32 v[102:103], v[146:147], v[72:73], v[102:103] op_sel:[0,1,0] op_sel_hi:[1,1,1]
	v_pk_fma_f32 v[104:105], v[146:147], v[74:75], v[104:105] op_sel:[0,0,0] op_sel_hi:[1,0,1]
	v_pk_fma_f32 v[106:107], v[146:147], v[74:75], v[106:107] op_sel:[0,1,0] op_sel_hi:[1,1,1]
	v_add_f32_dpp v50, v50, v50 row_half_mirror row_mask:0xf bank_mask:0xf bound_ctrl:1
	v_add_f32_dpp v51, v51, v51 row_half_mirror row_mask:0xf bank_mask:0xf bound_ctrl:1
	v_pk_fma_f32 v[108:109], v[146:147], v[76:77], v[108:109] op_sel:[0,0,0] op_sel_hi:[1,0,1]
	s_mov_b64 exec, s[86:87]
	ds_write_b64 v45, v[48:49] offset:1536
	s_mov_b64 exec, s[0:1]
	v_pk_fma_f32 v[110:111], v[146:147], v[76:77], v[110:111] op_sel:[0,1,0] op_sel_hi:[1,1,1]
	v_pk_fma_f32 v[96:97], v[50:51], v[78:79], v[96:97] op_sel:[0,0,0] op_sel_hi:[1,0,1]
	v_pk_fma_f32 v[98:99], v[50:51], v[78:79], v[98:99] op_sel:[0,1,0] op_sel_hi:[1,1,1]
	v_pk_fma_f32 v[100:101], v[50:51], v[80:81], v[100:101] op_sel:[0,0,0] op_sel_hi:[1,0,1]
	v_pk_fma_f32 v[102:103], v[50:51], v[80:81], v[102:103] op_sel:[0,1,0] op_sel_hi:[1,1,1]
	v_pk_fma_f32 v[104:105], v[50:51], v[82:83], v[104:105] op_sel:[0,0,0] op_sel_hi:[1,0,1]
	v_pk_fma_f32 v[106:107], v[50:51], v[82:83], v[106:107] op_sel:[0,1,0] op_sel_hi:[1,1,1]
	v_pk_fma_f32 v[108:109], v[50:51], v[84:85], v[108:109] op_sel:[0,0,0] op_sel_hi:[1,0,1]
	v_pk_fma_f32 v[110:111], v[50:51], v[84:85], v[110:111] op_sel:[0,1,0] op_sel_hi:[1,1,1]
	v_pk_mul_f32 v[48:49], v[96:97], v[86:87] op_sel:[0,0] op_sel_hi:[1,0]
	v_pk_mul_f32 v[50:51], v[96:97], v[62:63] op_sel:[0,0] op_sel_hi:[1,0]
	v_pk_fma_f32 v[48:49], v[98:99], v[86:87], v[48:49] op_sel:[0,1,0] op_sel_hi:[1,1,1]
	v_pk_fma_f32 v[50:51], v[98:99], v[62:63], v[50:51] op_sel:[0,1,0] op_sel_hi:[1,1,1]
	v_pk_fma_f32 v[48:49], v[100:101], v[88:89], v[48:49] op_sel:[0,0,0] op_sel_hi:[1,0,1]
	v_pk_fma_f32 v[50:51], v[100:101], v[64:65], v[50:51] op_sel:[0,0,0] op_sel_hi:[1,0,1]
	v_pk_fma_f32 v[48:49], v[102:103], v[88:89], v[48:49] op_sel:[0,1,0] op_sel_hi:[1,1,1]
	v_pk_fma_f32 v[50:51], v[102:103], v[64:65], v[50:51] op_sel:[0,1,0] op_sel_hi:[1,1,1]
	v_pk_fma_f32 v[48:49], v[104:105], v[90:91], v[48:49] op_sel:[0,0,0] op_sel_hi:[1,0,1]
	v_pk_fma_f32 v[50:51], v[104:105], v[66:67], v[50:51] op_sel:[0,0,0] op_sel_hi:[1,0,1]
	v_pk_fma_f32 v[48:49], v[106:107], v[90:91], v[48:49] op_sel:[0,1,0] op_sel_hi:[1,1,1]
	v_pk_fma_f32 v[50:51], v[106:107], v[66:67], v[50:51] op_sel:[0,1,0] op_sel_hi:[1,1,1]
	v_pk_fma_f32 v[48:49], v[108:109], v[92:93], v[48:49] op_sel:[0,0,0] op_sel_hi:[1,0,1]
	v_pk_fma_f32 v[50:51], v[108:109], v[68:69], v[50:51] op_sel:[0,0,0] op_sel_hi:[1,0,1]
	v_pk_fma_f32 v[48:49], v[110:111], v[92:93], v[48:49] op_sel:[0,1,0] op_sel_hi:[1,1,1]
	v_pk_fma_f32 v[50:51], v[110:111], v[68:69], v[50:51] op_sel:[0,1,0] op_sel_hi:[1,1,1]
	s_waitcnt lgkmcnt(11)
	ds_read_b128 v[70:73], v44 offset:11008
	ds_read_b128 v[74:77], v44 offset:11024
	ds_read_b128 v[78:81], v44 offset:11520
	ds_read_b128 v[82:85], v44 offset:11536
	ds_read_b128 v[86:89], v44 offset:11776
	ds_read_b128 v[90:93], v44 offset:11792
	ds_read_b64 v[146:147], v46 offset:10752
	ds_read_b128 v[62:65], v44 offset:12800
	ds_read_b128 v[66:69], v44 offset:12816
	v_add_f32_dpp v48, v48, v48 quad_perm:[1,0,3,2] row_mask:0xf bank_mask:0xf bound_ctrl:1
	v_add_f32_dpp v49, v49, v49 quad_perm:[1,0,3,2] row_mask:0xf bank_mask:0xf bound_ctrl:1
	v_add_f32_dpp v50, v50, v50 quad_perm:[1,0,3,2] row_mask:0xf bank_mask:0xf bound_ctrl:1
	v_add_f32_dpp v51, v51, v51 quad_perm:[1,0,3,2] row_mask:0xf bank_mask:0xf bound_ctrl:1
	v_pk_fma_f32 v[96:97], v[192:193], v[168:169], v[96:97] op_sel:[0,0,0] op_sel_hi:[1,0,1]
	v_pk_fma_f32 v[98:99], v[192:193], v[168:169], v[98:99] op_sel:[0,1,0] op_sel_hi:[1,1,1]
	v_pk_fma_f32 v[100:101], v[192:193], v[170:171], v[100:101] op_sel:[0,0,0] op_sel_hi:[1,0,1]
	v_add_f32_dpp v48, v48, v48 quad_perm:[2,3,0,1] row_mask:0xf bank_mask:0xf bound_ctrl:1
	v_add_f32_dpp v49, v49, v49 quad_perm:[2,3,0,1] row_mask:0xf bank_mask:0xf bound_ctrl:1
	v_add_f32_dpp v50, v50, v50 quad_perm:[2,3,0,1] row_mask:0xf bank_mask:0xf bound_ctrl:1
	v_add_f32_dpp v51, v51, v51 quad_perm:[2,3,0,1] row_mask:0xf bank_mask:0xf bound_ctrl:1
	v_pk_fma_f32 v[102:103], v[192:193], v[170:171], v[102:103] op_sel:[0,1,0] op_sel_hi:[1,1,1]
; #define LAS __attribute__((address_space(3)))
; __device__ __forceinline__ float red8(float x) { x += dpp_mov<0xB1>(x); x += dpp_mov<0x4E>(x); x += dpp_mov<0x141>(x); return x; }
; __device__ __forceinline__ void scan_phase(const KP& P, LAS unsigned char* lds, const int tid, const int bx, const int G) {
;     ...
;             for (int s = 0; s < 32; ++s) {
;                 const LAS float* p = cb + s * 384;
;                 const f32x4 w0 = *(const LAS f32x4*)(p), w1 = *(const LAS f32x4*)(p + 4);
;                 const f32x4 k0 = *(const LAS f32x4*)(p + 64), k1 = *(const LAS f32x4*)(p + 68);
;                 const f32x4 a0 = *(const LAS f32x4*)(p + 128), a1 = *(const LAS f32x4*)(p + 132);
;                 const f32x4 b0 = *(const LAS f32x4*)(p + 192), b1 = *(const LAS f32x4*)(p + 196);
;                 const f32x4 r0 = *(const LAS f32x4*)(p + 256), r1 = *(const LAS f32x4*)(p + 260);
;                 const float vv = buf[(c & 1) * 12288 + s * 384 + 320 + v];
;                 f32x2 sa2 = S[0] * (f32x2){a0.x, a0.y};
;                 sa2 += S[1] * (f32x2){a0.z, a0.w}; sa2 += S[2] * (f32x2){a1.x, a1.y}; sa2 += S[3] * (f32x2){a1.z, a1.w};
;                 const float sa = red8(sa2.x + sa2.y);
;                 const f32x2 sav = {sa, sa}, vv2 = {vv, vv};
;                 S[0] = S[0] * (f32x2){w0.x, w0.y} + sav * (f32x2){b0.x, b0.y} + vv2 * (f32x2){k0.x, k0.y};
;                 S[1] = S[1] * (f32x2){w0.z, w0.w} + sav * (f32x2){b0.z, b0.w} + vv2 * (f32x2){k0.z, k0.w};
;                 S[2] = S[2] * (f32x2){w1.x, w1.y} + sav * (f32x2){b1.x, b1.y} + vv2 * (f32x2){k1.x, k1.y};
;                 S[3] = S[3] * (f32x2){w1.z, w1.w} + sav * (f32x2){b1.z, b1.w} + vv2 * (f32x2){k1.z, k1.w};
;                 f32x2 y2 = S[0] * (f32x2){r0.x, r0.y};
;                 y2 += S[1] * (f32x2){r0.z, r0.w}; y2 += S[2] * (f32x2){r1.x, r1.y}; y2 += S[3] * (f32x2){r1.z, r1.w};
;                 const float y = red8(y2.x + y2.y);
;                 if (kc == 0) ybuf[s * 64 + v] = y;
;             }
	v_pk_fma_f32 v[104:105], v[192:193], v[172:173], v[104:105] op_sel:[0,0,0] op_sel_hi:[1,0,1]
	v_pk_fma_f32 v[106:107], v[192:193], v[172:173], v[106:107] op_sel:[0,1,0] op_sel_hi:[1,1,1]
	v_add_f32_dpp v50, v50, v50 row_half_mirror row_mask:0xf bank_mask:0xf bound_ctrl:1
	v_add_f32_dpp v51, v51, v51 row_half_mirror row_mask:0xf bank_mask:0xf bound_ctrl:1
	v_pk_fma_f32 v[108:109], v[192:193], v[174:175], v[108:109] op_sel:[0,0,0] op_sel_hi:[1,0,1]
	s_mov_b64 exec, s[86:87]
	ds_write_b64 v45, v[48:49] offset:2048
	s_mov_b64 exec, s[0:1]
	v_pk_fma_f32 v[110:111], v[192:193], v[174:175], v[110:111] op_sel:[0,1,0] op_sel_hi:[1,1,1]
	v_pk_fma_f32 v[96:97], v[50:51], v[176:177], v[96:97] op_sel:[0,0,0] op_sel_hi:[1,0,1]
	v_pk_fma_f32 v[98:99], v[50:51], v[176:177], v[98:99] op_sel:[0,1,0] op_sel_hi:[1,1,1]
	v_pk_fma_f32 v[100:101], v[50:51], v[178:179], v[100:101] op_sel:[0,0,0] op_sel_hi:[1,0,1]
	v_pk_fma_f32 v[102:103], v[50:51], v[178:179], v[102:103] op_sel:[0,1,0] op_sel_hi:[1,1,1]
	v_pk_fma_f32 v[104:105], v[50:51], v[180:181], v[104:105] op_sel:[0,0,0] op_sel_hi:[1,0,1]
	v_pk_fma_f32 v[106:107], v[50:51], v[180:181], v[106:107] op_sel:[0,1,0] op_sel_hi:[1,1,1]
	v_pk_fma_f32 v[108:109], v[50:51], v[182:183], v[108:109] op_sel:[0,0,0] op_sel_hi:[1,0,1]
	v_pk_fma_f32 v[110:111], v[50:51], v[182:183], v[110:111] op_sel:[0,1,0] op_sel_hi:[1,1,1]
	v_pk_mul_f32 v[48:49], v[96:97], v[184:185] op_sel:[0,0] op_sel_hi:[1,0]
	v_pk_mul_f32 v[50:51], v[96:97], v[148:149] op_sel:[0,0] op_sel_hi:[1,0]
	v_pk_fma_f32 v[48:49], v[98:99], v[184:185], v[48:49] op_sel:[0,1,0] op_sel_hi:[1,1,1]
	v_pk_fma_f32 v[50:51], v[98:99], v[148:149], v[50:51] op_sel:[0,1,0] op_sel_hi:[1,1,1]
	v_pk_fma_f32 v[48:49], v[100:101], v[186:187], v[48:49] op_sel:[0,0,0] op_sel_hi:[1,0,1]
	v_pk_fma_f32 v[50:51], v[100:101], v[150:151], v[50:51] op_sel:[0,0,0] op_sel_hi:[1,0,1]
	v_pk_fma_f32 v[48:49], v[102:103], v[186:187], v[48:49] op_sel:[0,1,0] op_sel_hi:[1,1,1]
	v_pk_fma_f32 v[50:51], v[102:103], v[150:151], v[50:51] op_sel:[0,1,0] op_sel_hi:[1,1,1]
	v_pk_fma_f32 v[48:49], v[104:105], v[188:189], v[48:49] op_sel:[0,0,0] op_sel_hi:[1,0,1]
	v_pk_fma_f32 v[50:51], v[104:105], v[152:153], v[50:51] op_sel:[0,0,0] op_sel_hi:[1,0,1]
	v_pk_fma_f32 v[48:49], v[106:107], v[188:189], v[48:49] op_sel:[0,1,0] op_sel_hi:[1,1,1]
	v_pk_fma_f32 v[50:51], v[106:107], v[152:153], v[50:51] op_sel:[0,1,0] op_sel_hi:[1,1,1]
	v_pk_fma_f32 v[48:49], v[108:109], v[190:191], v[48:49] op_sel:[0,0,0] op_sel_hi:[1,0,1]
	v_pk_fma_f32 v[50:51], v[108:109], v[154:155], v[50:51] op_sel:[0,0,0] op_sel_hi:[1,0,1]
	v_pk_fma_f32 v[48:49], v[110:111], v[190:191], v[48:49] op_sel:[0,1,0] op_sel_hi:[1,1,1]
	v_pk_fma_f32 v[50:51], v[110:111], v[154:155], v[50:51] op_sel:[0,1,0] op_sel_hi:[1,1,1]
	s_waitcnt lgkmcnt(11)
	ds_read_b128 v[168:171], v44 offset:12544
	ds_read_b128 v[172:175], v44 offset:12560
	ds_read_b128 v[176:179], v44 offset:13056
	ds_read_b128 v[180:183], v44 offset:13072
	ds_read_b128 v[184:187], v44 offset:13312
	ds_read_b128 v[188:191], v44 offset:13328
	ds_read_b64 v[192:193], v46 offset:12288
	ds_read_b128 v[148:151], v44 offset:14336
	ds_read_b128 v[152:155], v44 offset:14352
	v_add_f32_dpp v48, v48, v48 quad_perm:[1,0,3,2] row_mask:0xf bank_mask:0xf bound_ctrl:1
	v_add_f32_dpp v49, v49, v49 quad_perm:[1,0,3,2] row_mask:0xf bank_mask:0xf bound_ctrl:1
	v_add_f32_dpp v50, v50, v50 quad_perm:[1,0,3,2] row_mask:0xf bank_mask:0xf bound_ctrl:1
	v_add_f32_dpp v51, v51, v51 quad_perm:[1,0,3,2] row_mask:0xf bank_mask:0xf bound_ctrl:1
	v_pk_fma_f32 v[96:97], v[144:145], v[120:121], v[96:97] op_sel:[0,0,0] op_sel_hi:[1,0,1]
	v_pk_fma_f32 v[98:99], v[144:145], v[120:121], v[98:99] op_sel:[0,1,0] op_sel_hi:[1,1,1]
	v_pk_fma_f32 v[100:101], v[144:145], v[122:123], v[100:101] op_sel:[0,0,0] op_sel_hi:[1,0,1]
	v_add_f32_dpp v48, v48, v48 quad_perm:[2,3,0,1] row_mask:0xf bank_mask:0xf bound_ctrl:1
	v_add_f32_dpp v49, v49, v49 quad_perm:[2,3,0,1] row_mask:0xf bank_mask:0xf bound_ctrl:1
	v_add_f32_dpp v50, v50, v50 quad_perm:[2,3,0,1] row_mask:0xf bank_mask:0xf bound_ctrl:1
	v_add_f32_dpp v51, v51, v51 quad_perm:[2,3,0,1] row_mask:0xf bank_mask:0xf bound_ctrl:1
	v_pk_fma_f32 v[102:103], v[144:145], v[122:123], v[102:103] op_sel:[0,1,0] op_sel_hi:[1,1,1]
	v_pk_fma_f32 v[104:105], v[144:145], v[124:125], v[104:105] op_sel:[0,0,0] op_sel_hi:[1,0,1]
	v_pk_fma_f32 v[106:107], v[144:145], v[124:125], v[106:107] op_sel:[0,1,0] op_sel_hi:[1,1,1]
	v_add_f32_dpp v50, v50, v50 row_half_mirror row_mask:0xf bank_mask:0xf bound_ctrl:1
	v_add_f32_dpp v51, v51, v51 row_half_mirror row_mask:0xf bank_mask:0xf bound_ctrl:1
	v_pk_fma_f32 v[108:109], v[144:145], v[126:127], v[108:109] op_sel:[0,0,0] op_sel_hi:[1,0,1]
	s_mov_b64 exec, s[86:87]
	ds_write_b64 v45, v[48:49] offset:2560
	s_mov_b64 exec, s[0:1]
	v_pk_fma_f32 v[110:111], v[144:145], v[126:127], v[110:111] op_sel:[0,1,0] op_sel_hi:[1,1,1]
	v_pk_fma_f32 v[96:97], v[50:51], v[128:129], v[96:97] op_sel:[0,0,0] op_sel_hi:[1,0,1]
	v_pk_fma_f32 v[98:99], v[50:51], v[128:129], v[98:99] op_sel:[0,1,0] op_sel_hi:[1,1,1]
	v_pk_fma_f32 v[100:101], v[50:51], v[130:131], v[100:101] op_sel:[0,0,0] op_sel_hi:[1,0,1]
	v_pk_fma_f32 v[102:103], v[50:51], v[130:131], v[102:103] op_sel:[0,1,0] op_sel_hi:[1,1,1]
	v_pk_fma_f32 v[104:105], v[50:51], v[132:133], v[104:105] op_sel:[0,0,0] op_sel_hi:[1,0,1]
	v_pk_fma_f32 v[106:107], v[50:51], v[132:133], v[106:107] op_sel:[0,1,0] op_sel_hi:[1,1,1]
	v_pk_fma_f32 v[108:109], v[50:51], v[134:135], v[108:109] op_sel:[0,0,0] op_sel_hi:[1,0,1]
	v_pk_fma_f32 v[110:111], v[50:51], v[134:135], v[110:111] op_sel:[0,1,0] op_sel_hi:[1,1,1]
	v_pk_mul_f32 v[48:49], v[96:97], v[136:137] op_sel:[0,0] op_sel_hi:[1,0]
	v_pk_mul_f32 v[50:51], v[96:97], v[156:157] op_sel:[0,0] op_sel_hi:[1,0]
	v_pk_fma_f32 v[48:49], v[98:99], v[136:137], v[48:49] op_sel:[0,1,0] op_sel_hi:[1,1,1]
	v_pk_fma_f32 v[50:51], v[98:99], v[156:157], v[50:51] op_sel:[0,1,0] op_sel_hi:[1,1,1]
	v_pk_fma_f32 v[48:49], v[100:101], v[138:139], v[48:49] op_sel:[0,0,0] op_sel_hi:[1,0,1]
	v_pk_fma_f32 v[50:51], v[100:101], v[158:159], v[50:51] op_sel:[0,0,0] op_sel_hi:[1,0,1]
	v_pk_fma_f32 v[48:49], v[102:103], v[138:139], v[48:49] op_sel:[0,1,0] op_sel_hi:[1,1,1]
	v_pk_fma_f32 v[50:51], v[102:103], v[158:159], v[50:51] op_sel:[0,1,0] op_sel_hi:[1,1,1]
	v_pk_fma_f32 v[48:49], v[104:105], v[140:141], v[48:49] op_sel:[0,0,0] op_sel_hi:[1,0,1]
	v_pk_fma_f32 v[50:51], v[104:105], v[160:161], v[50:51] op_sel:[0,0,0] op_sel_hi:[1,0,1]
	v_pk_fma_f32 v[48:49], v[106:107], v[140:141], v[48:49] op_sel:[0,1,0] op_sel_hi:[1,1,1]
	v_pk_fma_f32 v[50:51], v[106:107], v[160:161], v[50:51] op_sel:[0,1,0] op_sel_hi:[1,1,1]
	v_pk_fma_f32 v[48:49], v[108:109], v[142:143], v[48:49] op_sel:[0,0,0] op_sel_hi:[1,0,1]
	v_pk_fma_f32 v[50:51], v[108:109], v[162:163], v[50:51] op_sel:[0,0,0] op_sel_hi:[1,0,1]
	v_pk_fma_f32 v[48:49], v[110:111], v[142:143], v[48:49] op_sel:[0,1,0] op_sel_hi:[1,1,1]
	v_pk_fma_f32 v[50:51], v[110:111], v[162:163], v[50:51] op_sel:[0,1,0] op_sel_hi:[1,1,1]
	s_waitcnt lgkmcnt(11)
; #define LAS __attribute__((address_space(3)))
; __device__ __forceinline__ float red8(float x) { x += dpp_mov<0xB1>(x); x += dpp_mov<0x4E>(x); x += dpp_mov<0x141>(x); return x; }
; __device__ __forceinline__ void scan_phase(const KP& P, LAS unsigned char* lds, const int tid, const int bx, const int G) {
;     ...
;             for (int s = 0; s < 32; ++s) {
;                 const LAS float* p = cb + s * 384;
;                 const f32x4 w0 = *(const LAS f32x4*)(p), w1 = *(const LAS f32x4*)(p + 4);
;                 const f32x4 k0 = *(const LAS f32x4*)(p + 64), k1 = *(const LAS f32x4*)(p + 68);
;                 const f32x4 a0 = *(const LAS f32x4*)(p + 128), a1 = *(const LAS f32x4*)(p + 132);
;                 const f32x4 b0 = *(const LAS f32x4*)(p + 192), b1 = *(const LAS f32x4*)(p + 196);
;                 const f32x4 r0 = *(const LAS f32x4*)(p + 256), r1 = *(const LAS f32x4*)(p + 260);
;                 const float vv = buf[(c & 1) * 12288 + s * 384 + 320 + v];
;                 f32x2 sa2 = S[0] * (f32x2){a0.x, a0.y};
;                 sa2 += S[1] * (f32x2){a0.z, a0.w}; sa2 += S[2] * (f32x2){a1.x, a1.y}; sa2 += S[3] * (f32x2){a1.z, a1.w};
;                 const float sa = red8(sa2.x + sa2.y);
;                 const f32x2 sav = {sa, sa}, vv2 = {vv, vv};
;                 S[0] = S[0] * (f32x2){w0.x, w0.y} + sav * (f32x2){b0.x, b0.y} + vv2 * (f32x2){k0.x, k0.y};
;                 S[1] = S[1] * (f32x2){w0.z, w0.w} + sav * (f32x2){b0.z, b0.w} + vv2 * (f32x2){k0.z, k0.w};
;                 S[2] = S[2] * (f32x2){w1.x, w1.y} + sav * (f32x2){b1.x, b1.y} + vv2 * (f32x2){k1.x, k1.y};
;                 S[3] = S[3] * (f32x2){w1.z, w1.w} + sav * (f32x2){b1.z, b1.w} + vv2 * (f32x2){k1.z, k1.w};
;                 f32x2 y2 = S[0] * (f32x2){r0.x, r0.y};
;                 y2 += S[1] * (f32x2){r0.z, r0.w}; y2 += S[2] * (f32x2){r1.x, r1.y}; y2 += S[3] * (f32x2){r1.z, r1.w};
;                 const float y = red8(y2.x + y2.y);
;                 if (kc == 0) ybuf[s * 64 + v] = y;
;             }
	ds_read_b128 v[120:123], v44 offset:14080
	ds_read_b128 v[124:127], v44 offset:14096
	ds_read_b128 v[128:131], v44 offset:14592
	ds_read_b128 v[132:135], v44 offset:14608
	ds_read_b128 v[136:139], v44 offset:14848
	ds_read_b128 v[140:143], v44 offset:14864
	ds_read_b64 v[144:145], v46 offset:13824
	ds_read_b128 v[156:159], v44 offset:15872
	ds_read_b128 v[160:163], v44 offset:15888
	v_add_f32_dpp v48, v48, v48 quad_perm:[1,0,3,2] row_mask:0xf bank_mask:0xf bound_ctrl:1
	v_add_f32_dpp v49, v49, v49 quad_perm:[1,0,3,2] row_mask:0xf bank_mask:0xf bound_ctrl:1
	v_add_f32_dpp v50, v50, v50 quad_perm:[1,0,3,2] row_mask:0xf bank_mask:0xf bound_ctrl:1
	v_add_f32_dpp v51, v51, v51 quad_perm:[1,0,3,2] row_mask:0xf bank_mask:0xf bound_ctrl:1
	v_pk_fma_f32 v[96:97], v[146:147], v[70:71], v[96:97] op_sel:[0,0,0] op_sel_hi:[1,0,1]
	v_pk_fma_f32 v[98:99], v[146:147], v[70:71], v[98:99] op_sel:[0,1,0] op_sel_hi:[1,1,1]
	v_pk_fma_f32 v[100:101], v[146:147], v[72:73], v[100:101] op_sel:[0,0,0] op_sel_hi:[1,0,1]
	v_add_f32_dpp v48, v48, v48 quad_perm:[2,3,0,1] row_mask:0xf bank_mask:0xf bound_ctrl:1
	v_add_f32_dpp v49, v49, v49 quad_perm:[2,3,0,1] row_mask:0xf bank_mask:0xf bound_ctrl:1
	v_add_f32_dpp v50, v50, v50 quad_perm:[2,3,0,1] row_mask:0xf bank_mask:0xf bound_ctrl:1
	v_add_f32_dpp v51, v51, v51 quad_perm:[2,3,0,1] row_mask:0xf bank_mask:0xf bound_ctrl:1
	v_pk_fma_f32 v[102:103], v[146:147], v[72:73], v[102:103] op_sel:[0,1,0] op_sel_hi:[1,1,1]
	v_pk_fma_f32 v[104:105], v[146:147], v[74:75], v[104:105] op_sel:[0,0,0] op_sel_hi:[1,0,1]
	v_pk_fma_f32 v[106:107], v[146:147], v[74:75], v[106:107] op_sel:[0,1,0] op_sel_hi:[1,1,1]
	v_add_f32_dpp v50, v50, v50 row_half_mirror row_mask:0xf bank_mask:0xf bound_ctrl:1
	v_add_f32_dpp v51, v51, v51 row_half_mirror row_mask:0xf bank_mask:0xf bound_ctrl:1
	v_pk_fma_f32 v[108:109], v[146:147], v[76:77], v[108:109] op_sel:[0,0,0] op_sel_hi:[1,0,1]
	s_mov_b64 exec, s[86:87]
	ds_write_b64 v45, v[48:49] offset:3072
	s_mov_b64 exec, s[0:1]
	v_pk_fma_f32 v[110:111], v[146:147], v[76:77], v[110:111] op_sel:[0,1,0] op_sel_hi:[1,1,1]
	v_pk_fma_f32 v[96:97], v[50:51], v[78:79], v[96:97] op_sel:[0,0,0] op_sel_hi:[1,0,1]
	v_pk_fma_f32 v[98:99], v[50:51], v[78:79], v[98:99] op_sel:[0,1,0] op_sel_hi:[1,1,1]
	v_pk_fma_f32 v[100:101], v[50:51], v[80:81], v[100:101] op_sel:[0,0,0] op_sel_hi:[1,0,1]
	v_pk_fma_f32 v[102:103], v[50:51], v[80:81], v[102:103] op_sel:[0,1,0] op_sel_hi:[1,1,1]
	v_pk_fma_f32 v[104:105], v[50:51], v[82:83], v[104:105] op_sel:[0,0,0] op_sel_hi:[1,0,1]
	v_pk_fma_f32 v[106:107], v[50:51], v[82:83], v[106:107] op_sel:[0,1,0] op_sel_hi:[1,1,1]
	v_pk_fma_f32 v[108:109], v[50:51], v[84:85], v[108:109] op_sel:[0,0,0] op_sel_hi:[1,0,1]
	v_pk_fma_f32 v[110:111], v[50:51], v[84:85], v[110:111] op_sel:[0,1,0] op_sel_hi:[1,1,1]
	v_pk_mul_f32 v[48:49], v[96:97], v[86:87] op_sel:[0,0] op_sel_hi:[1,0]
	v_pk_mul_f32 v[50:51], v[96:97], v[62:63] op_sel:[0,0] op_sel_hi:[1,0]
	v_pk_fma_f32 v[48:49], v[98:99], v[86:87], v[48:49] op_sel:[0,1,0] op_sel_hi:[1,1,1]
	v_pk_fma_f32 v[50:51], v[98:99], v[62:63], v[50:51] op_sel:[0,1,0] op_sel_hi:[1,1,1]
	v_pk_fma_f32 v[48:49], v[100:101], v[88:89], v[48:49] op_sel:[0,0,0] op_sel_hi:[1,0,1]
	v_pk_fma_f32 v[50:51], v[100:101], v[64:65], v[50:51] op_sel:[0,0,0] op_sel_hi:[1,0,1]
	v_pk_fma_f32 v[48:49], v[102:103], v[88:89], v[48:49] op_sel:[0,1,0] op_sel_hi:[1,1,1]
	v_pk_fma_f32 v[50:51], v[102:103], v[64:65], v[50:51] op_sel:[0,1,0] op_sel_hi:[1,1,1]
	v_pk_fma_f32 v[48:49], v[104:105], v[90:91], v[48:49] op_sel:[0,0,0] op_sel_hi:[1,0,1]
	v_pk_fma_f32 v[50:51], v[104:105], v[66:67], v[50:51] op_sel:[0,0,0] op_sel_hi:[1,0,1]
	v_pk_fma_f32 v[48:49], v[106:107], v[90:91], v[48:49] op_sel:[0,1,0] op_sel_hi:[1,1,1]
	v_pk_fma_f32 v[50:51], v[106:107], v[66:67], v[50:51] op_sel:[0,1,0] op_sel_hi:[1,1,1]
	v_pk_fma_f32 v[48:49], v[108:109], v[92:93], v[48:49] op_sel:[0,0,0] op_sel_hi:[1,0,1]
	v_pk_fma_f32 v[50:51], v[108:109], v[68:69], v[50:51] op_sel:[0,0,0] op_sel_hi:[1,0,1]
	v_pk_fma_f32 v[48:49], v[110:111], v[92:93], v[48:49] op_sel:[0,1,0] op_sel_hi:[1,1,1]
	v_pk_fma_f32 v[50:51], v[110:111], v[68:69], v[50:51] op_sel:[0,1,0] op_sel_hi:[1,1,1]
	s_waitcnt lgkmcnt(11)
	ds_read_b128 v[70:73], v44 offset:15616
	ds_read_b128 v[74:77], v44 offset:15632
	ds_read_b128 v[78:81], v44 offset:16128
	ds_read_b128 v[82:85], v44 offset:16144
	ds_read_b128 v[86:89], v44 offset:16384
	ds_read_b128 v[90:93], v44 offset:16400
	ds_read_b64 v[146:147], v46 offset:15360
	ds_read_b128 v[62:65], v44 offset:17408
	ds_read_b128 v[66:69], v44 offset:17424
	v_add_f32_dpp v48, v48, v48 quad_perm:[1,0,3,2] row_mask:0xf bank_mask:0xf bound_ctrl:1
	v_add_f32_dpp v49, v49, v49 quad_perm:[1,0,3,2] row_mask:0xf bank_mask:0xf bound_ctrl:1
	v_add_f32_dpp v50, v50, v50 quad_perm:[1,0,3,2] row_mask:0xf bank_mask:0xf bound_ctrl:1
	v_add_f32_dpp v51, v51, v51 quad_perm:[1,0,3,2] row_mask:0xf bank_mask:0xf bound_ctrl:1
	v_pk_fma_f32 v[96:97], v[192:193], v[168:169], v[96:97] op_sel:[0,0,0] op_sel_hi:[1,0,1]
	v_pk_fma_f32 v[98:99], v[192:193], v[168:169], v[98:99] op_sel:[0,1,0] op_sel_hi:[1,1,1]
	v_pk_fma_f32 v[100:101], v[192:193], v[170:171], v[100:101] op_sel:[0,0,0] op_sel_hi:[1,0,1]
	v_add_f32_dpp v48, v48, v48 quad_perm:[2,3,0,1] row_mask:0xf bank_mask:0xf bound_ctrl:1
	v_add_f32_dpp v49, v49, v49 quad_perm:[2,3,0,1] row_mask:0xf bank_mask:0xf bound_ctrl:1
	v_add_f32_dpp v50, v50, v50 quad_perm:[2,3,0,1] row_mask:0xf bank_mask:0xf bound_ctrl:1
	v_add_f32_dpp v51, v51, v51 quad_perm:[2,3,0,1] row_mask:0xf bank_mask:0xf bound_ctrl:1
	v_pk_fma_f32 v[102:103], v[192:193], v[170:171], v[102:103] op_sel:[0,1,0] op_sel_hi:[1,1,1]
; #define LAS __attribute__((address_space(3)))
; __device__ __forceinline__ float red8(float x) { x += dpp_mov<0xB1>(x); x += dpp_mov<0x4E>(x); x += dpp_mov<0x141>(x); return x; }
; __device__ __forceinline__ void scan_phase(const KP& P, LAS unsigned char* lds, const int tid, const int bx, const int G) {
;     ...
;             for (int s = 0; s < 32; ++s) {
;                 const LAS float* p = cb + s * 384;
;                 const f32x4 w0 = *(const LAS f32x4*)(p), w1 = *(const LAS f32x4*)(p + 4);
;                 const f32x4 k0 = *(const LAS f32x4*)(p + 64), k1 = *(const LAS f32x4*)(p + 68);
;                 const f32x4 a0 = *(const LAS f32x4*)(p + 128), a1 = *(const LAS f32x4*)(p + 132);
;                 const f32x4 b0 = *(const LAS f32x4*)(p + 192), b1 = *(const LAS f32x4*)(p + 196);
;                 const f32x4 r0 = *(const LAS f32x4*)(p + 256), r1 = *(const LAS f32x4*)(p + 260);
;                 const float vv = buf[(c & 1) * 12288 + s * 384 + 320 + v];
;                 f32x2 sa2 = S[0] * (f32x2){a0.x, a0.y};
;                 sa2 += S[1] * (f32x2){a0.z, a0.w}; sa2 += S[2] * (f32x2){a1.x, a1.y}; sa2 += S[3] * (f32x2){a1.z, a1.w};
;                 const float sa = red8(sa2.x + sa2.y);
;                 const f32x2 sav = {sa, sa}, vv2 = {vv, vv};
;                 S[0] = S[0] * (f32x2){w0.x, w0.y} + sav * (f32x2){b0.x, b0.y} + vv2 * (f32x2){k0.x, k0.y};
;                 S[1] = S[1] * (f32x2){w0.z, w0.w} + sav * (f32x2){b0.z, b0.w} + vv2 * (f32x2){k0.z, k0.w};
;                 S[2] = S[2] * (f32x2){w1.x, w1.y} + sav * (f32x2){b1.x, b1.y} + vv2 * (f32x2){k1.x, k1.y};
;                 S[3] = S[3] * (f32x2){w1.z, w1.w} + sav * (f32x2){b1.z, b1.w} + vv2 * (f32x2){k1.z, k1.w};
;                 f32x2 y2 = S[0] * (f32x2){r0.x, r0.y};
;                 y2 += S[1] * (f32x2){r0.z, r0.w}; y2 += S[2] * (f32x2){r1.x, r1.y}; y2 += S[3] * (f32x2){r1.z, r1.w};
;                 const float y = red8(y2.x + y2.y);
;                 if (kc == 0) ybuf[s * 64 + v] = y;
;             }
	v_pk_fma_f32 v[104:105], v[192:193], v[172:173], v[104:105] op_sel:[0,0,0] op_sel_hi:[1,0,1]
	v_pk_fma_f32 v[106:107], v[192:193], v[172:173], v[106:107] op_sel:[0,1,0] op_sel_hi:[1,1,1]
	v_add_f32_dpp v50, v50, v50 row_half_mirror row_mask:0xf bank_mask:0xf bound_ctrl:1
	v_add_f32_dpp v51, v51, v51 row_half_mirror row_mask:0xf bank_mask:0xf bound_ctrl:1
	v_pk_fma_f32 v[108:109], v[192:193], v[174:175], v[108:109] op_sel:[0,0,0] op_sel_hi:[1,0,1]
	s_mov_b64 exec, s[86:87]
	ds_write_b64 v45, v[48:49] offset:3584
	s_mov_b64 exec, s[0:1]
	v_pk_fma_f32 v[110:111], v[192:193], v[174:175], v[110:111] op_sel:[0,1,0] op_sel_hi:[1,1,1]
	v_pk_fma_f32 v[96:97], v[50:51], v[176:177], v[96:97] op_sel:[0,0,0] op_sel_hi:[1,0,1]
	v_pk_fma_f32 v[98:99], v[50:51], v[176:177], v[98:99] op_sel:[0,1,0] op_sel_hi:[1,1,1]
	v_pk_fma_f32 v[100:101], v[50:51], v[178:179], v[100:101] op_sel:[0,0,0] op_sel_hi:[1,0,1]
	v_pk_fma_f32 v[102:103], v[50:51], v[178:179], v[102:103] op_sel:[0,1,0] op_sel_hi:[1,1,1]
	v_pk_fma_f32 v[104:105], v[50:51], v[180:181], v[104:105] op_sel:[0,0,0] op_sel_hi:[1,0,1]
	v_pk_fma_f32 v[106:107], v[50:51], v[180:181], v[106:107] op_sel:[0,1,0] op_sel_hi:[1,1,1]
	v_pk_fma_f32 v[108:109], v[50:51], v[182:183], v[108:109] op_sel:[0,0,0] op_sel_hi:[1,0,1]
	v_pk_fma_f32 v[110:111], v[50:51], v[182:183], v[110:111] op_sel:[0,1,0] op_sel_hi:[1,1,1]
	v_pk_mul_f32 v[48:49], v[96:97], v[184:185] op_sel:[0,0] op_sel_hi:[1,0]
	v_pk_mul_f32 v[50:51], v[96:97], v[148:149] op_sel:[0,0] op_sel_hi:[1,0]
	v_pk_fma_f32 v[48:49], v[98:99], v[184:185], v[48:49] op_sel:[0,1,0] op_sel_hi:[1,1,1]
	v_pk_fma_f32 v[50:51], v[98:99], v[148:149], v[50:51] op_sel:[0,1,0] op_sel_hi:[1,1,1]
	v_pk_fma_f32 v[48:49], v[100:101], v[186:187], v[48:49] op_sel:[0,0,0] op_sel_hi:[1,0,1]
	v_pk_fma_f32 v[50:51], v[100:101], v[150:151], v[50:51] op_sel:[0,0,0] op_sel_hi:[1,0,1]
	v_pk_fma_f32 v[48:49], v[102:103], v[186:187], v[48:49] op_sel:[0,1,0] op_sel_hi:[1,1,1]
	v_pk_fma_f32 v[50:51], v[102:103], v[150:151], v[50:51] op_sel:[0,1,0] op_sel_hi:[1,1,1]
	v_pk_fma_f32 v[48:49], v[104:105], v[188:189], v[48:49] op_sel:[0,0,0] op_sel_hi:[1,0,1]
	v_pk_fma_f32 v[50:51], v[104:105], v[152:153], v[50:51] op_sel:[0,0,0] op_sel_hi:[1,0,1]
	v_pk_fma_f32 v[48:49], v[106:107], v[188:189], v[48:49] op_sel:[0,1,0] op_sel_hi:[1,1,1]
	v_pk_fma_f32 v[50:51], v[106:107], v[152:153], v[50:51] op_sel:[0,1,0] op_sel_hi:[1,1,1]
	v_pk_fma_f32 v[48:49], v[108:109], v[190:191], v[48:49] op_sel:[0,0,0] op_sel_hi:[1,0,1]
	v_pk_fma_f32 v[50:51], v[108:109], v[154:155], v[50:51] op_sel:[0,0,0] op_sel_hi:[1,0,1]
	v_pk_fma_f32 v[48:49], v[110:111], v[190:191], v[48:49] op_sel:[0,1,0] op_sel_hi:[1,1,1]
	v_pk_fma_f32 v[50:51], v[110:111], v[154:155], v[50:51] op_sel:[0,1,0] op_sel_hi:[1,1,1]
	s_waitcnt lgkmcnt(11)
	ds_read_b128 v[168:171], v44 offset:17152
	ds_read_b128 v[172:175], v44 offset:17168
	ds_read_b128 v[176:179], v44 offset:17664
	ds_read_b128 v[180:183], v44 offset:17680
	ds_read_b128 v[184:187], v44 offset:17920
	ds_read_b128 v[188:191], v44 offset:17936
	ds_read_b64 v[192:193], v46 offset:16896
	ds_read_b128 v[148:151], v44 offset:18944
	ds_read_b128 v[152:155], v44 offset:18960
	v_add_f32_dpp v48, v48, v48 quad_perm:[1,0,3,2] row_mask:0xf bank_mask:0xf bound_ctrl:1
	v_add_f32_dpp v49, v49, v49 quad_perm:[1,0,3,2] row_mask:0xf bank_mask:0xf bound_ctrl:1
	v_add_f32_dpp v50, v50, v50 quad_perm:[1,0,3,2] row_mask:0xf bank_mask:0xf bound_ctrl:1
	v_add_f32_dpp v51, v51, v51 quad_perm:[1,0,3,2] row_mask:0xf bank_mask:0xf bound_ctrl:1
	v_pk_fma_f32 v[96:97], v[144:145], v[120:121], v[96:97] op_sel:[0,0,0] op_sel_hi:[1,0,1]
	v_pk_fma_f32 v[98:99], v[144:145], v[120:121], v[98:99] op_sel:[0,1,0] op_sel_hi:[1,1,1]
	v_pk_fma_f32 v[100:101], v[144:145], v[122:123], v[100:101] op_sel:[0,0,0] op_sel_hi:[1,0,1]
	v_add_f32_dpp v48, v48, v48 quad_perm:[2,3,0,1] row_mask:0xf bank_mask:0xf bound_ctrl:1
	v_add_f32_dpp v49, v49, v49 quad_perm:[2,3,0,1] row_mask:0xf bank_mask:0xf bound_ctrl:1
	v_add_f32_dpp v50, v50, v50 quad_perm:[2,3,0,1] row_mask:0xf bank_mask:0xf bound_ctrl:1
	v_add_f32_dpp v51, v51, v51 quad_perm:[2,3,0,1] row_mask:0xf bank_mask:0xf bound_ctrl:1
	v_pk_fma_f32 v[102:103], v[144:145], v[122:123], v[102:103] op_sel:[0,1,0] op_sel_hi:[1,1,1]
	v_pk_fma_f32 v[104:105], v[144:145], v[124:125], v[104:105] op_sel:[0,0,0] op_sel_hi:[1,0,1]
	v_pk_fma_f32 v[106:107], v[144:145], v[124:125], v[106:107] op_sel:[0,1,0] op_sel_hi:[1,1,1]
	v_add_f32_dpp v50, v50, v50 row_half_mirror row_mask:0xf bank_mask:0xf bound_ctrl:1
	v_add_f32_dpp v51, v51, v51 row_half_mirror row_mask:0xf bank_mask:0xf bound_ctrl:1
	v_pk_fma_f32 v[108:109], v[144:145], v[126:127], v[108:109] op_sel:[0,0,0] op_sel_hi:[1,0,1]
	s_mov_b64 exec, s[86:87]
	ds_write_b64 v45, v[48:49] offset:4096
	s_mov_b64 exec, s[0:1]
	v_pk_fma_f32 v[110:111], v[144:145], v[126:127], v[110:111] op_sel:[0,1,0] op_sel_hi:[1,1,1]
	v_pk_fma_f32 v[96:97], v[50:51], v[128:129], v[96:97] op_sel:[0,0,0] op_sel_hi:[1,0,1]
	v_pk_fma_f32 v[98:99], v[50:51], v[128:129], v[98:99] op_sel:[0,1,0] op_sel_hi:[1,1,1]
	v_pk_fma_f32 v[100:101], v[50:51], v[130:131], v[100:101] op_sel:[0,0,0] op_sel_hi:[1,0,1]
	v_pk_fma_f32 v[102:103], v[50:51], v[130:131], v[102:103] op_sel:[0,1,0] op_sel_hi:[1,1,1]
	v_pk_fma_f32 v[104:105], v[50:51], v[132:133], v[104:105] op_sel:[0,0,0] op_sel_hi:[1,0,1]
	v_pk_fma_f32 v[106:107], v[50:51], v[132:133], v[106:107] op_sel:[0,1,0] op_sel_hi:[1,1,1]
	v_pk_fma_f32 v[108:109], v[50:51], v[134:135], v[108:109] op_sel:[0,0,0] op_sel_hi:[1,0,1]
	v_pk_fma_f32 v[110:111], v[50:51], v[134:135], v[110:111] op_sel:[0,1,0] op_sel_hi:[1,1,1]
	v_pk_mul_f32 v[48:49], v[96:97], v[136:137] op_sel:[0,0] op_sel_hi:[1,0]
	v_pk_mul_f32 v[50:51], v[96:97], v[156:157] op_sel:[0,0] op_sel_hi:[1,0]
	v_pk_fma_f32 v[48:49], v[98:99], v[136:137], v[48:49] op_sel:[0,1,0] op_sel_hi:[1,1,1]
	v_pk_fma_f32 v[50:51], v[98:99], v[156:157], v[50:51] op_sel:[0,1,0] op_sel_hi:[1,1,1]
	v_pk_fma_f32 v[48:49], v[100:101], v[138:139], v[48:49] op_sel:[0,0,0] op_sel_hi:[1,0,1]
	v_pk_fma_f32 v[50:51], v[100:101], v[158:159], v[50:51] op_sel:[0,0,0] op_sel_hi:[1,0,1]
	v_pk_fma_f32 v[48:49], v[102:103], v[138:139], v[48:49] op_sel:[0,1,0] op_sel_hi:[1,1,1]
	v_pk_fma_f32 v[50:51], v[102:103], v[158:159], v[50:51] op_sel:[0,1,0] op_sel_hi:[1,1,1]
	v_pk_fma_f32 v[48:49], v[104:105], v[140:141], v[48:49] op_sel:[0,0,0] op_sel_hi:[1,0,1]
	v_pk_fma_f32 v[50:51], v[104:105], v[160:161], v[50:51] op_sel:[0,0,0] op_sel_hi:[1,0,1]
	v_pk_fma_f32 v[48:49], v[106:107], v[140:141], v[48:49] op_sel:[0,1,0] op_sel_hi:[1,1,1]
	v_pk_fma_f32 v[50:51], v[106:107], v[160:161], v[50:51] op_sel:[0,1,0] op_sel_hi:[1,1,1]
	v_pk_fma_f32 v[48:49], v[108:109], v[142:143], v[48:49] op_sel:[0,0,0] op_sel_hi:[1,0,1]
	v_pk_fma_f32 v[50:51], v[108:109], v[162:163], v[50:51] op_sel:[0,0,0] op_sel_hi:[1,0,1]
	v_pk_fma_f32 v[48:49], v[110:111], v[142:143], v[48:49] op_sel:[0,1,0] op_sel_hi:[1,1,1]
	v_pk_fma_f32 v[50:51], v[110:111], v[162:163], v[50:51] op_sel:[0,1,0] op_sel_hi:[1,1,1]
	s_waitcnt lgkmcnt(11)
; #define LAS __attribute__((address_space(3)))
; __device__ __forceinline__ float red8(float x) { x += dpp_mov<0xB1>(x); x += dpp_mov<0x4E>(x); x += dpp_mov<0x141>(x); return x; }
; __device__ __forceinline__ void scan_phase(const KP& P, LAS unsigned char* lds, const int tid, const int bx, const int G) {
;     ...
;             for (int s = 0; s < 32; ++s) {
;                 const LAS float* p = cb + s * 384;
;                 const f32x4 w0 = *(const LAS f32x4*)(p), w1 = *(const LAS f32x4*)(p + 4);
;                 const f32x4 k0 = *(const LAS f32x4*)(p + 64), k1 = *(const LAS f32x4*)(p + 68);
;                 const f32x4 a0 = *(const LAS f32x4*)(p + 128), a1 = *(const LAS f32x4*)(p + 132);
;                 const f32x4 b0 = *(const LAS f32x4*)(p + 192), b1 = *(const LAS f32x4*)(p + 196);
;                 const f32x4 r0 = *(const LAS f32x4*)(p + 256), r1 = *(const LAS f32x4*)(p + 260);
;                 const float vv = buf[(c & 1) * 12288 + s * 384 + 320 + v];
;                 f32x2 sa2 = S[0] * (f32x2){a0.x, a0.y};
;                 sa2 += S[1] * (f32x2){a0.z, a0.w}; sa2 += S[2] * (f32x2){a1.x, a1.y}; sa2 += S[3] * (f32x2){a1.z, a1.w};
;                 const float sa = red8(sa2.x + sa2.y);
;                 const f32x2 sav = {sa, sa}, vv2 = {vv, vv};
;                 S[0] = S[0] * (f32x2){w0.x, w0.y} + sav * (f32x2){b0.x, b0.y} + vv2 * (f32x2){k0.x, k0.y};
;                 S[1] = S[1] * (f32x2){w0.z, w0.w} + sav * (f32x2){b0.z, b0.w} + vv2 * (f32x2){k0.z, k0.w};
;                 S[2] = S[2] * (f32x2){w1.x, w1.y} + sav * (f32x2){b1.x, b1.y} + vv2 * (f32x2){k1.x, k1.y};
;                 S[3] = S[3] * (f32x2){w1.z, w1.w} + sav * (f32x2){b1.z, b1.w} + vv2 * (f32x2){k1.z, k1.w};
;                 f32x2 y2 = S[0] * (f32x2){r0.x, r0.y};
;                 y2 += S[1] * (f32x2){r0.z, r0.w}; y2 += S[2] * (f32x2){r1.x, r1.y}; y2 += S[3] * (f32x2){r1.z, r1.w};
;                 const float y = red8(y2.x + y2.y);
;                 if (kc == 0) ybuf[s * 64 + v] = y;
;             }
	ds_read_b128 v[120:123], v44 offset:18688
	ds_read_b128 v[124:127], v44 offset:18704
	ds_read_b128 v[128:131], v44 offset:19200
	ds_read_b128 v[132:135], v44 offset:19216
	ds_read_b128 v[136:139], v44 offset:19456
	ds_read_b128 v[140:143], v44 offset:19472
	ds_read_b64 v[144:145], v46 offset:18432
	ds_read_b128 v[156:159], v44 offset:20480
	ds_read_b128 v[160:163], v44 offset:20496
	v_add_f32_dpp v48, v48, v48 quad_perm:[1,0,3,2] row_mask:0xf bank_mask:0xf bound_ctrl:1
	v_add_f32_dpp v49, v49, v49 quad_perm:[1,0,3,2] row_mask:0xf bank_mask:0xf bound_ctrl:1
	v_add_f32_dpp v50, v50, v50 quad_perm:[1,0,3,2] row_mask:0xf bank_mask:0xf bound_ctrl:1
	v_add_f32_dpp v51, v51, v51 quad_perm:[1,0,3,2] row_mask:0xf bank_mask:0xf bound_ctrl:1
	v_pk_fma_f32 v[96:97], v[146:147], v[70:71], v[96:97] op_sel:[0,0,0] op_sel_hi:[1,0,1]
	v_pk_fma_f32 v[98:99], v[146:147], v[70:71], v[98:99] op_sel:[0,1,0] op_sel_hi:[1,1,1]
	v_pk_fma_f32 v[100:101], v[146:147], v[72:73], v[100:101] op_sel:[0,0,0] op_sel_hi:[1,0,1]
	v_add_f32_dpp v48, v48, v48 quad_perm:[2,3,0,1] row_mask:0xf bank_mask:0xf bound_ctrl:1
	v_add_f32_dpp v49, v49, v49 quad_perm:[2,3,0,1] row_mask:0xf bank_mask:0xf bound_ctrl:1
	v_add_f32_dpp v50, v50, v50 quad_perm:[2,3,0,1] row_mask:0xf bank_mask:0xf bound_ctrl:1
	v_add_f32_dpp v51, v51, v51 quad_perm:[2,3,0,1] row_mask:0xf bank_mask:0xf bound_ctrl:1
	v_pk_fma_f32 v[102:103], v[146:147], v[72:73], v[102:103] op_sel:[0,1,0] op_sel_hi:[1,1,1]
	v_pk_fma_f32 v[104:105], v[146:147], v[74:75], v[104:105] op_sel:[0,0,0] op_sel_hi:[1,0,1]
	v_pk_fma_f32 v[106:107], v[146:147], v[74:75], v[106:107] op_sel:[0,1,0] op_sel_hi:[1,1,1]
	v_add_f32_dpp v50, v50, v50 row_half_mirror row_mask:0xf bank_mask:0xf bound_ctrl:1
	v_add_f32_dpp v51, v51, v51 row_half_mirror row_mask:0xf bank_mask:0xf bound_ctrl:1
	v_pk_fma_f32 v[108:109], v[146:147], v[76:77], v[108:109] op_sel:[0,0,0] op_sel_hi:[1,0,1]
	s_mov_b64 exec, s[86:87]
	ds_write_b64 v45, v[48:49] offset:4608
	s_mov_b64 exec, s[0:1]
	v_pk_fma_f32 v[110:111], v[146:147], v[76:77], v[110:111] op_sel:[0,1,0] op_sel_hi:[1,1,1]
	v_pk_fma_f32 v[96:97], v[50:51], v[78:79], v[96:97] op_sel:[0,0,0] op_sel_hi:[1,0,1]
	v_pk_fma_f32 v[98:99], v[50:51], v[78:79], v[98:99] op_sel:[0,1,0] op_sel_hi:[1,1,1]
	v_pk_fma_f32 v[100:101], v[50:51], v[80:81], v[100:101] op_sel:[0,0,0] op_sel_hi:[1,0,1]
	v_pk_fma_f32 v[102:103], v[50:51], v[80:81], v[102:103] op_sel:[0,1,0] op_sel_hi:[1,1,1]
	v_pk_fma_f32 v[104:105], v[50:51], v[82:83], v[104:105] op_sel:[0,0,0] op_sel_hi:[1,0,1]
	v_pk_fma_f32 v[106:107], v[50:51], v[82:83], v[106:107] op_sel:[0,1,0] op_sel_hi:[1,1,1]
	v_pk_fma_f32 v[108:109], v[50:51], v[84:85], v[108:109] op_sel:[0,0,0] op_sel_hi:[1,0,1]
	v_pk_fma_f32 v[110:111], v[50:51], v[84:85], v[110:111] op_sel:[0,1,0] op_sel_hi:[1,1,1]
	v_pk_mul_f32 v[48:49], v[96:97], v[86:87] op_sel:[0,0] op_sel_hi:[1,0]
	v_pk_mul_f32 v[50:51], v[96:97], v[62:63] op_sel:[0,0] op_sel_hi:[1,0]
	v_pk_fma_f32 v[48:49], v[98:99], v[86:87], v[48:49] op_sel:[0,1,0] op_sel_hi:[1,1,1]
	v_pk_fma_f32 v[50:51], v[98:99], v[62:63], v[50:51] op_sel:[0,1,0] op_sel_hi:[1,1,1]
	v_pk_fma_f32 v[48:49], v[100:101], v[88:89], v[48:49] op_sel:[0,0,0] op_sel_hi:[1,0,1]
	v_pk_fma_f32 v[50:51], v[100:101], v[64:65], v[50:51] op_sel:[0,0,0] op_sel_hi:[1,0,1]
	v_pk_fma_f32 v[48:49], v[102:103], v[88:89], v[48:49] op_sel:[0,1,0] op_sel_hi:[1,1,1]
	v_pk_fma_f32 v[50:51], v[102:103], v[64:65], v[50:51] op_sel:[0,1,0] op_sel_hi:[1,1,1]
	v_pk_fma_f32 v[48:49], v[104:105], v[90:91], v[48:49] op_sel:[0,0,0] op_sel_hi:[1,0,1]
	v_pk_fma_f32 v[50:51], v[104:105], v[66:67], v[50:51] op_sel:[0,0,0] op_sel_hi:[1,0,1]
	v_pk_fma_f32 v[48:49], v[106:107], v[90:91], v[48:49] op_sel:[0,1,0] op_sel_hi:[1,1,1]
	v_pk_fma_f32 v[50:51], v[106:107], v[66:67], v[50:51] op_sel:[0,1,0] op_sel_hi:[1,1,1]
	v_pk_fma_f32 v[48:49], v[108:109], v[92:93], v[48:49] op_sel:[0,0,0] op_sel_hi:[1,0,1]
	v_pk_fma_f32 v[50:51], v[108:109], v[68:69], v[50:51] op_sel:[0,0,0] op_sel_hi:[1,0,1]
	v_pk_fma_f32 v[48:49], v[110:111], v[92:93], v[48:49] op_sel:[0,1,0] op_sel_hi:[1,1,1]
	v_pk_fma_f32 v[50:51], v[110:111], v[68:69], v[50:51] op_sel:[0,1,0] op_sel_hi:[1,1,1]
	s_waitcnt lgkmcnt(11)
	ds_read_b128 v[70:73], v44 offset:20224
	ds_read_b128 v[74:77], v44 offset:20240
	ds_read_b128 v[78:81], v44 offset:20736
	ds_read_b128 v[82:85], v44 offset:20752
	ds_read_b128 v[86:89], v44 offset:20992
	ds_read_b128 v[90:93], v44 offset:21008
	ds_read_b64 v[146:147], v46 offset:19968
	ds_read_b128 v[62:65], v44 offset:22016
	ds_read_b128 v[66:69], v44 offset:22032
	v_add_f32_dpp v48, v48, v48 quad_perm:[1,0,3,2] row_mask:0xf bank_mask:0xf bound_ctrl:1
	v_add_f32_dpp v49, v49, v49 quad_perm:[1,0,3,2] row_mask:0xf bank_mask:0xf bound_ctrl:1
	v_add_f32_dpp v50, v50, v50 quad_perm:[1,0,3,2] row_mask:0xf bank_mask:0xf bound_ctrl:1
	v_add_f32_dpp v51, v51, v51 quad_perm:[1,0,3,2] row_mask:0xf bank_mask:0xf bound_ctrl:1
	v_pk_fma_f32 v[96:97], v[192:193], v[168:169], v[96:97] op_sel:[0,0,0] op_sel_hi:[1,0,1]
	v_pk_fma_f32 v[98:99], v[192:193], v[168:169], v[98:99] op_sel:[0,1,0] op_sel_hi:[1,1,1]
	v_pk_fma_f32 v[100:101], v[192:193], v[170:171], v[100:101] op_sel:[0,0,0] op_sel_hi:[1,0,1]
	v_add_f32_dpp v48, v48, v48 quad_perm:[2,3,0,1] row_mask:0xf bank_mask:0xf bound_ctrl:1
	v_add_f32_dpp v49, v49, v49 quad_perm:[2,3,0,1] row_mask:0xf bank_mask:0xf bound_ctrl:1
	v_add_f32_dpp v50, v50, v50 quad_perm:[2,3,0,1] row_mask:0xf bank_mask:0xf bound_ctrl:1
	v_add_f32_dpp v51, v51, v51 quad_perm:[2,3,0,1] row_mask:0xf bank_mask:0xf bound_ctrl:1
	v_pk_fma_f32 v[102:103], v[192:193], v[170:171], v[102:103] op_sel:[0,1,0] op_sel_hi:[1,1,1]
; #define LAS __attribute__((address_space(3)))
; __device__ __forceinline__ float red8(float x) { x += dpp_mov<0xB1>(x); x += dpp_mov<0x4E>(x); x += dpp_mov<0x141>(x); return x; }
; __device__ __forceinline__ void scan_phase(const KP& P, LAS unsigned char* lds, const int tid, const int bx, const int G) {
;     ...
;             for (int s = 0; s < 32; ++s) {
;                 const LAS float* p = cb + s * 384;
;                 const f32x4 w0 = *(const LAS f32x4*)(p), w1 = *(const LAS f32x4*)(p + 4);
;                 const f32x4 k0 = *(const LAS f32x4*)(p + 64), k1 = *(const LAS f32x4*)(p + 68);
;                 const f32x4 a0 = *(const LAS f32x4*)(p + 128), a1 = *(const LAS f32x4*)(p + 132);
;                 const f32x4 b0 = *(const LAS f32x4*)(p + 192), b1 = *(const LAS f32x4*)(p + 196);
;                 const f32x4 r0 = *(const LAS f32x4*)(p + 256), r1 = *(const LAS f32x4*)(p + 260);
;                 const float vv = buf[(c & 1) * 12288 + s * 384 + 320 + v];
;                 f32x2 sa2 = S[0] * (f32x2){a0.x, a0.y};
;                 sa2 += S[1] * (f32x2){a0.z, a0.w}; sa2 += S[2] * (f32x2){a1.x, a1.y}; sa2 += S[3] * (f32x2){a1.z, a1.w};
;                 const float sa = red8(sa2.x + sa2.y);
;                 const f32x2 sav = {sa, sa}, vv2 = {vv, vv};
;                 S[0] = S[0] * (f32x2){w0.x, w0.y} + sav * (f32x2){b0.x, b0.y} + vv2 * (f32x2){k0.x, k0.y};
;                 S[1] = S[1] * (f32x2){w0.z, w0.w} + sav * (f32x2){b0.z, b0.w} + vv2 * (f32x2){k0.z, k0.w};
;                 S[2] = S[2] * (f32x2){w1.x, w1.y} + sav * (f32x2){b1.x, b1.y} + vv2 * (f32x2){k1.x, k1.y};
;                 S[3] = S[3] * (f32x2){w1.z, w1.w} + sav * (f32x2){b1.z, b1.w} + vv2 * (f32x2){k1.z, k1.w};
;                 f32x2 y2 = S[0] * (f32x2){r0.x, r0.y};
;                 y2 += S[1] * (f32x2){r0.z, r0.w}; y2 += S[2] * (f32x2){r1.x, r1.y}; y2 += S[3] * (f32x2){r1.z, r1.w};
;                 const float y = red8(y2.x + y2.y);
;                 if (kc == 0) ybuf[s * 64 + v] = y;
;             }
	v_pk_fma_f32 v[104:105], v[192:193], v[172:173], v[104:105] op_sel:[0,0,0] op_sel_hi:[1,0,1]
	v_pk_fma_f32 v[106:107], v[192:193], v[172:173], v[106:107] op_sel:[0,1,0] op_sel_hi:[1,1,1]
	v_add_f32_dpp v50, v50, v50 row_half_mirror row_mask:0xf bank_mask:0xf bound_ctrl:1
	v_add_f32_dpp v51, v51, v51 row_half_mirror row_mask:0xf bank_mask:0xf bound_ctrl:1
	v_pk_fma_f32 v[108:109], v[192:193], v[174:175], v[108:109] op_sel:[0,0,0] op_sel_hi:[1,0,1]
	s_mov_b64 exec, s[86:87]
	ds_write_b64 v45, v[48:49] offset:5120
	s_mov_b64 exec, s[0:1]
	v_pk_fma_f32 v[110:111], v[192:193], v[174:175], v[110:111] op_sel:[0,1,0] op_sel_hi:[1,1,1]
	v_pk_fma_f32 v[96:97], v[50:51], v[176:177], v[96:97] op_sel:[0,0,0] op_sel_hi:[1,0,1]
	v_pk_fma_f32 v[98:99], v[50:51], v[176:177], v[98:99] op_sel:[0,1,0] op_sel_hi:[1,1,1]
	v_pk_fma_f32 v[100:101], v[50:51], v[178:179], v[100:101] op_sel:[0,0,0] op_sel_hi:[1,0,1]
	v_pk_fma_f32 v[102:103], v[50:51], v[178:179], v[102:103] op_sel:[0,1,0] op_sel_hi:[1,1,1]
	v_pk_fma_f32 v[104:105], v[50:51], v[180:181], v[104:105] op_sel:[0,0,0] op_sel_hi:[1,0,1]
	v_pk_fma_f32 v[106:107], v[50:51], v[180:181], v[106:107] op_sel:[0,1,0] op_sel_hi:[1,1,1]
	v_pk_fma_f32 v[108:109], v[50:51], v[182:183], v[108:109] op_sel:[0,0,0] op_sel_hi:[1,0,1]
	v_pk_fma_f32 v[110:111], v[50:51], v[182:183], v[110:111] op_sel:[0,1,0] op_sel_hi:[1,1,1]
	v_pk_mul_f32 v[48:49], v[96:97], v[184:185] op_sel:[0,0] op_sel_hi:[1,0]
	v_pk_mul_f32 v[50:51], v[96:97], v[148:149] op_sel:[0,0] op_sel_hi:[1,0]
	v_pk_fma_f32 v[48:49], v[98:99], v[184:185], v[48:49] op_sel:[0,1,0] op_sel_hi:[1,1,1]
	v_pk_fma_f32 v[50:51], v[98:99], v[148:149], v[50:51] op_sel:[0,1,0] op_sel_hi:[1,1,1]
	v_pk_fma_f32 v[48:49], v[100:101], v[186:187], v[48:49] op_sel:[0,0,0] op_sel_hi:[1,0,1]
	v_pk_fma_f32 v[50:51], v[100:101], v[150:151], v[50:51] op_sel:[0,0,0] op_sel_hi:[1,0,1]
	v_pk_fma_f32 v[48:49], v[102:103], v[186:187], v[48:49] op_sel:[0,1,0] op_sel_hi:[1,1,1]
	v_pk_fma_f32 v[50:51], v[102:103], v[150:151], v[50:51] op_sel:[0,1,0] op_sel_hi:[1,1,1]
	v_pk_fma_f32 v[48:49], v[104:105], v[188:189], v[48:49] op_sel:[0,0,0] op_sel_hi:[1,0,1]
	v_pk_fma_f32 v[50:51], v[104:105], v[152:153], v[50:51] op_sel:[0,0,0] op_sel_hi:[1,0,1]
	v_pk_fma_f32 v[48:49], v[106:107], v[188:189], v[48:49] op_sel:[0,1,0] op_sel_hi:[1,1,1]
	v_pk_fma_f32 v[50:51], v[106:107], v[152:153], v[50:51] op_sel:[0,1,0] op_sel_hi:[1,1,1]
	v_pk_fma_f32 v[48:49], v[108:109], v[190:191], v[48:49] op_sel:[0,0,0] op_sel_hi:[1,0,1]
	v_pk_fma_f32 v[50:51], v[108:109], v[154:155], v[50:51] op_sel:[0,0,0] op_sel_hi:[1,0,1]
	v_pk_fma_f32 v[48:49], v[110:111], v[190:191], v[48:49] op_sel:[0,1,0] op_sel_hi:[1,1,1]
	v_pk_fma_f32 v[50:51], v[110:111], v[154:155], v[50:51] op_sel:[0,1,0] op_sel_hi:[1,1,1]
	s_waitcnt lgkmcnt(11)
	ds_read_b128 v[168:171], v44 offset:21760
	ds_read_b128 v[172:175], v44 offset:21776
	ds_read_b128 v[176:179], v44 offset:22272
	ds_read_b128 v[180:183], v44 offset:22288
	ds_read_b128 v[184:187], v44 offset:22528
	ds_read_b128 v[188:191], v44 offset:22544
	ds_read_b64 v[192:193], v46 offset:21504
	ds_read_b128 v[148:151], v44 offset:23552
	ds_read_b128 v[152:155], v44 offset:23568
	v_add_f32_dpp v48, v48, v48 quad_perm:[1,0,3,2] row_mask:0xf bank_mask:0xf bound_ctrl:1
	v_add_f32_dpp v49, v49, v49 quad_perm:[1,0,3,2] row_mask:0xf bank_mask:0xf bound_ctrl:1
	v_add_f32_dpp v50, v50, v50 quad_perm:[1,0,3,2] row_mask:0xf bank_mask:0xf bound_ctrl:1
	v_add_f32_dpp v51, v51, v51 quad_perm:[1,0,3,2] row_mask:0xf bank_mask:0xf bound_ctrl:1
	v_pk_fma_f32 v[96:97], v[144:145], v[120:121], v[96:97] op_sel:[0,0,0] op_sel_hi:[1,0,1]
	v_pk_fma_f32 v[98:99], v[144:145], v[120:121], v[98:99] op_sel:[0,1,0] op_sel_hi:[1,1,1]
	v_pk_fma_f32 v[100:101], v[144:145], v[122:123], v[100:101] op_sel:[0,0,0] op_sel_hi:[1,0,1]
	v_add_f32_dpp v48, v48, v48 quad_perm:[2,3,0,1] row_mask:0xf bank_mask:0xf bound_ctrl:1
	v_add_f32_dpp v49, v49, v49 quad_perm:[2,3,0,1] row_mask:0xf bank_mask:0xf bound_ctrl:1
	v_add_f32_dpp v50, v50, v50 quad_perm:[2,3,0,1] row_mask:0xf bank_mask:0xf bound_ctrl:1
	v_add_f32_dpp v51, v51, v51 quad_perm:[2,3,0,1] row_mask:0xf bank_mask:0xf bound_ctrl:1
	v_pk_fma_f32 v[102:103], v[144:145], v[122:123], v[102:103] op_sel:[0,1,0] op_sel_hi:[1,1,1]
	v_pk_fma_f32 v[104:105], v[144:145], v[124:125], v[104:105] op_sel:[0,0,0] op_sel_hi:[1,0,1]
	v_pk_fma_f32 v[106:107], v[144:145], v[124:125], v[106:107] op_sel:[0,1,0] op_sel_hi:[1,1,1]
	v_add_f32_dpp v50, v50, v50 row_half_mirror row_mask:0xf bank_mask:0xf bound_ctrl:1
	v_add_f32_dpp v51, v51, v51 row_half_mirror row_mask:0xf bank_mask:0xf bound_ctrl:1
	v_pk_fma_f32 v[108:109], v[144:145], v[126:127], v[108:109] op_sel:[0,0,0] op_sel_hi:[1,0,1]
	s_mov_b64 exec, s[86:87]
	ds_write_b64 v45, v[48:49] offset:5632
	s_mov_b64 exec, s[0:1]
	v_pk_fma_f32 v[110:111], v[144:145], v[126:127], v[110:111] op_sel:[0,1,0] op_sel_hi:[1,1,1]
	v_pk_fma_f32 v[96:97], v[50:51], v[128:129], v[96:97] op_sel:[0,0,0] op_sel_hi:[1,0,1]
	v_pk_fma_f32 v[98:99], v[50:51], v[128:129], v[98:99] op_sel:[0,1,0] op_sel_hi:[1,1,1]
	v_pk_fma_f32 v[100:101], v[50:51], v[130:131], v[100:101] op_sel:[0,0,0] op_sel_hi:[1,0,1]
	v_pk_fma_f32 v[102:103], v[50:51], v[130:131], v[102:103] op_sel:[0,1,0] op_sel_hi:[1,1,1]
	v_pk_fma_f32 v[104:105], v[50:51], v[132:133], v[104:105] op_sel:[0,0,0] op_sel_hi:[1,0,1]
	v_pk_fma_f32 v[106:107], v[50:51], v[132:133], v[106:107] op_sel:[0,1,0] op_sel_hi:[1,1,1]
	v_pk_fma_f32 v[108:109], v[50:51], v[134:135], v[108:109] op_sel:[0,0,0] op_sel_hi:[1,0,1]
	v_pk_fma_f32 v[110:111], v[50:51], v[134:135], v[110:111] op_sel:[0,1,0] op_sel_hi:[1,1,1]
	v_pk_mul_f32 v[48:49], v[96:97], v[136:137] op_sel:[0,0] op_sel_hi:[1,0]
	v_pk_mul_f32 v[50:51], v[96:97], v[156:157] op_sel:[0,0] op_sel_hi:[1,0]
	v_pk_fma_f32 v[48:49], v[98:99], v[136:137], v[48:49] op_sel:[0,1,0] op_sel_hi:[1,1,1]
	v_pk_fma_f32 v[50:51], v[98:99], v[156:157], v[50:51] op_sel:[0,1,0] op_sel_hi:[1,1,1]
	v_pk_fma_f32 v[48:49], v[100:101], v[138:139], v[48:49] op_sel:[0,0,0] op_sel_hi:[1,0,1]
	v_pk_fma_f32 v[50:51], v[100:101], v[158:159], v[50:51] op_sel:[0,0,0] op_sel_hi:[1,0,1]
	v_pk_fma_f32 v[48:49], v[102:103], v[138:139], v[48:49] op_sel:[0,1,0] op_sel_hi:[1,1,1]
	v_pk_fma_f32 v[50:51], v[102:103], v[158:159], v[50:51] op_sel:[0,1,0] op_sel_hi:[1,1,1]
	v_pk_fma_f32 v[48:49], v[104:105], v[140:141], v[48:49] op_sel:[0,0,0] op_sel_hi:[1,0,1]
	v_pk_fma_f32 v[50:51], v[104:105], v[160:161], v[50:51] op_sel:[0,0,0] op_sel_hi:[1,0,1]
	v_pk_fma_f32 v[48:49], v[106:107], v[140:141], v[48:49] op_sel:[0,1,0] op_sel_hi:[1,1,1]
	v_pk_fma_f32 v[50:51], v[106:107], v[160:161], v[50:51] op_sel:[0,1,0] op_sel_hi:[1,1,1]
	v_pk_fma_f32 v[48:49], v[108:109], v[142:143], v[48:49] op_sel:[0,0,0] op_sel_hi:[1,0,1]
	v_pk_fma_f32 v[50:51], v[108:109], v[162:163], v[50:51] op_sel:[0,0,0] op_sel_hi:[1,0,1]
	v_pk_fma_f32 v[48:49], v[110:111], v[142:143], v[48:49] op_sel:[0,1,0] op_sel_hi:[1,1,1]
	v_pk_fma_f32 v[50:51], v[110:111], v[162:163], v[50:51] op_sel:[0,1,0] op_sel_hi:[1,1,1]
	s_waitcnt lgkmcnt(11)
; #define LAS __attribute__((address_space(3)))
; __device__ __forceinline__ float red8(float x) { x += dpp_mov<0xB1>(x); x += dpp_mov<0x4E>(x); x += dpp_mov<0x141>(x); return x; }
; __device__ __forceinline__ void scan_phase(const KP& P, LAS unsigned char* lds, const int tid, const int bx, const int G) {
;     ...
;             for (int s = 0; s < 32; ++s) {
;                 const LAS float* p = cb + s * 384;
;                 const f32x4 w0 = *(const LAS f32x4*)(p), w1 = *(const LAS f32x4*)(p + 4);
;                 const f32x4 k0 = *(const LAS f32x4*)(p + 64), k1 = *(const LAS f32x4*)(p + 68);
;                 const f32x4 a0 = *(const LAS f32x4*)(p + 128), a1 = *(const LAS f32x4*)(p + 132);
;                 const f32x4 b0 = *(const LAS f32x4*)(p + 192), b1 = *(const LAS f32x4*)(p + 196);
;                 const f32x4 r0 = *(const LAS f32x4*)(p + 256), r1 = *(const LAS f32x4*)(p + 260);
;                 const float vv = buf[(c & 1) * 12288 + s * 384 + 320 + v];
;                 f32x2 sa2 = S[0] * (f32x2){a0.x, a0.y};
;                 sa2 += S[1] * (f32x2){a0.z, a0.w}; sa2 += S[2] * (f32x2){a1.x, a1.y}; sa2 += S[3] * (f32x2){a1.z, a1.w};
;                 const float sa = red8(sa2.x + sa2.y);
;                 const f32x2 sav = {sa, sa}, vv2 = {vv, vv};
;                 S[0] = S[0] * (f32x2){w0.x, w0.y} + sav * (f32x2){b0.x, b0.y} + vv2 * (f32x2){k0.x, k0.y};
;                 S[1] = S[1] * (f32x2){w0.z, w0.w} + sav * (f32x2){b0.z, b0.w} + vv2 * (f32x2){k0.z, k0.w};
;                 S[2] = S[2] * (f32x2){w1.x, w1.y} + sav * (f32x2){b1.x, b1.y} + vv2 * (f32x2){k1.x, k1.y};
;                 S[3] = S[3] * (f32x2){w1.z, w1.w} + sav * (f32x2){b1.z, b1.w} + vv2 * (f32x2){k1.z, k1.w};
;                 f32x2 y2 = S[0] * (f32x2){r0.x, r0.y};
;                 y2 += S[1] * (f32x2){r0.z, r0.w}; y2 += S[2] * (f32x2){r1.x, r1.y}; y2 += S[3] * (f32x2){r1.z, r1.w};
;                 const float y = red8(y2.x + y2.y);
;                 if (kc == 0) ybuf[s * 64 + v] = y;
;             }
	ds_read_b128 v[120:123], v44 offset:23296
	ds_read_b128 v[124:127], v44 offset:23312
	ds_read_b128 v[128:131], v44 offset:23808
	ds_read_b128 v[132:135], v44 offset:23824
	ds_read_b128 v[136:139], v44 offset:24064
	ds_read_b128 v[140:143], v44 offset:24080
	ds_read_b64 v[144:145], v46 offset:23040
	ds_read_b128 v[156:159], v44 offset:25088
	ds_read_b128 v[160:163], v44 offset:25104
	v_add_f32_dpp v48, v48, v48 quad_perm:[1,0,3,2] row_mask:0xf bank_mask:0xf bound_ctrl:1
	v_add_f32_dpp v49, v49, v49 quad_perm:[1,0,3,2] row_mask:0xf bank_mask:0xf bound_ctrl:1
	v_add_f32_dpp v50, v50, v50 quad_perm:[1,0,3,2] row_mask:0xf bank_mask:0xf bound_ctrl:1
	v_add_f32_dpp v51, v51, v51 quad_perm:[1,0,3,2] row_mask:0xf bank_mask:0xf bound_ctrl:1
	v_pk_fma_f32 v[96:97], v[146:147], v[70:71], v[96:97] op_sel:[0,0,0] op_sel_hi:[1,0,1]
	v_pk_fma_f32 v[98:99], v[146:147], v[70:71], v[98:99] op_sel:[0,1,0] op_sel_hi:[1,1,1]
	v_pk_fma_f32 v[100:101], v[146:147], v[72:73], v[100:101] op_sel:[0,0,0] op_sel_hi:[1,0,1]
	v_add_f32_dpp v48, v48, v48 quad_perm:[2,3,0,1] row_mask:0xf bank_mask:0xf bound_ctrl:1
	v_add_f32_dpp v49, v49, v49 quad_perm:[2,3,0,1] row_mask:0xf bank_mask:0xf bound_ctrl:1
	v_add_f32_dpp v50, v50, v50 quad_perm:[2,3,0,1] row_mask:0xf bank_mask:0xf bound_ctrl:1
	v_add_f32_dpp v51, v51, v51 quad_perm:[2,3,0,1] row_mask:0xf bank_mask:0xf bound_ctrl:1
	v_pk_fma_f32 v[102:103], v[146:147], v[72:73], v[102:103] op_sel:[0,1,0] op_sel_hi:[1,1,1]
	v_pk_fma_f32 v[104:105], v[146:147], v[74:75], v[104:105] op_sel:[0,0,0] op_sel_hi:[1,0,1]
	v_pk_fma_f32 v[106:107], v[146:147], v[74:75], v[106:107] op_sel:[0,1,0] op_sel_hi:[1,1,1]
	v_add_f32_dpp v50, v50, v50 row_half_mirror row_mask:0xf bank_mask:0xf bound_ctrl:1
	v_add_f32_dpp v51, v51, v51 row_half_mirror row_mask:0xf bank_mask:0xf bound_ctrl:1
	v_pk_fma_f32 v[108:109], v[146:147], v[76:77], v[108:109] op_sel:[0,0,0] op_sel_hi:[1,0,1]
	s_mov_b64 exec, s[86:87]
	ds_write_b64 v45, v[48:49] offset:6144
	s_mov_b64 exec, s[0:1]
	v_pk_fma_f32 v[110:111], v[146:147], v[76:77], v[110:111] op_sel:[0,1,0] op_sel_hi:[1,1,1]
	v_pk_fma_f32 v[96:97], v[50:51], v[78:79], v[96:97] op_sel:[0,0,0] op_sel_hi:[1,0,1]
	v_pk_fma_f32 v[98:99], v[50:51], v[78:79], v[98:99] op_sel:[0,1,0] op_sel_hi:[1,1,1]
	v_pk_fma_f32 v[100:101], v[50:51], v[80:81], v[100:101] op_sel:[0,0,0] op_sel_hi:[1,0,1]
	v_pk_fma_f32 v[102:103], v[50:51], v[80:81], v[102:103] op_sel:[0,1,0] op_sel_hi:[1,1,1]
	v_pk_fma_f32 v[104:105], v[50:51], v[82:83], v[104:105] op_sel:[0,0,0] op_sel_hi:[1,0,1]
	v_pk_fma_f32 v[106:107], v[50:51], v[82:83], v[106:107] op_sel:[0,1,0] op_sel_hi:[1,1,1]
	v_pk_fma_f32 v[108:109], v[50:51], v[84:85], v[108:109] op_sel:[0,0,0] op_sel_hi:[1,0,1]
	v_pk_fma_f32 v[110:111], v[50:51], v[84:85], v[110:111] op_sel:[0,1,0] op_sel_hi:[1,1,1]
	v_pk_mul_f32 v[48:49], v[96:97], v[86:87] op_sel:[0,0] op_sel_hi:[1,0]
	v_pk_mul_f32 v[50:51], v[96:97], v[62:63] op_sel:[0,0] op_sel_hi:[1,0]
	v_pk_fma_f32 v[48:49], v[98:99], v[86:87], v[48:49] op_sel:[0,1,0] op_sel_hi:[1,1,1]
	v_pk_fma_f32 v[50:51], v[98:99], v[62:63], v[50:51] op_sel:[0,1,0] op_sel_hi:[1,1,1]
	v_pk_fma_f32 v[48:49], v[100:101], v[88:89], v[48:49] op_sel:[0,0,0] op_sel_hi:[1,0,1]
	v_pk_fma_f32 v[50:51], v[100:101], v[64:65], v[50:51] op_sel:[0,0,0] op_sel_hi:[1,0,1]
	v_pk_fma_f32 v[48:49], v[102:103], v[88:89], v[48:49] op_sel:[0,1,0] op_sel_hi:[1,1,1]
	v_pk_fma_f32 v[50:51], v[102:103], v[64:65], v[50:51] op_sel:[0,1,0] op_sel_hi:[1,1,1]
	v_pk_fma_f32 v[48:49], v[104:105], v[90:91], v[48:49] op_sel:[0,0,0] op_sel_hi:[1,0,1]
	v_pk_fma_f32 v[50:51], v[104:105], v[66:67], v[50:51] op_sel:[0,0,0] op_sel_hi:[1,0,1]
	v_pk_fma_f32 v[48:49], v[106:107], v[90:91], v[48:49] op_sel:[0,1,0] op_sel_hi:[1,1,1]
	v_pk_fma_f32 v[50:51], v[106:107], v[66:67], v[50:51] op_sel:[0,1,0] op_sel_hi:[1,1,1]
	v_pk_fma_f32 v[48:49], v[108:109], v[92:93], v[48:49] op_sel:[0,0,0] op_sel_hi:[1,0,1]
	v_pk_fma_f32 v[50:51], v[108:109], v[68:69], v[50:51] op_sel:[0,0,0] op_sel_hi:[1,0,1]
	v_pk_fma_f32 v[48:49], v[110:111], v[92:93], v[48:49] op_sel:[0,1,0] op_sel_hi:[1,1,1]
	v_pk_fma_f32 v[50:51], v[110:111], v[68:69], v[50:51] op_sel:[0,1,0] op_sel_hi:[1,1,1]
	s_waitcnt lgkmcnt(11)
	ds_read_b128 v[70:73], v44 offset:24832
	ds_read_b128 v[74:77], v44 offset:24848
	ds_read_b128 v[78:81], v44 offset:25344
	ds_read_b128 v[82:85], v44 offset:25360
	ds_read_b128 v[86:89], v44 offset:25600
	ds_read_b128 v[90:93], v44 offset:25616
	ds_read_b64 v[146:147], v46 offset:24576
	ds_read_b128 v[62:65], v44 offset:26624
	ds_read_b128 v[66:69], v44 offset:26640
	v_add_f32_dpp v48, v48, v48 quad_perm:[1,0,3,2] row_mask:0xf bank_mask:0xf bound_ctrl:1
	v_add_f32_dpp v49, v49, v49 quad_perm:[1,0,3,2] row_mask:0xf bank_mask:0xf bound_ctrl:1
	v_add_f32_dpp v50, v50, v50 quad_perm:[1,0,3,2] row_mask:0xf bank_mask:0xf bound_ctrl:1
	v_add_f32_dpp v51, v51, v51 quad_perm:[1,0,3,2] row_mask:0xf bank_mask:0xf bound_ctrl:1
	v_pk_fma_f32 v[96:97], v[192:193], v[168:169], v[96:97] op_sel:[0,0,0] op_sel_hi:[1,0,1]
	v_pk_fma_f32 v[98:99], v[192:193], v[168:169], v[98:99] op_sel:[0,1,0] op_sel_hi:[1,1,1]
	v_pk_fma_f32 v[100:101], v[192:193], v[170:171], v[100:101] op_sel:[0,0,0] op_sel_hi:[1,0,1]
	v_add_f32_dpp v48, v48, v48 quad_perm:[2,3,0,1] row_mask:0xf bank_mask:0xf bound_ctrl:1
	v_add_f32_dpp v49, v49, v49 quad_perm:[2,3,0,1] row_mask:0xf bank_mask:0xf bound_ctrl:1
	v_add_f32_dpp v50, v50, v50 quad_perm:[2,3,0,1] row_mask:0xf bank_mask:0xf bound_ctrl:1
	v_add_f32_dpp v51, v51, v51 quad_perm:[2,3,0,1] row_mask:0xf bank_mask:0xf bound_ctrl:1
	v_pk_fma_f32 v[102:103], v[192:193], v[170:171], v[102:103] op_sel:[0,1,0] op_sel_hi:[1,1,1]
; #define LAS __attribute__((address_space(3)))
; __device__ __forceinline__ float red8(float x) { x += dpp_mov<0xB1>(x); x += dpp_mov<0x4E>(x); x += dpp_mov<0x141>(x); return x; }
; __device__ __forceinline__ void scan_phase(const KP& P, LAS unsigned char* lds, const int tid, const int bx, const int G) {
;     ...
;             for (int s = 0; s < 32; ++s) {
;                 const LAS float* p = cb + s * 384;
;                 const f32x4 w0 = *(const LAS f32x4*)(p), w1 = *(const LAS f32x4*)(p + 4);
;                 const f32x4 k0 = *(const LAS f32x4*)(p + 64), k1 = *(const LAS f32x4*)(p + 68);
;                 const f32x4 a0 = *(const LAS f32x4*)(p + 128), a1 = *(const LAS f32x4*)(p + 132);
;                 const f32x4 b0 = *(const LAS f32x4*)(p + 192), b1 = *(const LAS f32x4*)(p + 196);
;                 const f32x4 r0 = *(const LAS f32x4*)(p + 256), r1 = *(const LAS f32x4*)(p + 260);
;                 const float vv = buf[(c & 1) * 12288 + s * 384 + 320 + v];
;                 f32x2 sa2 = S[0] * (f32x2){a0.x, a0.y};
;                 sa2 += S[1] * (f32x2){a0.z, a0.w}; sa2 += S[2] * (f32x2){a1.x, a1.y}; sa2 += S[3] * (f32x2){a1.z, a1.w};
;                 const float sa = red8(sa2.x + sa2.y);
;                 const f32x2 sav = {sa, sa}, vv2 = {vv, vv};
;                 S[0] = S[0] * (f32x2){w0.x, w0.y} + sav * (f32x2){b0.x, b0.y} + vv2 * (f32x2){k0.x, k0.y};
;                 S[1] = S[1] * (f32x2){w0.z, w0.w} + sav * (f32x2){b0.z, b0.w} + vv2 * (f32x2){k0.z, k0.w};
;                 S[2] = S[2] * (f32x2){w1.x, w1.y} + sav * (f32x2){b1.x, b1.y} + vv2 * (f32x2){k1.x, k1.y};
;                 S[3] = S[3] * (f32x2){w1.z, w1.w} + sav * (f32x2){b1.z, b1.w} + vv2 * (f32x2){k1.z, k1.w};
;                 f32x2 y2 = S[0] * (f32x2){r0.x, r0.y};
;                 y2 += S[1] * (f32x2){r0.z, r0.w}; y2 += S[2] * (f32x2){r1.x, r1.y}; y2 += S[3] * (f32x2){r1.z, r1.w};
;                 const float y = red8(y2.x + y2.y);
;                 if (kc == 0) ybuf[s * 64 + v] = y;
;             }
	v_pk_fma_f32 v[104:105], v[192:193], v[172:173], v[104:105] op_sel:[0,0,0] op_sel_hi:[1,0,1]
	v_pk_fma_f32 v[106:107], v[192:193], v[172:173], v[106:107] op_sel:[0,1,0] op_sel_hi:[1,1,1]
	v_add_f32_dpp v50, v50, v50 row_half_mirror row_mask:0xf bank_mask:0xf bound_ctrl:1
	v_add_f32_dpp v51, v51, v51 row_half_mirror row_mask:0xf bank_mask:0xf bound_ctrl:1
	v_pk_fma_f32 v[108:109], v[192:193], v[174:175], v[108:109] op_sel:[0,0,0] op_sel_hi:[1,0,1]
	s_mov_b64 exec, s[86:87]
	ds_write_b64 v45, v[48:49] offset:6656
	s_mov_b64 exec, s[0:1]
	v_pk_fma_f32 v[110:111], v[192:193], v[174:175], v[110:111] op_sel:[0,1,0] op_sel_hi:[1,1,1]
	v_pk_fma_f32 v[96:97], v[50:51], v[176:177], v[96:97] op_sel:[0,0,0] op_sel_hi:[1,0,1]
	v_pk_fma_f32 v[98:99], v[50:51], v[176:177], v[98:99] op_sel:[0,1,0] op_sel_hi:[1,1,1]
	v_pk_fma_f32 v[100:101], v[50:51], v[178:179], v[100:101] op_sel:[0,0,0] op_sel_hi:[1,0,1]
	v_pk_fma_f32 v[102:103], v[50:51], v[178:179], v[102:103] op_sel:[0,1,0] op_sel_hi:[1,1,1]
	v_pk_fma_f32 v[104:105], v[50:51], v[180:181], v[104:105] op_sel:[0,0,0] op_sel_hi:[1,0,1]
	v_pk_fma_f32 v[106:107], v[50:51], v[180:181], v[106:107] op_sel:[0,1,0] op_sel_hi:[1,1,1]
	v_pk_fma_f32 v[108:109], v[50:51], v[182:183], v[108:109] op_sel:[0,0,0] op_sel_hi:[1,0,1]
	v_pk_fma_f32 v[110:111], v[50:51], v[182:183], v[110:111] op_sel:[0,1,0] op_sel_hi:[1,1,1]
	v_pk_mul_f32 v[48:49], v[96:97], v[184:185] op_sel:[0,0] op_sel_hi:[1,0]
	v_pk_mul_f32 v[50:51], v[96:97], v[148:149] op_sel:[0,0] op_sel_hi:[1,0]
	v_pk_fma_f32 v[48:49], v[98:99], v[184:185], v[48:49] op_sel:[0,1,0] op_sel_hi:[1,1,1]
	v_pk_fma_f32 v[50:51], v[98:99], v[148:149], v[50:51] op_sel:[0,1,0] op_sel_hi:[1,1,1]
	v_pk_fma_f32 v[48:49], v[100:101], v[186:187], v[48:49] op_sel:[0,0,0] op_sel_hi:[1,0,1]
	v_pk_fma_f32 v[50:51], v[100:101], v[150:151], v[50:51] op_sel:[0,0,0] op_sel_hi:[1,0,1]
	v_pk_fma_f32 v[48:49], v[102:103], v[186:187], v[48:49] op_sel:[0,1,0] op_sel_hi:[1,1,1]
	v_pk_fma_f32 v[50:51], v[102:103], v[150:151], v[50:51] op_sel:[0,1,0] op_sel_hi:[1,1,1]
	v_pk_fma_f32 v[48:49], v[104:105], v[188:189], v[48:49] op_sel:[0,0,0] op_sel_hi:[1,0,1]
	v_pk_fma_f32 v[50:51], v[104:105], v[152:153], v[50:51] op_sel:[0,0,0] op_sel_hi:[1,0,1]
	v_pk_fma_f32 v[48:49], v[106:107], v[188:189], v[48:49] op_sel:[0,1,0] op_sel_hi:[1,1,1]
	v_pk_fma_f32 v[50:51], v[106:107], v[152:153], v[50:51] op_sel:[0,1,0] op_sel_hi:[1,1,1]
	v_pk_fma_f32 v[48:49], v[108:109], v[190:191], v[48:49] op_sel:[0,0,0] op_sel_hi:[1,0,1]
	v_pk_fma_f32 v[50:51], v[108:109], v[154:155], v[50:51] op_sel:[0,0,0] op_sel_hi:[1,0,1]
	v_pk_fma_f32 v[48:49], v[110:111], v[190:191], v[48:49] op_sel:[0,1,0] op_sel_hi:[1,1,1]
	v_pk_fma_f32 v[50:51], v[110:111], v[154:155], v[50:51] op_sel:[0,1,0] op_sel_hi:[1,1,1]
	s_waitcnt lgkmcnt(11)
	ds_read_b128 v[168:171], v44 offset:26368
	ds_read_b128 v[172:175], v44 offset:26384
	ds_read_b128 v[176:179], v44 offset:26880
	ds_read_b128 v[180:183], v44 offset:26896
	ds_read_b128 v[184:187], v44 offset:27136
	ds_read_b128 v[188:191], v44 offset:27152
	ds_read_b64 v[192:193], v46 offset:26112
	ds_read_b128 v[148:151], v44 offset:28160
	ds_read_b128 v[152:155], v44 offset:28176
	v_add_f32_dpp v48, v48, v48 quad_perm:[1,0,3,2] row_mask:0xf bank_mask:0xf bound_ctrl:1
	v_add_f32_dpp v49, v49, v49 quad_perm:[1,0,3,2] row_mask:0xf bank_mask:0xf bound_ctrl:1
	v_add_f32_dpp v50, v50, v50 quad_perm:[1,0,3,2] row_mask:0xf bank_mask:0xf bound_ctrl:1
	v_add_f32_dpp v51, v51, v51 quad_perm:[1,0,3,2] row_mask:0xf bank_mask:0xf bound_ctrl:1
	v_pk_fma_f32 v[96:97], v[144:145], v[120:121], v[96:97] op_sel:[0,0,0] op_sel_hi:[1,0,1]
	v_pk_fma_f32 v[98:99], v[144:145], v[120:121], v[98:99] op_sel:[0,1,0] op_sel_hi:[1,1,1]
	v_pk_fma_f32 v[100:101], v[144:145], v[122:123], v[100:101] op_sel:[0,0,0] op_sel_hi:[1,0,1]
	v_add_f32_dpp v48, v48, v48 quad_perm:[2,3,0,1] row_mask:0xf bank_mask:0xf bound_ctrl:1
	v_add_f32_dpp v49, v49, v49 quad_perm:[2,3,0,1] row_mask:0xf bank_mask:0xf bound_ctrl:1
	v_add_f32_dpp v50, v50, v50 quad_perm:[2,3,0,1] row_mask:0xf bank_mask:0xf bound_ctrl:1
	v_add_f32_dpp v51, v51, v51 quad_perm:[2,3,0,1] row_mask:0xf bank_mask:0xf bound_ctrl:1
	v_pk_fma_f32 v[102:103], v[144:145], v[122:123], v[102:103] op_sel:[0,1,0] op_sel_hi:[1,1,1]
	v_pk_fma_f32 v[104:105], v[144:145], v[124:125], v[104:105] op_sel:[0,0,0] op_sel_hi:[1,0,1]
	v_pk_fma_f32 v[106:107], v[144:145], v[124:125], v[106:107] op_sel:[0,1,0] op_sel_hi:[1,1,1]
	v_add_f32_dpp v50, v50, v50 row_half_mirror row_mask:0xf bank_mask:0xf bound_ctrl:1
	v_add_f32_dpp v51, v51, v51 row_half_mirror row_mask:0xf bank_mask:0xf bound_ctrl:1
	v_pk_fma_f32 v[108:109], v[144:145], v[126:127], v[108:109] op_sel:[0,0,0] op_sel_hi:[1,0,1]
	s_mov_b64 exec, s[86:87]
	ds_write_b64 v45, v[48:49] offset:7168
	s_mov_b64 exec, s[0:1]
	v_pk_fma_f32 v[110:111], v[144:145], v[126:127], v[110:111] op_sel:[0,1,0] op_sel_hi:[1,1,1]
	v_pk_fma_f32 v[96:97], v[50:51], v[128:129], v[96:97] op_sel:[0,0,0] op_sel_hi:[1,0,1]
	v_pk_fma_f32 v[98:99], v[50:51], v[128:129], v[98:99] op_sel:[0,1,0] op_sel_hi:[1,1,1]
	v_pk_fma_f32 v[100:101], v[50:51], v[130:131], v[100:101] op_sel:[0,0,0] op_sel_hi:[1,0,1]
	v_pk_fma_f32 v[102:103], v[50:51], v[130:131], v[102:103] op_sel:[0,1,0] op_sel_hi:[1,1,1]
	v_pk_fma_f32 v[104:105], v[50:51], v[132:133], v[104:105] op_sel:[0,0,0] op_sel_hi:[1,0,1]
	v_pk_fma_f32 v[106:107], v[50:51], v[132:133], v[106:107] op_sel:[0,1,0] op_sel_hi:[1,1,1]
	v_pk_fma_f32 v[108:109], v[50:51], v[134:135], v[108:109] op_sel:[0,0,0] op_sel_hi:[1,0,1]
	v_pk_fma_f32 v[110:111], v[50:51], v[134:135], v[110:111] op_sel:[0,1,0] op_sel_hi:[1,1,1]
	v_pk_mul_f32 v[48:49], v[96:97], v[136:137] op_sel:[0,0] op_sel_hi:[1,0]
	v_pk_mul_f32 v[50:51], v[96:97], v[156:157] op_sel:[0,0] op_sel_hi:[1,0]
	v_pk_fma_f32 v[48:49], v[98:99], v[136:137], v[48:49] op_sel:[0,1,0] op_sel_hi:[1,1,1]
	v_pk_fma_f32 v[50:51], v[98:99], v[156:157], v[50:51] op_sel:[0,1,0] op_sel_hi:[1,1,1]
	v_pk_fma_f32 v[48:49], v[100:101], v[138:139], v[48:49] op_sel:[0,0,0] op_sel_hi:[1,0,1]
	v_pk_fma_f32 v[50:51], v[100:101], v[158:159], v[50:51] op_sel:[0,0,0] op_sel_hi:[1,0,1]
	v_pk_fma_f32 v[48:49], v[102:103], v[138:139], v[48:49] op_sel:[0,1,0] op_sel_hi:[1,1,1]
	v_pk_fma_f32 v[50:51], v[102:103], v[158:159], v[50:51] op_sel:[0,1,0] op_sel_hi:[1,1,1]
	v_pk_fma_f32 v[48:49], v[104:105], v[140:141], v[48:49] op_sel:[0,0,0] op_sel_hi:[1,0,1]
	v_pk_fma_f32 v[50:51], v[104:105], v[160:161], v[50:51] op_sel:[0,0,0] op_sel_hi:[1,0,1]
	v_pk_fma_f32 v[48:49], v[106:107], v[140:141], v[48:49] op_sel:[0,1,0] op_sel_hi:[1,1,1]
	v_pk_fma_f32 v[50:51], v[106:107], v[160:161], v[50:51] op_sel:[0,1,0] op_sel_hi:[1,1,1]
	v_pk_fma_f32 v[48:49], v[108:109], v[142:143], v[48:49] op_sel:[0,0,0] op_sel_hi:[1,0,1]
	v_pk_fma_f32 v[50:51], v[108:109], v[162:163], v[50:51] op_sel:[0,0,0] op_sel_hi:[1,0,1]
	v_pk_fma_f32 v[48:49], v[110:111], v[142:143], v[48:49] op_sel:[0,1,0] op_sel_hi:[1,1,1]
	v_pk_fma_f32 v[50:51], v[110:111], v[162:163], v[50:51] op_sel:[0,1,0] op_sel_hi:[1,1,1]
	s_waitcnt lgkmcnt(11)
; #define LAS __attribute__((address_space(3)))
; __device__ __forceinline__ float red8(float x) { x += dpp_mov<0xB1>(x); x += dpp_mov<0x4E>(x); x += dpp_mov<0x141>(x); return x; }
; __device__ __forceinline__ void scan_phase(const KP& P, LAS unsigned char* lds, const int tid, const int bx, const int G) {
;     ...
;             for (int s = 0; s < 32; ++s) {
;                 const LAS float* p = cb + s * 384;
;                 const f32x4 w0 = *(const LAS f32x4*)(p), w1 = *(const LAS f32x4*)(p + 4);
;                 const f32x4 k0 = *(const LAS f32x4*)(p + 64), k1 = *(const LAS f32x4*)(p + 68);
;                 const f32x4 a0 = *(const LAS f32x4*)(p + 128), a1 = *(const LAS f32x4*)(p + 132);
;                 const f32x4 b0 = *(const LAS f32x4*)(p + 192), b1 = *(const LAS f32x4*)(p + 196);
;                 const f32x4 r0 = *(const LAS f32x4*)(p + 256), r1 = *(const LAS f32x4*)(p + 260);
;                 const float vv = buf[(c & 1) * 12288 + s * 384 + 320 + v];
;                 f32x2 sa2 = S[0] * (f32x2){a0.x, a0.y};
;                 sa2 += S[1] * (f32x2){a0.z, a0.w}; sa2 += S[2] * (f32x2){a1.x, a1.y}; sa2 += S[3] * (f32x2){a1.z, a1.w};
;                 const float sa = red8(sa2.x + sa2.y);
;                 const f32x2 sav = {sa, sa}, vv2 = {vv, vv};
;                 S[0] = S[0] * (f32x2){w0.x, w0.y} + sav * (f32x2){b0.x, b0.y} + vv2 * (f32x2){k0.x, k0.y};
;                 S[1] = S[1] * (f32x2){w0.z, w0.w} + sav * (f32x2){b0.z, b0.w} + vv2 * (f32x2){k0.z, k0.w};
;                 S[2] = S[2] * (f32x2){w1.x, w1.y} + sav * (f32x2){b1.x, b1.y} + vv2 * (f32x2){k1.x, k1.y};
;                 S[3] = S[3] * (f32x2){w1.z, w1.w} + sav * (f32x2){b1.z, b1.w} + vv2 * (f32x2){k1.z, k1.w};
;                 f32x2 y2 = S[0] * (f32x2){r0.x, r0.y};
;                 y2 += S[1] * (f32x2){r0.z, r0.w}; y2 += S[2] * (f32x2){r1.x, r1.y}; y2 += S[3] * (f32x2){r1.z, r1.w};
;                 const float y = red8(y2.x + y2.y);
;                 if (kc == 0) ybuf[s * 64 + v] = y;
;             }
	ds_read_b128 v[120:123], v44 offset:27904
	ds_read_b128 v[124:127], v44 offset:27920
	ds_read_b128 v[128:131], v44 offset:28416
	ds_read_b128 v[132:135], v44 offset:28432
	ds_read_b128 v[136:139], v44 offset:28672
	ds_read_b128 v[140:143], v44 offset:28688
	ds_read_b64 v[144:145], v46 offset:27648
	ds_read_b128 v[156:159], v44 offset:29696
	ds_read_b128 v[160:163], v44 offset:29712
	v_add_f32_dpp v48, v48, v48 quad_perm:[1,0,3,2] row_mask:0xf bank_mask:0xf bound_ctrl:1
	v_add_f32_dpp v49, v49, v49 quad_perm:[1,0,3,2] row_mask:0xf bank_mask:0xf bound_ctrl:1
	v_add_f32_dpp v50, v50, v50 quad_perm:[1,0,3,2] row_mask:0xf bank_mask:0xf bound_ctrl:1
	v_add_f32_dpp v51, v51, v51 quad_perm:[1,0,3,2] row_mask:0xf bank_mask:0xf bound_ctrl:1
	v_pk_fma_f32 v[96:97], v[146:147], v[70:71], v[96:97] op_sel:[0,0,0] op_sel_hi:[1,0,1]
	v_pk_fma_f32 v[98:99], v[146:147], v[70:71], v[98:99] op_sel:[0,1,0] op_sel_hi:[1,1,1]
	v_pk_fma_f32 v[100:101], v[146:147], v[72:73], v[100:101] op_sel:[0,0,0] op_sel_hi:[1,0,1]
	v_add_f32_dpp v48, v48, v48 quad_perm:[2,3,0,1] row_mask:0xf bank_mask:0xf bound_ctrl:1
	v_add_f32_dpp v49, v49, v49 quad_perm:[2,3,0,1] row_mask:0xf bank_mask:0xf bound_ctrl:1
	v_add_f32_dpp v50, v50, v50 quad_perm:[2,3,0,1] row_mask:0xf bank_mask:0xf bound_ctrl:1
	v_add_f32_dpp v51, v51, v51 quad_perm:[2,3,0,1] row_mask:0xf bank_mask:0xf bound_ctrl:1
	v_pk_fma_f32 v[102:103], v[146:147], v[72:73], v[102:103] op_sel:[0,1,0] op_sel_hi:[1,1,1]
	v_pk_fma_f32 v[104:105], v[146:147], v[74:75], v[104:105] op_sel:[0,0,0] op_sel_hi:[1,0,1]
	v_pk_fma_f32 v[106:107], v[146:147], v[74:75], v[106:107] op_sel:[0,1,0] op_sel_hi:[1,1,1]
	v_add_f32_dpp v50, v50, v50 row_half_mirror row_mask:0xf bank_mask:0xf bound_ctrl:1
	v_add_f32_dpp v51, v51, v51 row_half_mirror row_mask:0xf bank_mask:0xf bound_ctrl:1
	v_pk_fma_f32 v[108:109], v[146:147], v[76:77], v[108:109] op_sel:[0,0,0] op_sel_hi:[1,0,1]
	s_mov_b64 exec, s[86:87]
	ds_write_b64 v45, v[48:49] offset:7680
	s_mov_b64 exec, s[0:1]
	v_pk_fma_f32 v[110:111], v[146:147], v[76:77], v[110:111] op_sel:[0,1,0] op_sel_hi:[1,1,1]
	v_pk_fma_f32 v[96:97], v[50:51], v[78:79], v[96:97] op_sel:[0,0,0] op_sel_hi:[1,0,1]
	v_pk_fma_f32 v[98:99], v[50:51], v[78:79], v[98:99] op_sel:[0,1,0] op_sel_hi:[1,1,1]
	v_pk_fma_f32 v[100:101], v[50:51], v[80:81], v[100:101] op_sel:[0,0,0] op_sel_hi:[1,0,1]
	v_pk_fma_f32 v[102:103], v[50:51], v[80:81], v[102:103] op_sel:[0,1,0] op_sel_hi:[1,1,1]
	v_pk_fma_f32 v[104:105], v[50:51], v[82:83], v[104:105] op_sel:[0,0,0] op_sel_hi:[1,0,1]
	v_pk_fma_f32 v[106:107], v[50:51], v[82:83], v[106:107] op_sel:[0,1,0] op_sel_hi:[1,1,1]
	v_pk_fma_f32 v[108:109], v[50:51], v[84:85], v[108:109] op_sel:[0,0,0] op_sel_hi:[1,0,1]
	v_pk_fma_f32 v[110:111], v[50:51], v[84:85], v[110:111] op_sel:[0,1,0] op_sel_hi:[1,1,1]
	v_pk_mul_f32 v[48:49], v[96:97], v[86:87] op_sel:[0,0] op_sel_hi:[1,0]
	v_pk_mul_f32 v[50:51], v[96:97], v[62:63] op_sel:[0,0] op_sel_hi:[1,0]
	v_pk_fma_f32 v[48:49], v[98:99], v[86:87], v[48:49] op_sel:[0,1,0] op_sel_hi:[1,1,1]
	v_pk_fma_f32 v[50:51], v[98:99], v[62:63], v[50:51] op_sel:[0,1,0] op_sel_hi:[1,1,1]
	v_pk_fma_f32 v[48:49], v[100:101], v[88:89], v[48:49] op_sel:[0,0,0] op_sel_hi:[1,0,1]
	v_pk_fma_f32 v[50:51], v[100:101], v[64:65], v[50:51] op_sel:[0,0,0] op_sel_hi:[1,0,1]
	v_pk_fma_f32 v[48:49], v[102:103], v[88:89], v[48:49] op_sel:[0,1,0] op_sel_hi:[1,1,1]
	v_pk_fma_f32 v[50:51], v[102:103], v[64:65], v[50:51] op_sel:[0,1,0] op_sel_hi:[1,1,1]
	v_pk_fma_f32 v[48:49], v[104:105], v[90:91], v[48:49] op_sel:[0,0,0] op_sel_hi:[1,0,1]
	v_pk_fma_f32 v[50:51], v[104:105], v[66:67], v[50:51] op_sel:[0,0,0] op_sel_hi:[1,0,1]
	v_pk_fma_f32 v[48:49], v[106:107], v[90:91], v[48:49] op_sel:[0,1,0] op_sel_hi:[1,1,1]
	v_pk_fma_f32 v[50:51], v[106:107], v[66:67], v[50:51] op_sel:[0,1,0] op_sel_hi:[1,1,1]
	v_pk_fma_f32 v[48:49], v[108:109], v[92:93], v[48:49] op_sel:[0,0,0] op_sel_hi:[1,0,1]
	v_pk_fma_f32 v[50:51], v[108:109], v[68:69], v[50:51] op_sel:[0,0,0] op_sel_hi:[1,0,1]
	v_pk_fma_f32 v[48:49], v[110:111], v[92:93], v[48:49] op_sel:[0,1,0] op_sel_hi:[1,1,1]
	v_pk_fma_f32 v[50:51], v[110:111], v[68:69], v[50:51] op_sel:[0,1,0] op_sel_hi:[1,1,1]
	s_waitcnt lgkmcnt(11)
	ds_read_b128 v[70:73], v44 offset:29440
	ds_read_b128 v[74:77], v44 offset:29456
	ds_read_b128 v[78:81], v44 offset:29952
	ds_read_b128 v[82:85], v44 offset:29968
	ds_read_b128 v[86:89], v44 offset:30208
	ds_read_b128 v[90:93], v44 offset:30224
	ds_read_b64 v[146:147], v46 offset:29184
	ds_read_b128 v[62:65], v44 offset:31232
	ds_read_b128 v[66:69], v44 offset:31248
	v_add_f32_dpp v48, v48, v48 quad_perm:[1,0,3,2] row_mask:0xf bank_mask:0xf bound_ctrl:1
	v_add_f32_dpp v49, v49, v49 quad_perm:[1,0,3,2] row_mask:0xf bank_mask:0xf bound_ctrl:1
	v_add_f32_dpp v50, v50, v50 quad_perm:[1,0,3,2] row_mask:0xf bank_mask:0xf bound_ctrl:1
	v_add_f32_dpp v51, v51, v51 quad_perm:[1,0,3,2] row_mask:0xf bank_mask:0xf bound_ctrl:1
	v_pk_fma_f32 v[96:97], v[192:193], v[168:169], v[96:97] op_sel:[0,0,0] op_sel_hi:[1,0,1]
	v_pk_fma_f32 v[98:99], v[192:193], v[168:169], v[98:99] op_sel:[0,1,0] op_sel_hi:[1,1,1]
	v_pk_fma_f32 v[100:101], v[192:193], v[170:171], v[100:101] op_sel:[0,0,0] op_sel_hi:[1,0,1]
	v_add_f32_dpp v48, v48, v48 quad_perm:[2,3,0,1] row_mask:0xf bank_mask:0xf bound_ctrl:1
	v_add_f32_dpp v49, v49, v49 quad_perm:[2,3,0,1] row_mask:0xf bank_mask:0xf bound_ctrl:1
	v_add_f32_dpp v50, v50, v50 quad_perm:[2,3,0,1] row_mask:0xf bank_mask:0xf bound_ctrl:1
	v_add_f32_dpp v51, v51, v51 quad_perm:[2,3,0,1] row_mask:0xf bank_mask:0xf bound_ctrl:1
	v_pk_fma_f32 v[102:103], v[192:193], v[170:171], v[102:103] op_sel:[0,1,0] op_sel_hi:[1,1,1]
; #define LAS __attribute__((address_space(3)))
; __device__ __forceinline__ float red8(float x) { x += dpp_mov<0xB1>(x); x += dpp_mov<0x4E>(x); x += dpp_mov<0x141>(x); return x; }
; __device__ __forceinline__ void scan_phase(const KP& P, LAS unsigned char* lds, const int tid, const int bx, const int G) {
;     ...
;             for (int s = 0; s < 32; ++s) {
;                 const LAS float* p = cb + s * 384;
;                 const f32x4 w0 = *(const LAS f32x4*)(p), w1 = *(const LAS f32x4*)(p + 4);
;                 const f32x4 k0 = *(const LAS f32x4*)(p + 64), k1 = *(const LAS f32x4*)(p + 68);
;                 const f32x4 a0 = *(const LAS f32x4*)(p + 128), a1 = *(const LAS f32x4*)(p + 132);
;                 const f32x4 b0 = *(const LAS f32x4*)(p + 192), b1 = *(const LAS f32x4*)(p + 196);
;                 const f32x4 r0 = *(const LAS f32x4*)(p + 256), r1 = *(const LAS f32x4*)(p + 260);
;                 const float vv = buf[(c & 1) * 12288 + s * 384 + 320 + v];
;                 f32x2 sa2 = S[0] * (f32x2){a0.x, a0.y};
;                 sa2 += S[1] * (f32x2){a0.z, a0.w}; sa2 += S[2] * (f32x2){a1.x, a1.y}; sa2 += S[3] * (f32x2){a1.z, a1.w};
;                 const float sa = red8(sa2.x + sa2.y);
;                 const f32x2 sav = {sa, sa}, vv2 = {vv, vv};
;                 S[0] = S[0] * (f32x2){w0.x, w0.y} + sav * (f32x2){b0.x, b0.y} + vv2 * (f32x2){k0.x, k0.y};
;                 S[1] = S[1] * (f32x2){w0.z, w0.w} + sav * (f32x2){b0.z, b0.w} + vv2 * (f32x2){k0.z, k0.w};
;                 S[2] = S[2] * (f32x2){w1.x, w1.y} + sav * (f32x2){b1.x, b1.y} + vv2 * (f32x2){k1.x, k1.y};
;                 S[3] = S[3] * (f32x2){w1.z, w1.w} + sav * (f32x2){b1.z, b1.w} + vv2 * (f32x2){k1.z, k1.w};
;                 f32x2 y2 = S[0] * (f32x2){r0.x, r0.y};
;                 y2 += S[1] * (f32x2){r0.z, r0.w}; y2 += S[2] * (f32x2){r1.x, r1.y}; y2 += S[3] * (f32x2){r1.z, r1.w};
;                 const float y = red8(y2.x + y2.y);
;                 if (kc == 0) ybuf[s * 64 + v] = y;
;             }
	v_pk_fma_f32 v[104:105], v[192:193], v[172:173], v[104:105] op_sel:[0,0,0] op_sel_hi:[1,0,1]
	v_pk_fma_f32 v[106:107], v[192:193], v[172:173], v[106:107] op_sel:[0,1,0] op_sel_hi:[1,1,1]
	v_add_f32_dpp v50, v50, v50 row_half_mirror row_mask:0xf bank_mask:0xf bound_ctrl:1
	v_add_f32_dpp v51, v51, v51 row_half_mirror row_mask:0xf bank_mask:0xf bound_ctrl:1
	v_pk_fma_f32 v[108:109], v[192:193], v[174:175], v[108:109] op_sel:[0,0,0] op_sel_hi:[1,0,1]
	s_mov_b64 exec, s[86:87]
	ds_write_b64 v45, v[48:49] offset:8192
	s_mov_b64 exec, s[0:1]
	v_pk_fma_f32 v[110:111], v[192:193], v[174:175], v[110:111] op_sel:[0,1,0] op_sel_hi:[1,1,1]
	v_pk_fma_f32 v[96:97], v[50:51], v[176:177], v[96:97] op_sel:[0,0,0] op_sel_hi:[1,0,1]
	v_pk_fma_f32 v[98:99], v[50:51], v[176:177], v[98:99] op_sel:[0,1,0] op_sel_hi:[1,1,1]
	v_pk_fma_f32 v[100:101], v[50:51], v[178:179], v[100:101] op_sel:[0,0,0] op_sel_hi:[1,0,1]
	v_pk_fma_f32 v[102:103], v[50:51], v[178:179], v[102:103] op_sel:[0,1,0] op_sel_hi:[1,1,1]
	v_pk_fma_f32 v[104:105], v[50:51], v[180:181], v[104:105] op_sel:[0,0,0] op_sel_hi:[1,0,1]
	v_pk_fma_f32 v[106:107], v[50:51], v[180:181], v[106:107] op_sel:[0,1,0] op_sel_hi:[1,1,1]
	v_pk_fma_f32 v[108:109], v[50:51], v[182:183], v[108:109] op_sel:[0,0,0] op_sel_hi:[1,0,1]
	v_pk_fma_f32 v[110:111], v[50:51], v[182:183], v[110:111] op_sel:[0,1,0] op_sel_hi:[1,1,1]
	v_pk_mul_f32 v[48:49], v[96:97], v[184:185] op_sel:[0,0] op_sel_hi:[1,0]
	v_pk_mul_f32 v[50:51], v[96:97], v[148:149] op_sel:[0,0] op_sel_hi:[1,0]
	v_pk_fma_f32 v[48:49], v[98:99], v[184:185], v[48:49] op_sel:[0,1,0] op_sel_hi:[1,1,1]
	v_pk_fma_f32 v[50:51], v[98:99], v[148:149], v[50:51] op_sel:[0,1,0] op_sel_hi:[1,1,1]
	v_pk_fma_f32 v[48:49], v[100:101], v[186:187], v[48:49] op_sel:[0,0,0] op_sel_hi:[1,0,1]
	v_pk_fma_f32 v[50:51], v[100:101], v[150:151], v[50:51] op_sel:[0,0,0] op_sel_hi:[1,0,1]
	v_pk_fma_f32 v[48:49], v[102:103], v[186:187], v[48:49] op_sel:[0,1,0] op_sel_hi:[1,1,1]
	v_pk_fma_f32 v[50:51], v[102:103], v[150:151], v[50:51] op_sel:[0,1,0] op_sel_hi:[1,1,1]
	v_pk_fma_f32 v[48:49], v[104:105], v[188:189], v[48:49] op_sel:[0,0,0] op_sel_hi:[1,0,1]
	v_pk_fma_f32 v[50:51], v[104:105], v[152:153], v[50:51] op_sel:[0,0,0] op_sel_hi:[1,0,1]
	v_pk_fma_f32 v[48:49], v[106:107], v[188:189], v[48:49] op_sel:[0,1,0] op_sel_hi:[1,1,1]
	v_pk_fma_f32 v[50:51], v[106:107], v[152:153], v[50:51] op_sel:[0,1,0] op_sel_hi:[1,1,1]
	v_pk_fma_f32 v[48:49], v[108:109], v[190:191], v[48:49] op_sel:[0,0,0] op_sel_hi:[1,0,1]
	v_pk_fma_f32 v[50:51], v[108:109], v[154:155], v[50:51] op_sel:[0,0,0] op_sel_hi:[1,0,1]
	v_pk_fma_f32 v[48:49], v[110:111], v[190:191], v[48:49] op_sel:[0,1,0] op_sel_hi:[1,1,1]
	v_pk_fma_f32 v[50:51], v[110:111], v[154:155], v[50:51] op_sel:[0,1,0] op_sel_hi:[1,1,1]
	s_waitcnt lgkmcnt(11)
	ds_read_b128 v[168:171], v44 offset:30976
	ds_read_b128 v[172:175], v44 offset:30992
	ds_read_b128 v[176:179], v44 offset:31488
	ds_read_b128 v[180:183], v44 offset:31504
	ds_read_b128 v[184:187], v44 offset:31744
	ds_read_b128 v[188:191], v44 offset:31760
	ds_read_b64 v[192:193], v46 offset:30720
	ds_read_b128 v[148:151], v44 offset:32768
	ds_read_b128 v[152:155], v44 offset:32784
	v_add_f32_dpp v48, v48, v48 quad_perm:[1,0,3,2] row_mask:0xf bank_mask:0xf bound_ctrl:1
	v_add_f32_dpp v49, v49, v49 quad_perm:[1,0,3,2] row_mask:0xf bank_mask:0xf bound_ctrl:1
	v_add_f32_dpp v50, v50, v50 quad_perm:[1,0,3,2] row_mask:0xf bank_mask:0xf bound_ctrl:1
	v_add_f32_dpp v51, v51, v51 quad_perm:[1,0,3,2] row_mask:0xf bank_mask:0xf bound_ctrl:1
	v_pk_fma_f32 v[96:97], v[144:145], v[120:121], v[96:97] op_sel:[0,0,0] op_sel_hi:[1,0,1]
	v_pk_fma_f32 v[98:99], v[144:145], v[120:121], v[98:99] op_sel:[0,1,0] op_sel_hi:[1,1,1]
	v_pk_fma_f32 v[100:101], v[144:145], v[122:123], v[100:101] op_sel:[0,0,0] op_sel_hi:[1,0,1]
	v_add_f32_dpp v48, v48, v48 quad_perm:[2,3,0,1] row_mask:0xf bank_mask:0xf bound_ctrl:1
	v_add_f32_dpp v49, v49, v49 quad_perm:[2,3,0,1] row_mask:0xf bank_mask:0xf bound_ctrl:1
	v_add_f32_dpp v50, v50, v50 quad_perm:[2,3,0,1] row_mask:0xf bank_mask:0xf bound_ctrl:1
	v_add_f32_dpp v51, v51, v51 quad_perm:[2,3,0,1] row_mask:0xf bank_mask:0xf bound_ctrl:1
	v_pk_fma_f32 v[102:103], v[144:145], v[122:123], v[102:103] op_sel:[0,1,0] op_sel_hi:[1,1,1]
	v_pk_fma_f32 v[104:105], v[144:145], v[124:125], v[104:105] op_sel:[0,0,0] op_sel_hi:[1,0,1]
	v_pk_fma_f32 v[106:107], v[144:145], v[124:125], v[106:107] op_sel:[0,1,0] op_sel_hi:[1,1,1]
	v_add_f32_dpp v50, v50, v50 row_half_mirror row_mask:0xf bank_mask:0xf bound_ctrl:1
	v_add_f32_dpp v51, v51, v51 row_half_mirror row_mask:0xf bank_mask:0xf bound_ctrl:1
	v_pk_fma_f32 v[108:109], v[144:145], v[126:127], v[108:109] op_sel:[0,0,0] op_sel_hi:[1,0,1]
	s_mov_b64 exec, s[86:87]
	ds_write_b64 v45, v[48:49] offset:8704
	s_mov_b64 exec, s[0:1]
	v_pk_fma_f32 v[110:111], v[144:145], v[126:127], v[110:111] op_sel:[0,1,0] op_sel_hi:[1,1,1]
	v_pk_fma_f32 v[96:97], v[50:51], v[128:129], v[96:97] op_sel:[0,0,0] op_sel_hi:[1,0,1]
	v_pk_fma_f32 v[98:99], v[50:51], v[128:129], v[98:99] op_sel:[0,1,0] op_sel_hi:[1,1,1]
	v_pk_fma_f32 v[100:101], v[50:51], v[130:131], v[100:101] op_sel:[0,0,0] op_sel_hi:[1,0,1]
	v_pk_fma_f32 v[102:103], v[50:51], v[130:131], v[102:103] op_sel:[0,1,0] op_sel_hi:[1,1,1]
	v_pk_fma_f32 v[104:105], v[50:51], v[132:133], v[104:105] op_sel:[0,0,0] op_sel_hi:[1,0,1]
	v_pk_fma_f32 v[106:107], v[50:51], v[132:133], v[106:107] op_sel:[0,1,0] op_sel_hi:[1,1,1]
	v_pk_fma_f32 v[108:109], v[50:51], v[134:135], v[108:109] op_sel:[0,0,0] op_sel_hi:[1,0,1]
	v_pk_fma_f32 v[110:111], v[50:51], v[134:135], v[110:111] op_sel:[0,1,0] op_sel_hi:[1,1,1]
	v_pk_mul_f32 v[48:49], v[96:97], v[136:137] op_sel:[0,0] op_sel_hi:[1,0]
	v_pk_mul_f32 v[50:51], v[96:97], v[156:157] op_sel:[0,0] op_sel_hi:[1,0]
	v_pk_fma_f32 v[48:49], v[98:99], v[136:137], v[48:49] op_sel:[0,1,0] op_sel_hi:[1,1,1]
	v_pk_fma_f32 v[50:51], v[98:99], v[156:157], v[50:51] op_sel:[0,1,0] op_sel_hi:[1,1,1]
	v_pk_fma_f32 v[48:49], v[100:101], v[138:139], v[48:49] op_sel:[0,0,0] op_sel_hi:[1,0,1]
	v_pk_fma_f32 v[50:51], v[100:101], v[158:159], v[50:51] op_sel:[0,0,0] op_sel_hi:[1,0,1]
	v_pk_fma_f32 v[48:49], v[102:103], v[138:139], v[48:49] op_sel:[0,1,0] op_sel_hi:[1,1,1]
	v_pk_fma_f32 v[50:51], v[102:103], v[158:159], v[50:51] op_sel:[0,1,0] op_sel_hi:[1,1,1]
	v_pk_fma_f32 v[48:49], v[104:105], v[140:141], v[48:49] op_sel:[0,0,0] op_sel_hi:[1,0,1]
	v_pk_fma_f32 v[50:51], v[104:105], v[160:161], v[50:51] op_sel:[0,0,0] op_sel_hi:[1,0,1]
	v_pk_fma_f32 v[48:49], v[106:107], v[140:141], v[48:49] op_sel:[0,1,0] op_sel_hi:[1,1,1]
	v_pk_fma_f32 v[50:51], v[106:107], v[160:161], v[50:51] op_sel:[0,1,0] op_sel_hi:[1,1,1]
	v_pk_fma_f32 v[48:49], v[108:109], v[142:143], v[48:49] op_sel:[0,0,0] op_sel_hi:[1,0,1]
	v_pk_fma_f32 v[50:51], v[108:109], v[162:163], v[50:51] op_sel:[0,0,0] op_sel_hi:[1,0,1]
	v_pk_fma_f32 v[48:49], v[110:111], v[142:143], v[48:49] op_sel:[0,1,0] op_sel_hi:[1,1,1]
	v_pk_fma_f32 v[50:51], v[110:111], v[162:163], v[50:51] op_sel:[0,1,0] op_sel_hi:[1,1,1]
	s_waitcnt lgkmcnt(11)
; #define LAS __attribute__((address_space(3)))
; __device__ __forceinline__ float red8(float x) { x += dpp_mov<0xB1>(x); x += dpp_mov<0x4E>(x); x += dpp_mov<0x141>(x); return x; }
; __device__ __forceinline__ void scan_phase(const KP& P, LAS unsigned char* lds, const int tid, const int bx, const int G) {
;     ...
;             for (int s = 0; s < 32; ++s) {
;                 const LAS float* p = cb + s * 384;
;                 const f32x4 w0 = *(const LAS f32x4*)(p), w1 = *(const LAS f32x4*)(p + 4);
;                 const f32x4 k0 = *(const LAS f32x4*)(p + 64), k1 = *(const LAS f32x4*)(p + 68);
;                 const f32x4 a0 = *(const LAS f32x4*)(p + 128), a1 = *(const LAS f32x4*)(p + 132);
;                 const f32x4 b0 = *(const LAS f32x4*)(p + 192), b1 = *(const LAS f32x4*)(p + 196);
;                 const f32x4 r0 = *(const LAS f32x4*)(p + 256), r1 = *(const LAS f32x4*)(p + 260);
;                 const float vv = buf[(c & 1) * 12288 + s * 384 + 320 + v];
;                 f32x2 sa2 = S[0] * (f32x2){a0.x, a0.y};
;                 sa2 += S[1] * (f32x2){a0.z, a0.w}; sa2 += S[2] * (f32x2){a1.x, a1.y}; sa2 += S[3] * (f32x2){a1.z, a1.w};
;                 const float sa = red8(sa2.x + sa2.y);
;                 const f32x2 sav = {sa, sa}, vv2 = {vv, vv};
;                 S[0] = S[0] * (f32x2){w0.x, w0.y} + sav * (f32x2){b0.x, b0.y} + vv2 * (f32x2){k0.x, k0.y};
;                 S[1] = S[1] * (f32x2){w0.z, w0.w} + sav * (f32x2){b0.z, b0.w} + vv2 * (f32x2){k0.z, k0.w};
;                 S[2] = S[2] * (f32x2){w1.x, w1.y} + sav * (f32x2){b1.x, b1.y} + vv2 * (f32x2){k1.x, k1.y};
;                 S[3] = S[3] * (f32x2){w1.z, w1.w} + sav * (f32x2){b1.z, b1.w} + vv2 * (f32x2){k1.z, k1.w};
;                 f32x2 y2 = S[0] * (f32x2){r0.x, r0.y};
;                 y2 += S[1] * (f32x2){r0.z, r0.w}; y2 += S[2] * (f32x2){r1.x, r1.y}; y2 += S[3] * (f32x2){r1.z, r1.w};
;                 const float y = red8(y2.x + y2.y);
;                 if (kc == 0) ybuf[s * 64 + v] = y;
;             }
	ds_read_b128 v[120:123], v44 offset:32512
	ds_read_b128 v[124:127], v44 offset:32528
	ds_read_b128 v[128:131], v44 offset:33024
	ds_read_b128 v[132:135], v44 offset:33040
	ds_read_b128 v[136:139], v44 offset:33280
	ds_read_b128 v[140:143], v44 offset:33296
	ds_read_b64 v[144:145], v46 offset:32256
	ds_read_b128 v[156:159], v44 offset:34304
	ds_read_b128 v[160:163], v44 offset:34320
	v_add_f32_dpp v48, v48, v48 quad_perm:[1,0,3,2] row_mask:0xf bank_mask:0xf bound_ctrl:1
	v_add_f32_dpp v49, v49, v49 quad_perm:[1,0,3,2] row_mask:0xf bank_mask:0xf bound_ctrl:1
	v_add_f32_dpp v50, v50, v50 quad_perm:[1,0,3,2] row_mask:0xf bank_mask:0xf bound_ctrl:1
	v_add_f32_dpp v51, v51, v51 quad_perm:[1,0,3,2] row_mask:0xf bank_mask:0xf bound_ctrl:1
	v_pk_fma_f32 v[96:97], v[146:147], v[70:71], v[96:97] op_sel:[0,0,0] op_sel_hi:[1,0,1]
	v_pk_fma_f32 v[98:99], v[146:147], v[70:71], v[98:99] op_sel:[0,1,0] op_sel_hi:[1,1,1]
	v_pk_fma_f32 v[100:101], v[146:147], v[72:73], v[100:101] op_sel:[0,0,0] op_sel_hi:[1,0,1]
	v_add_f32_dpp v48, v48, v48 quad_perm:[2,3,0,1] row_mask:0xf bank_mask:0xf bound_ctrl:1
	v_add_f32_dpp v49, v49, v49 quad_perm:[2,3,0,1] row_mask:0xf bank_mask:0xf bound_ctrl:1
	v_add_f32_dpp v50, v50, v50 quad_perm:[2,3,0,1] row_mask:0xf bank_mask:0xf bound_ctrl:1
	v_add_f32_dpp v51, v51, v51 quad_perm:[2,3,0,1] row_mask:0xf bank_mask:0xf bound_ctrl:1
	v_pk_fma_f32 v[102:103], v[146:147], v[72:73], v[102:103] op_sel:[0,1,0] op_sel_hi:[1,1,1]
	v_pk_fma_f32 v[104:105], v[146:147], v[74:75], v[104:105] op_sel:[0,0,0] op_sel_hi:[1,0,1]
	v_pk_fma_f32 v[106:107], v[146:147], v[74:75], v[106:107] op_sel:[0,1,0] op_sel_hi:[1,1,1]
	v_add_f32_dpp v50, v50, v50 row_half_mirror row_mask:0xf bank_mask:0xf bound_ctrl:1
	v_add_f32_dpp v51, v51, v51 row_half_mirror row_mask:0xf bank_mask:0xf bound_ctrl:1
	v_pk_fma_f32 v[108:109], v[146:147], v[76:77], v[108:109] op_sel:[0,0,0] op_sel_hi:[1,0,1]
	s_mov_b64 exec, s[86:87]
	ds_write_b64 v45, v[48:49] offset:9216
	s_mov_b64 exec, s[0:1]
	v_pk_fma_f32 v[110:111], v[146:147], v[76:77], v[110:111] op_sel:[0,1,0] op_sel_hi:[1,1,1]
	v_pk_fma_f32 v[96:97], v[50:51], v[78:79], v[96:97] op_sel:[0,0,0] op_sel_hi:[1,0,1]
	v_pk_fma_f32 v[98:99], v[50:51], v[78:79], v[98:99] op_sel:[0,1,0] op_sel_hi:[1,1,1]
	v_pk_fma_f32 v[100:101], v[50:51], v[80:81], v[100:101] op_sel:[0,0,0] op_sel_hi:[1,0,1]
	v_pk_fma_f32 v[102:103], v[50:51], v[80:81], v[102:103] op_sel:[0,1,0] op_sel_hi:[1,1,1]
	v_pk_fma_f32 v[104:105], v[50:51], v[82:83], v[104:105] op_sel:[0,0,0] op_sel_hi:[1,0,1]
	v_pk_fma_f32 v[106:107], v[50:51], v[82:83], v[106:107] op_sel:[0,1,0] op_sel_hi:[1,1,1]
	v_pk_fma_f32 v[108:109], v[50:51], v[84:85], v[108:109] op_sel:[0,0,0] op_sel_hi:[1,0,1]
	v_pk_fma_f32 v[110:111], v[50:51], v[84:85], v[110:111] op_sel:[0,1,0] op_sel_hi:[1,1,1]
	v_pk_mul_f32 v[48:49], v[96:97], v[86:87] op_sel:[0,0] op_sel_hi:[1,0]
	v_pk_mul_f32 v[50:51], v[96:97], v[62:63] op_sel:[0,0] op_sel_hi:[1,0]
	v_pk_fma_f32 v[48:49], v[98:99], v[86:87], v[48:49] op_sel:[0,1,0] op_sel_hi:[1,1,1]
	v_pk_fma_f32 v[50:51], v[98:99], v[62:63], v[50:51] op_sel:[0,1,0] op_sel_hi:[1,1,1]
	v_pk_fma_f32 v[48:49], v[100:101], v[88:89], v[48:49] op_sel:[0,0,0] op_sel_hi:[1,0,1]
	v_pk_fma_f32 v[50:51], v[100:101], v[64:65], v[50:51] op_sel:[0,0,0] op_sel_hi:[1,0,1]
	v_pk_fma_f32 v[48:49], v[102:103], v[88:89], v[48:49] op_sel:[0,1,0] op_sel_hi:[1,1,1]
	v_pk_fma_f32 v[50:51], v[102:103], v[64:65], v[50:51] op_sel:[0,1,0] op_sel_hi:[1,1,1]
	v_pk_fma_f32 v[48:49], v[104:105], v[90:91], v[48:49] op_sel:[0,0,0] op_sel_hi:[1,0,1]
	v_pk_fma_f32 v[50:51], v[104:105], v[66:67], v[50:51] op_sel:[0,0,0] op_sel_hi:[1,0,1]
	v_pk_fma_f32 v[48:49], v[106:107], v[90:91], v[48:49] op_sel:[0,1,0] op_sel_hi:[1,1,1]
	v_pk_fma_f32 v[50:51], v[106:107], v[66:67], v[50:51] op_sel:[0,1,0] op_sel_hi:[1,1,1]
	v_pk_fma_f32 v[48:49], v[108:109], v[92:93], v[48:49] op_sel:[0,0,0] op_sel_hi:[1,0,1]
	v_pk_fma_f32 v[50:51], v[108:109], v[68:69], v[50:51] op_sel:[0,0,0] op_sel_hi:[1,0,1]
	v_pk_fma_f32 v[48:49], v[110:111], v[92:93], v[48:49] op_sel:[0,1,0] op_sel_hi:[1,1,1]
	v_pk_fma_f32 v[50:51], v[110:111], v[68:69], v[50:51] op_sel:[0,1,0] op_sel_hi:[1,1,1]
	s_waitcnt lgkmcnt(11)
	ds_read_b128 v[70:73], v44 offset:34048
	ds_read_b128 v[74:77], v44 offset:34064
	ds_read_b128 v[78:81], v44 offset:34560
	ds_read_b128 v[82:85], v44 offset:34576
	ds_read_b128 v[86:89], v44 offset:34816
	ds_read_b128 v[90:93], v44 offset:34832
	ds_read_b64 v[146:147], v46 offset:33792
	ds_read_b128 v[62:65], v44 offset:35840
	ds_read_b128 v[66:69], v44 offset:35856
	v_add_f32_dpp v48, v48, v48 quad_perm:[1,0,3,2] row_mask:0xf bank_mask:0xf bound_ctrl:1
	v_add_f32_dpp v49, v49, v49 quad_perm:[1,0,3,2] row_mask:0xf bank_mask:0xf bound_ctrl:1
	v_add_f32_dpp v50, v50, v50 quad_perm:[1,0,3,2] row_mask:0xf bank_mask:0xf bound_ctrl:1
	v_add_f32_dpp v51, v51, v51 quad_perm:[1,0,3,2] row_mask:0xf bank_mask:0xf bound_ctrl:1
	v_pk_fma_f32 v[96:97], v[192:193], v[168:169], v[96:97] op_sel:[0,0,0] op_sel_hi:[1,0,1]
	v_pk_fma_f32 v[98:99], v[192:193], v[168:169], v[98:99] op_sel:[0,1,0] op_sel_hi:[1,1,1]
	v_pk_fma_f32 v[100:101], v[192:193], v[170:171], v[100:101] op_sel:[0,0,0] op_sel_hi:[1,0,1]
	v_add_f32_dpp v48, v48, v48 quad_perm:[2,3,0,1] row_mask:0xf bank_mask:0xf bound_ctrl:1
	v_add_f32_dpp v49, v49, v49 quad_perm:[2,3,0,1] row_mask:0xf bank_mask:0xf bound_ctrl:1
	v_add_f32_dpp v50, v50, v50 quad_perm:[2,3,0,1] row_mask:0xf bank_mask:0xf bound_ctrl:1
	v_add_f32_dpp v51, v51, v51 quad_perm:[2,3,0,1] row_mask:0xf bank_mask:0xf bound_ctrl:1
	v_pk_fma_f32 v[102:103], v[192:193], v[170:171], v[102:103] op_sel:[0,1,0] op_sel_hi:[1,1,1]
; #define LAS __attribute__((address_space(3)))
; __device__ __forceinline__ float red8(float x) { x += dpp_mov<0xB1>(x); x += dpp_mov<0x4E>(x); x += dpp_mov<0x141>(x); return x; }
; __device__ __forceinline__ void scan_phase(const KP& P, LAS unsigned char* lds, const int tid, const int bx, const int G) {
;     ...
;             for (int s = 0; s < 32; ++s) {
;                 const LAS float* p = cb + s * 384;
;                 const f32x4 w0 = *(const LAS f32x4*)(p), w1 = *(const LAS f32x4*)(p + 4);
;                 const f32x4 k0 = *(const LAS f32x4*)(p + 64), k1 = *(const LAS f32x4*)(p + 68);
;                 const f32x4 a0 = *(const LAS f32x4*)(p + 128), a1 = *(const LAS f32x4*)(p + 132);
;                 const f32x4 b0 = *(const LAS f32x4*)(p + 192), b1 = *(const LAS f32x4*)(p + 196);
;                 const f32x4 r0 = *(const LAS f32x4*)(p + 256), r1 = *(const LAS f32x4*)(p + 260);
;                 const float vv = buf[(c & 1) * 12288 + s * 384 + 320 + v];
;                 f32x2 sa2 = S[0] * (f32x2){a0.x, a0.y};
;                 sa2 += S[1] * (f32x2){a0.z, a0.w}; sa2 += S[2] * (f32x2){a1.x, a1.y}; sa2 += S[3] * (f32x2){a1.z, a1.w};
;                 const float sa = red8(sa2.x + sa2.y);
;                 const f32x2 sav = {sa, sa}, vv2 = {vv, vv};
;                 S[0] = S[0] * (f32x2){w0.x, w0.y} + sav * (f32x2){b0.x, b0.y} + vv2 * (f32x2){k0.x, k0.y};
;                 S[1] = S[1] * (f32x2){w0.z, w0.w} + sav * (f32x2){b0.z, b0.w} + vv2 * (f32x2){k0.z, k0.w};
;                 S[2] = S[2] * (f32x2){w1.x, w1.y} + sav * (f32x2){b1.x, b1.y} + vv2 * (f32x2){k1.x, k1.y};
;                 S[3] = S[3] * (f32x2){w1.z, w1.w} + sav * (f32x2){b1.z, b1.w} + vv2 * (f32x2){k1.z, k1.w};
;                 f32x2 y2 = S[0] * (f32x2){r0.x, r0.y};
;                 y2 += S[1] * (f32x2){r0.z, r0.w}; y2 += S[2] * (f32x2){r1.x, r1.y}; y2 += S[3] * (f32x2){r1.z, r1.w};
;                 const float y = red8(y2.x + y2.y);
;                 if (kc == 0) ybuf[s * 64 + v] = y;
;             }
	v_pk_fma_f32 v[104:105], v[192:193], v[172:173], v[104:105] op_sel:[0,0,0] op_sel_hi:[1,0,1]
	v_pk_fma_f32 v[106:107], v[192:193], v[172:173], v[106:107] op_sel:[0,1,0] op_sel_hi:[1,1,1]
	v_add_f32_dpp v50, v50, v50 row_half_mirror row_mask:0xf bank_mask:0xf bound_ctrl:1
	v_add_f32_dpp v51, v51, v51 row_half_mirror row_mask:0xf bank_mask:0xf bound_ctrl:1
	v_pk_fma_f32 v[108:109], v[192:193], v[174:175], v[108:109] op_sel:[0,0,0] op_sel_hi:[1,0,1]
	s_mov_b64 exec, s[86:87]
	ds_write_b64 v45, v[48:49] offset:9728
	s_mov_b64 exec, s[0:1]
	v_pk_fma_f32 v[110:111], v[192:193], v[174:175], v[110:111] op_sel:[0,1,0] op_sel_hi:[1,1,1]
	v_pk_fma_f32 v[96:97], v[50:51], v[176:177], v[96:97] op_sel:[0,0,0] op_sel_hi:[1,0,1]
	v_pk_fma_f32 v[98:99], v[50:51], v[176:177], v[98:99] op_sel:[0,1,0] op_sel_hi:[1,1,1]
	v_pk_fma_f32 v[100:101], v[50:51], v[178:179], v[100:101] op_sel:[0,0,0] op_sel_hi:[1,0,1]
	v_pk_fma_f32 v[102:103], v[50:51], v[178:179], v[102:103] op_sel:[0,1,0] op_sel_hi:[1,1,1]
	v_pk_fma_f32 v[104:105], v[50:51], v[180:181], v[104:105] op_sel:[0,0,0] op_sel_hi:[1,0,1]
	v_pk_fma_f32 v[106:107], v[50:51], v[180:181], v[106:107] op_sel:[0,1,0] op_sel_hi:[1,1,1]
	v_pk_fma_f32 v[108:109], v[50:51], v[182:183], v[108:109] op_sel:[0,0,0] op_sel_hi:[1,0,1]
	v_pk_fma_f32 v[110:111], v[50:51], v[182:183], v[110:111] op_sel:[0,1,0] op_sel_hi:[1,1,1]
	v_pk_mul_f32 v[48:49], v[96:97], v[184:185] op_sel:[0,0] op_sel_hi:[1,0]
	v_pk_mul_f32 v[50:51], v[96:97], v[148:149] op_sel:[0,0] op_sel_hi:[1,0]
	v_pk_fma_f32 v[48:49], v[98:99], v[184:185], v[48:49] op_sel:[0,1,0] op_sel_hi:[1,1,1]
	v_pk_fma_f32 v[50:51], v[98:99], v[148:149], v[50:51] op_sel:[0,1,0] op_sel_hi:[1,1,1]
	v_pk_fma_f32 v[48:49], v[100:101], v[186:187], v[48:49] op_sel:[0,0,0] op_sel_hi:[1,0,1]
	v_pk_fma_f32 v[50:51], v[100:101], v[150:151], v[50:51] op_sel:[0,0,0] op_sel_hi:[1,0,1]
	v_pk_fma_f32 v[48:49], v[102:103], v[186:187], v[48:49] op_sel:[0,1,0] op_sel_hi:[1,1,1]
	v_pk_fma_f32 v[50:51], v[102:103], v[150:151], v[50:51] op_sel:[0,1,0] op_sel_hi:[1,1,1]
	v_pk_fma_f32 v[48:49], v[104:105], v[188:189], v[48:49] op_sel:[0,0,0] op_sel_hi:[1,0,1]
	v_pk_fma_f32 v[50:51], v[104:105], v[152:153], v[50:51] op_sel:[0,0,0] op_sel_hi:[1,0,1]
	v_pk_fma_f32 v[48:49], v[106:107], v[188:189], v[48:49] op_sel:[0,1,0] op_sel_hi:[1,1,1]
	v_pk_fma_f32 v[50:51], v[106:107], v[152:153], v[50:51] op_sel:[0,1,0] op_sel_hi:[1,1,1]
	v_pk_fma_f32 v[48:49], v[108:109], v[190:191], v[48:49] op_sel:[0,0,0] op_sel_hi:[1,0,1]
	v_pk_fma_f32 v[50:51], v[108:109], v[154:155], v[50:51] op_sel:[0,0,0] op_sel_hi:[1,0,1]
	v_pk_fma_f32 v[48:49], v[110:111], v[190:191], v[48:49] op_sel:[0,1,0] op_sel_hi:[1,1,1]
	v_pk_fma_f32 v[50:51], v[110:111], v[154:155], v[50:51] op_sel:[0,1,0] op_sel_hi:[1,1,1]
	s_waitcnt lgkmcnt(11)
	ds_read_b128 v[168:171], v44 offset:35584
	ds_read_b128 v[172:175], v44 offset:35600
	ds_read_b128 v[176:179], v44 offset:36096
	ds_read_b128 v[180:183], v44 offset:36112
	ds_read_b128 v[184:187], v44 offset:36352
	ds_read_b128 v[188:191], v44 offset:36368
	ds_read_b64 v[192:193], v46 offset:35328
	ds_read_b128 v[148:151], v44 offset:37376
	ds_read_b128 v[152:155], v44 offset:37392
	v_add_f32_dpp v48, v48, v48 quad_perm:[1,0,3,2] row_mask:0xf bank_mask:0xf bound_ctrl:1
	v_add_f32_dpp v49, v49, v49 quad_perm:[1,0,3,2] row_mask:0xf bank_mask:0xf bound_ctrl:1
	v_add_f32_dpp v50, v50, v50 quad_perm:[1,0,3,2] row_mask:0xf bank_mask:0xf bound_ctrl:1
	v_add_f32_dpp v51, v51, v51 quad_perm:[1,0,3,2] row_mask:0xf bank_mask:0xf bound_ctrl:1
	v_pk_fma_f32 v[96:97], v[144:145], v[120:121], v[96:97] op_sel:[0,0,0] op_sel_hi:[1,0,1]
	v_pk_fma_f32 v[98:99], v[144:145], v[120:121], v[98:99] op_sel:[0,1,0] op_sel_hi:[1,1,1]
	v_pk_fma_f32 v[100:101], v[144:145], v[122:123], v[100:101] op_sel:[0,0,0] op_sel_hi:[1,0,1]
	v_add_f32_dpp v48, v48, v48 quad_perm:[2,3,0,1] row_mask:0xf bank_mask:0xf bound_ctrl:1
	v_add_f32_dpp v49, v49, v49 quad_perm:[2,3,0,1] row_mask:0xf bank_mask:0xf bound_ctrl:1
	v_add_f32_dpp v50, v50, v50 quad_perm:[2,3,0,1] row_mask:0xf bank_mask:0xf bound_ctrl:1
	v_add_f32_dpp v51, v51, v51 quad_perm:[2,3,0,1] row_mask:0xf bank_mask:0xf bound_ctrl:1
	v_pk_fma_f32 v[102:103], v[144:145], v[122:123], v[102:103] op_sel:[0,1,0] op_sel_hi:[1,1,1]
	v_pk_fma_f32 v[104:105], v[144:145], v[124:125], v[104:105] op_sel:[0,0,0] op_sel_hi:[1,0,1]
	v_pk_fma_f32 v[106:107], v[144:145], v[124:125], v[106:107] op_sel:[0,1,0] op_sel_hi:[1,1,1]
	v_add_f32_dpp v50, v50, v50 row_half_mirror row_mask:0xf bank_mask:0xf bound_ctrl:1
	v_add_f32_dpp v51, v51, v51 row_half_mirror row_mask:0xf bank_mask:0xf bound_ctrl:1
	v_pk_fma_f32 v[108:109], v[144:145], v[126:127], v[108:109] op_sel:[0,0,0] op_sel_hi:[1,0,1]
	s_mov_b64 exec, s[86:87]
	ds_write_b64 v45, v[48:49] offset:10240
	s_mov_b64 exec, s[0:1]
	v_pk_fma_f32 v[110:111], v[144:145], v[126:127], v[110:111] op_sel:[0,1,0] op_sel_hi:[1,1,1]
	v_pk_fma_f32 v[96:97], v[50:51], v[128:129], v[96:97] op_sel:[0,0,0] op_sel_hi:[1,0,1]
	v_pk_fma_f32 v[98:99], v[50:51], v[128:129], v[98:99] op_sel:[0,1,0] op_sel_hi:[1,1,1]
	v_pk_fma_f32 v[100:101], v[50:51], v[130:131], v[100:101] op_sel:[0,0,0] op_sel_hi:[1,0,1]
	v_pk_fma_f32 v[102:103], v[50:51], v[130:131], v[102:103] op_sel:[0,1,0] op_sel_hi:[1,1,1]
	v_pk_fma_f32 v[104:105], v[50:51], v[132:133], v[104:105] op_sel:[0,0,0] op_sel_hi:[1,0,1]
	v_pk_fma_f32 v[106:107], v[50:51], v[132:133], v[106:107] op_sel:[0,1,0] op_sel_hi:[1,1,1]
	v_pk_fma_f32 v[108:109], v[50:51], v[134:135], v[108:109] op_sel:[0,0,0] op_sel_hi:[1,0,1]
	v_pk_fma_f32 v[110:111], v[50:51], v[134:135], v[110:111] op_sel:[0,1,0] op_sel_hi:[1,1,1]
	v_pk_mul_f32 v[48:49], v[96:97], v[136:137] op_sel:[0,0] op_sel_hi:[1,0]
	v_pk_mul_f32 v[50:51], v[96:97], v[156:157] op_sel:[0,0] op_sel_hi:[1,0]
	v_pk_fma_f32 v[48:49], v[98:99], v[136:137], v[48:49] op_sel:[0,1,0] op_sel_hi:[1,1,1]
	v_pk_fma_f32 v[50:51], v[98:99], v[156:157], v[50:51] op_sel:[0,1,0] op_sel_hi:[1,1,1]
	v_pk_fma_f32 v[48:49], v[100:101], v[138:139], v[48:49] op_sel:[0,0,0] op_sel_hi:[1,0,1]
	v_pk_fma_f32 v[50:51], v[100:101], v[158:159], v[50:51] op_sel:[0,0,0] op_sel_hi:[1,0,1]
	v_pk_fma_f32 v[48:49], v[102:103], v[138:139], v[48:49] op_sel:[0,1,0] op_sel_hi:[1,1,1]
	v_pk_fma_f32 v[50:51], v[102:103], v[158:159], v[50:51] op_sel:[0,1,0] op_sel_hi:[1,1,1]
	v_pk_fma_f32 v[48:49], v[104:105], v[140:141], v[48:49] op_sel:[0,0,0] op_sel_hi:[1,0,1]
	v_pk_fma_f32 v[50:51], v[104:105], v[160:161], v[50:51] op_sel:[0,0,0] op_sel_hi:[1,0,1]
	v_pk_fma_f32 v[48:49], v[106:107], v[140:141], v[48:49] op_sel:[0,1,0] op_sel_hi:[1,1,1]
	v_pk_fma_f32 v[50:51], v[106:107], v[160:161], v[50:51] op_sel:[0,1,0] op_sel_hi:[1,1,1]
	v_pk_fma_f32 v[48:49], v[108:109], v[142:143], v[48:49] op_sel:[0,0,0] op_sel_hi:[1,0,1]
	v_pk_fma_f32 v[50:51], v[108:109], v[162:163], v[50:51] op_sel:[0,0,0] op_sel_hi:[1,0,1]
	v_pk_fma_f32 v[48:49], v[110:111], v[142:143], v[48:49] op_sel:[0,1,0] op_sel_hi:[1,1,1]
	v_pk_fma_f32 v[50:51], v[110:111], v[162:163], v[50:51] op_sel:[0,1,0] op_sel_hi:[1,1,1]
	s_waitcnt lgkmcnt(11)
; #define LAS __attribute__((address_space(3)))
; __device__ __forceinline__ float red8(float x) { x += dpp_mov<0xB1>(x); x += dpp_mov<0x4E>(x); x += dpp_mov<0x141>(x); return x; }
; __device__ __forceinline__ void scan_phase(const KP& P, LAS unsigned char* lds, const int tid, const int bx, const int G) {
;     ...
;             for (int s = 0; s < 32; ++s) {
;                 const LAS float* p = cb + s * 384;
;                 const f32x4 w0 = *(const LAS f32x4*)(p), w1 = *(const LAS f32x4*)(p + 4);
;                 const f32x4 k0 = *(const LAS f32x4*)(p + 64), k1 = *(const LAS f32x4*)(p + 68);
;                 const f32x4 a0 = *(const LAS f32x4*)(p + 128), a1 = *(const LAS f32x4*)(p + 132);
;                 const f32x4 b0 = *(const LAS f32x4*)(p + 192), b1 = *(const LAS f32x4*)(p + 196);
;                 const f32x4 r0 = *(const LAS f32x4*)(p + 256), r1 = *(const LAS f32x4*)(p + 260);
;                 const float vv = buf[(c & 1) * 12288 + s * 384 + 320 + v];
;                 f32x2 sa2 = S[0] * (f32x2){a0.x, a0.y};
;                 sa2 += S[1] * (f32x2){a0.z, a0.w}; sa2 += S[2] * (f32x2){a1.x, a1.y}; sa2 += S[3] * (f32x2){a1.z, a1.w};
;                 const float sa = red8(sa2.x + sa2.y);
;                 const f32x2 sav = {sa, sa}, vv2 = {vv, vv};
;                 S[0] = S[0] * (f32x2){w0.x, w0.y} + sav * (f32x2){b0.x, b0.y} + vv2 * (f32x2){k0.x, k0.y};
;                 S[1] = S[1] * (f32x2){w0.z, w0.w} + sav * (f32x2){b0.z, b0.w} + vv2 * (f32x2){k0.z, k0.w};
;                 S[2] = S[2] * (f32x2){w1.x, w1.y} + sav * (f32x2){b1.x, b1.y} + vv2 * (f32x2){k1.x, k1.y};
;                 S[3] = S[3] * (f32x2){w1.z, w1.w} + sav * (f32x2){b1.z, b1.w} + vv2 * (f32x2){k1.z, k1.w};
;                 f32x2 y2 = S[0] * (f32x2){r0.x, r0.y};
;                 y2 += S[1] * (f32x2){r0.z, r0.w}; y2 += S[2] * (f32x2){r1.x, r1.y}; y2 += S[3] * (f32x2){r1.z, r1.w};
;                 const float y = red8(y2.x + y2.y);
;                 if (kc == 0) ybuf[s * 64 + v] = y;
	ds_read_b128 v[120:123], v44 offset:37120
	ds_read_b128 v[124:127], v44 offset:37136
	ds_read_b128 v[128:131], v44 offset:37632
	ds_read_b128 v[132:135], v44 offset:37648
	ds_read_b128 v[136:139], v44 offset:37888
	ds_read_b128 v[140:143], v44 offset:37904
	ds_read_b64 v[144:145], v46 offset:36864
	ds_read_b128 v[156:159], v44 offset:38912
	ds_read_b128 v[160:163], v44 offset:38928
	v_add_f32_dpp v48, v48, v48 quad_perm:[1,0,3,2] row_mask:0xf bank_mask:0xf bound_ctrl:1
	v_add_f32_dpp v49, v49, v49 quad_perm:[1,0,3,2] row_mask:0xf bank_mask:0xf bound_ctrl:1
	v_add_f32_dpp v50, v50, v50 quad_perm:[1,0,3,2] row_mask:0xf bank_mask:0xf bound_ctrl:1
	v_add_f32_dpp v51, v51, v51 quad_perm:[1,0,3,2] row_mask:0xf bank_mask:0xf bound_ctrl:1
	v_pk_fma_f32 v[96:97], v[146:147], v[70:71], v[96:97] op_sel:[0,0,0] op_sel_hi:[1,0,1]
	v_pk_fma_f32 v[98:99], v[146:147], v[70:71], v[98:99] op_sel:[0,1,0] op_sel_hi:[1,1,1]
	v_pk_fma_f32 v[100:101], v[146:147], v[72:73], v[100:101] op_sel:[0,0,0] op_sel_hi:[1,0,1]
	v_add_f32_dpp v48, v48, v48 quad_perm:[2,3,0,1] row_mask:0xf bank_mask:0xf bound_ctrl:1
	v_add_f32_dpp v49, v49, v49 quad_perm:[2,3,0,1] row_mask:0xf bank_mask:0xf bound_ctrl:1
	v_add_f32_dpp v50, v50, v50 quad_perm:[2,3,0,1] row_mask:0xf bank_mask:0xf bound_ctrl:1
	v_add_f32_dpp v51, v51, v51 quad_perm:[2,3,0,1] row_mask:0xf bank_mask:0xf bound_ctrl:1
	v_pk_fma_f32 v[102:103], v[146:147], v[72:73], v[102:103] op_sel:[0,1,0] op_sel_hi:[1,1,1]
	v_pk_fma_f32 v[104:105], v[146:147], v[74:75], v[104:105] op_sel:[0,0,0] op_sel_hi:[1,0,1]
	v_pk_fma_f32 v[106:107], v[146:147], v[74:75], v[106:107] op_sel:[0,1,0] op_sel_hi:[1,1,1]
	v_add_f32_dpp v50, v50, v50 row_half_mirror row_mask:0xf bank_mask:0xf bound_ctrl:1
	v_add_f32_dpp v51, v51, v51 row_half_mirror row_mask:0xf bank_mask:0xf bound_ctrl:1
	v_pk_fma_f32 v[108:109], v[146:147], v[76:77], v[108:109] op_sel:[0,0,0] op_sel_hi:[1,0,1]
	s_mov_b64 exec, s[86:87]
	ds_write_b64 v45, v[48:49] offset:10752
	s_mov_b64 exec, s[0:1]
	v_pk_fma_f32 v[110:111], v[146:147], v[76:77], v[110:111] op_sel:[0,1,0] op_sel_hi:[1,1,1]
	v_pk_fma_f32 v[96:97], v[50:51], v[78:79], v[96:97] op_sel:[0,0,0] op_sel_hi:[1,0,1]
	v_pk_fma_f32 v[98:99], v[50:51], v[78:79], v[98:99] op_sel:[0,1,0] op_sel_hi:[1,1,1]
	v_pk_fma_f32 v[100:101], v[50:51], v[80:81], v[100:101] op_sel:[0,0,0] op_sel_hi:[1,0,1]
	v_pk_fma_f32 v[102:103], v[50:51], v[80:81], v[102:103] op_sel:[0,1,0] op_sel_hi:[1,1,1]
	v_pk_fma_f32 v[104:105], v[50:51], v[82:83], v[104:105] op_sel:[0,0,0] op_sel_hi:[1,0,1]
	v_pk_fma_f32 v[106:107], v[50:51], v[82:83], v[106:107] op_sel:[0,1,0] op_sel_hi:[1,1,1]
	v_pk_fma_f32 v[108:109], v[50:51], v[84:85], v[108:109] op_sel:[0,0,0] op_sel_hi:[1,0,1]
	v_pk_fma_f32 v[110:111], v[50:51], v[84:85], v[110:111] op_sel:[0,1,0] op_sel_hi:[1,1,1]
	v_pk_mul_f32 v[48:49], v[96:97], v[86:87] op_sel:[0,0] op_sel_hi:[1,0]
	v_pk_mul_f32 v[50:51], v[96:97], v[62:63] op_sel:[0,0] op_sel_hi:[1,0]
	v_pk_fma_f32 v[48:49], v[98:99], v[86:87], v[48:49] op_sel:[0,1,0] op_sel_hi:[1,1,1]
	v_pk_fma_f32 v[50:51], v[98:99], v[62:63], v[50:51] op_sel:[0,1,0] op_sel_hi:[1,1,1]
	v_pk_fma_f32 v[48:49], v[100:101], v[88:89], v[48:49] op_sel:[0,0,0] op_sel_hi:[1,0,1]
	v_pk_fma_f32 v[50:51], v[100:101], v[64:65], v[50:51] op_sel:[0,0,0] op_sel_hi:[1,0,1]
	v_pk_fma_f32 v[48:49], v[102:103], v[88:89], v[48:49] op_sel:[0,1,0] op_sel_hi:[1,1,1]
	v_pk_fma_f32 v[50:51], v[102:103], v[64:65], v[50:51] op_sel:[0,1,0] op_sel_hi:[1,1,1]
	v_pk_fma_f32 v[48:49], v[104:105], v[90:91], v[48:49] op_sel:[0,0,0] op_sel_hi:[1,0,1]
	v_pk_fma_f32 v[50:51], v[104:105], v[66:67], v[50:51] op_sel:[0,0,0] op_sel_hi:[1,0,1]
	v_pk_fma_f32 v[48:49], v[106:107], v[90:91], v[48:49] op_sel:[0,1,0] op_sel_hi:[1,1,1]
	v_pk_fma_f32 v[50:51], v[106:107], v[66:67], v[50:51] op_sel:[0,1,0] op_sel_hi:[1,1,1]
	v_pk_fma_f32 v[48:49], v[108:109], v[92:93], v[48:49] op_sel:[0,0,0] op_sel_hi:[1,0,1]
	v_pk_fma_f32 v[50:51], v[108:109], v[68:69], v[50:51] op_sel:[0,0,0] op_sel_hi:[1,0,1]
	v_pk_fma_f32 v[48:49], v[110:111], v[92:93], v[48:49] op_sel:[0,1,0] op_sel_hi:[1,1,1]
	v_pk_fma_f32 v[50:51], v[110:111], v[68:69], v[50:51] op_sel:[0,1,0] op_sel_hi:[1,1,1]
	s_waitcnt lgkmcnt(11)
	ds_read_b128 v[70:73], v44 offset:38656
	ds_read_b128 v[74:77], v44 offset:38672
	ds_read_b128 v[78:81], v44 offset:39168
	ds_read_b128 v[82:85], v44 offset:39184
	ds_read_b128 v[86:89], v44 offset:39424
	ds_read_b128 v[90:93], v44 offset:39440
	ds_read_b64 v[146:147], v46 offset:38400
	ds_read_b128 v[62:65], v44 offset:40448
	ds_read_b128 v[66:69], v44 offset:40464
	v_add_f32_dpp v48, v48, v48 quad_perm:[1,0,3,2] row_mask:0xf bank_mask:0xf bound_ctrl:1
	v_add_f32_dpp v49, v49, v49 quad_perm:[1,0,3,2] row_mask:0xf bank_mask:0xf bound_ctrl:1
	v_add_f32_dpp v50, v50, v50 quad_perm:[1,0,3,2] row_mask:0xf bank_mask:0xf bound_ctrl:1
	v_add_f32_dpp v51, v51, v51 quad_perm:[1,0,3,2] row_mask:0xf bank_mask:0xf bound_ctrl:1
	v_pk_fma_f32 v[96:97], v[192:193], v[168:169], v[96:97] op_sel:[0,0,0] op_sel_hi:[1,0,1]
	v_pk_fma_f32 v[98:99], v[192:193], v[168:169], v[98:99] op_sel:[0,1,0] op_sel_hi:[1,1,1]
	v_pk_fma_f32 v[100:101], v[192:193], v[170:171], v[100:101] op_sel:[0,0,0] op_sel_hi:[1,0,1]
	v_add_f32_dpp v48, v48, v48 quad_perm:[2,3,0,1] row_mask:0xf bank_mask:0xf bound_ctrl:1
	v_add_f32_dpp v49, v49, v49 quad_perm:[2,3,0,1] row_mask:0xf bank_mask:0xf bound_ctrl:1
	v_add_f32_dpp v50, v50, v50 quad_perm:[2,3,0,1] row_mask:0xf bank_mask:0xf bound_ctrl:1
	v_add_f32_dpp v51, v51, v51 quad_perm:[2,3,0,1] row_mask:0xf bank_mask:0xf bound_ctrl:1
	v_pk_fma_f32 v[102:103], v[192:193], v[170:171], v[102:103] op_sel:[0,1,0] op_sel_hi:[1,1,1]
; #define LAS __attribute__((address_space(3)))
; __device__ __forceinline__ float red8(float x) { x += dpp_mov<0xB1>(x); x += dpp_mov<0x4E>(x); x += dpp_mov<0x141>(x); return x; }
; __device__ __forceinline__ void scan_phase(const KP& P, LAS unsigned char* lds, const int tid, const int bx, const int G) {
;     ...
;             for (int s = 0; s < 32; ++s) {
;                 const LAS float* p = cb + s * 384;
;                 const f32x4 w0 = *(const LAS f32x4*)(p), w1 = *(const LAS f32x4*)(p + 4);
;                 const f32x4 k0 = *(const LAS f32x4*)(p + 64), k1 = *(const LAS f32x4*)(p + 68);
;                 const f32x4 a0 = *(const LAS f32x4*)(p + 128), a1 = *(const LAS f32x4*)(p + 132);
;                 const f32x4 b0 = *(const LAS f32x4*)(p + 192), b1 = *(const LAS f32x4*)(p + 196);
;                 const f32x4 r0 = *(const LAS f32x4*)(p + 256), r1 = *(const LAS f32x4*)(p + 260);
;                 const float vv = buf[(c & 1) * 12288 + s * 384 + 320 + v];
;                 f32x2 sa2 = S[0] * (f32x2){a0.x, a0.y};
;                 sa2 += S[1] * (f32x2){a0.z, a0.w}; sa2 += S[2] * (f32x2){a1.x, a1.y}; sa2 += S[3] * (f32x2){a1.z, a1.w};
;                 const float sa = red8(sa2.x + sa2.y);
;                 const f32x2 sav = {sa, sa}, vv2 = {vv, vv};
;                 S[0] = S[0] * (f32x2){w0.x, w0.y} + sav * (f32x2){b0.x, b0.y} + vv2 * (f32x2){k0.x, k0.y};
;                 S[1] = S[1] * (f32x2){w0.z, w0.w} + sav * (f32x2){b0.z, b0.w} + vv2 * (f32x2){k0.z, k0.w};
;                 S[2] = S[2] * (f32x2){w1.x, w1.y} + sav * (f32x2){b1.x, b1.y} + vv2 * (f32x2){k1.x, k1.y};
;                 S[3] = S[3] * (f32x2){w1.z, w1.w} + sav * (f32x2){b1.z, b1.w} + vv2 * (f32x2){k1.z, k1.w};
;                 f32x2 y2 = S[0] * (f32x2){r0.x, r0.y};
;                 y2 += S[1] * (f32x2){r0.z, r0.w}; y2 += S[2] * (f32x2){r1.x, r1.y}; y2 += S[3] * (f32x2){r1.z, r1.w};
;                 const float y = red8(y2.x + y2.y);
;                 if (kc == 0) ybuf[s * 64 + v] = y;
	v_pk_fma_f32 v[104:105], v[192:193], v[172:173], v[104:105] op_sel:[0,0,0] op_sel_hi:[1,0,1]
	v_pk_fma_f32 v[106:107], v[192:193], v[172:173], v[106:107] op_sel:[0,1,0] op_sel_hi:[1,1,1]
	v_add_f32_dpp v50, v50, v50 row_half_mirror row_mask:0xf bank_mask:0xf bound_ctrl:1
	v_add_f32_dpp v51, v51, v51 row_half_mirror row_mask:0xf bank_mask:0xf bound_ctrl:1
	v_pk_fma_f32 v[108:109], v[192:193], v[174:175], v[108:109] op_sel:[0,0,0] op_sel_hi:[1,0,1]
	s_mov_b64 exec, s[86:87]
	ds_write_b64 v45, v[48:49] offset:11264
	s_mov_b64 exec, s[0:1]
	v_pk_fma_f32 v[110:111], v[192:193], v[174:175], v[110:111] op_sel:[0,1,0] op_sel_hi:[1,1,1]
	v_pk_fma_f32 v[96:97], v[50:51], v[176:177], v[96:97] op_sel:[0,0,0] op_sel_hi:[1,0,1]
	v_pk_fma_f32 v[98:99], v[50:51], v[176:177], v[98:99] op_sel:[0,1,0] op_sel_hi:[1,1,1]
	v_pk_fma_f32 v[100:101], v[50:51], v[178:179], v[100:101] op_sel:[0,0,0] op_sel_hi:[1,0,1]
	v_pk_fma_f32 v[102:103], v[50:51], v[178:179], v[102:103] op_sel:[0,1,0] op_sel_hi:[1,1,1]
	v_pk_fma_f32 v[104:105], v[50:51], v[180:181], v[104:105] op_sel:[0,0,0] op_sel_hi:[1,0,1]
	v_pk_fma_f32 v[106:107], v[50:51], v[180:181], v[106:107] op_sel:[0,1,0] op_sel_hi:[1,1,1]
	v_pk_fma_f32 v[108:109], v[50:51], v[182:183], v[108:109] op_sel:[0,0,0] op_sel_hi:[1,0,1]
	v_pk_fma_f32 v[110:111], v[50:51], v[182:183], v[110:111] op_sel:[0,1,0] op_sel_hi:[1,1,1]
	v_pk_mul_f32 v[48:49], v[96:97], v[184:185] op_sel:[0,0] op_sel_hi:[1,0]
	v_pk_mul_f32 v[50:51], v[96:97], v[148:149] op_sel:[0,0] op_sel_hi:[1,0]
	v_pk_fma_f32 v[48:49], v[98:99], v[184:185], v[48:49] op_sel:[0,1,0] op_sel_hi:[1,1,1]
	v_pk_fma_f32 v[50:51], v[98:99], v[148:149], v[50:51] op_sel:[0,1,0] op_sel_hi:[1,1,1]
	v_pk_fma_f32 v[48:49], v[100:101], v[186:187], v[48:49] op_sel:[0,0,0] op_sel_hi:[1,0,1]
	v_pk_fma_f32 v[50:51], v[100:101], v[150:151], v[50:51] op_sel:[0,0,0] op_sel_hi:[1,0,1]
	v_pk_fma_f32 v[48:49], v[102:103], v[186:187], v[48:49] op_sel:[0,1,0] op_sel_hi:[1,1,1]
	v_pk_fma_f32 v[50:51], v[102:103], v[150:151], v[50:51] op_sel:[0,1,0] op_sel_hi:[1,1,1]
	v_pk_fma_f32 v[48:49], v[104:105], v[188:189], v[48:49] op_sel:[0,0,0] op_sel_hi:[1,0,1]
	v_pk_fma_f32 v[50:51], v[104:105], v[152:153], v[50:51] op_sel:[0,0,0] op_sel_hi:[1,0,1]
	v_pk_fma_f32 v[48:49], v[106:107], v[188:189], v[48:49] op_sel:[0,1,0] op_sel_hi:[1,1,1]
	v_pk_fma_f32 v[50:51], v[106:107], v[152:153], v[50:51] op_sel:[0,1,0] op_sel_hi:[1,1,1]
	v_pk_fma_f32 v[48:49], v[108:109], v[190:191], v[48:49] op_sel:[0,0,0] op_sel_hi:[1,0,1]
	v_pk_fma_f32 v[50:51], v[108:109], v[154:155], v[50:51] op_sel:[0,0,0] op_sel_hi:[1,0,1]
	v_pk_fma_f32 v[48:49], v[110:111], v[190:191], v[48:49] op_sel:[0,1,0] op_sel_hi:[1,1,1]
	v_pk_fma_f32 v[50:51], v[110:111], v[154:155], v[50:51] op_sel:[0,1,0] op_sel_hi:[1,1,1]
	s_waitcnt lgkmcnt(11)
	ds_read_b128 v[168:171], v44 offset:40192
	ds_read_b128 v[172:175], v44 offset:40208
	ds_read_b128 v[176:179], v44 offset:40704
	ds_read_b128 v[180:183], v44 offset:40720
	ds_read_b128 v[184:187], v44 offset:40960
	ds_read_b128 v[188:191], v44 offset:40976
	ds_read_b64 v[192:193], v46 offset:39936
	ds_read_b128 v[148:151], v44 offset:41984
	ds_read_b128 v[152:155], v44 offset:42000
	v_add_f32_dpp v48, v48, v48 quad_perm:[1,0,3,2] row_mask:0xf bank_mask:0xf bound_ctrl:1
	v_add_f32_dpp v49, v49, v49 quad_perm:[1,0,3,2] row_mask:0xf bank_mask:0xf bound_ctrl:1
	v_add_f32_dpp v50, v50, v50 quad_perm:[1,0,3,2] row_mask:0xf bank_mask:0xf bound_ctrl:1
	v_add_f32_dpp v51, v51, v51 quad_perm:[1,0,3,2] row_mask:0xf bank_mask:0xf bound_ctrl:1
	v_pk_fma_f32 v[96:97], v[144:145], v[120:121], v[96:97] op_sel:[0,0,0] op_sel_hi:[1,0,1]
	v_pk_fma_f32 v[98:99], v[144:145], v[120:121], v[98:99] op_sel:[0,1,0] op_sel_hi:[1,1,1]
	v_pk_fma_f32 v[100:101], v[144:145], v[122:123], v[100:101] op_sel:[0,0,0] op_sel_hi:[1,0,1]
	v_add_f32_dpp v48, v48, v48 quad_perm:[2,3,0,1] row_mask:0xf bank_mask:0xf bound_ctrl:1
	v_add_f32_dpp v49, v49, v49 quad_perm:[2,3,0,1] row_mask:0xf bank_mask:0xf bound_ctrl:1
	v_add_f32_dpp v50, v50, v50 quad_perm:[2,3,0,1] row_mask:0xf bank_mask:0xf bound_ctrl:1
	v_add_f32_dpp v51, v51, v51 quad_perm:[2,3,0,1] row_mask:0xf bank_mask:0xf bound_ctrl:1
	v_pk_fma_f32 v[102:103], v[144:145], v[122:123], v[102:103] op_sel:[0,1,0] op_sel_hi:[1,1,1]
	v_pk_fma_f32 v[104:105], v[144:145], v[124:125], v[104:105] op_sel:[0,0,0] op_sel_hi:[1,0,1]
	v_pk_fma_f32 v[106:107], v[144:145], v[124:125], v[106:107] op_sel:[0,1,0] op_sel_hi:[1,1,1]
	v_add_f32_dpp v50, v50, v50 row_half_mirror row_mask:0xf bank_mask:0xf bound_ctrl:1
	v_add_f32_dpp v51, v51, v51 row_half_mirror row_mask:0xf bank_mask:0xf bound_ctrl:1
	v_pk_fma_f32 v[108:109], v[144:145], v[126:127], v[108:109] op_sel:[0,0,0] op_sel_hi:[1,0,1]
	s_mov_b64 exec, s[86:87]
	ds_write_b64 v45, v[48:49] offset:11776
	s_mov_b64 exec, s[0:1]
	v_pk_fma_f32 v[110:111], v[144:145], v[126:127], v[110:111] op_sel:[0,1,0] op_sel_hi:[1,1,1]
	v_pk_fma_f32 v[96:97], v[50:51], v[128:129], v[96:97] op_sel:[0,0,0] op_sel_hi:[1,0,1]
	v_pk_fma_f32 v[98:99], v[50:51], v[128:129], v[98:99] op_sel:[0,1,0] op_sel_hi:[1,1,1]
	v_pk_fma_f32 v[100:101], v[50:51], v[130:131], v[100:101] op_sel:[0,0,0] op_sel_hi:[1,0,1]
	v_pk_fma_f32 v[102:103], v[50:51], v[130:131], v[102:103] op_sel:[0,1,0] op_sel_hi:[1,1,1]
	v_pk_fma_f32 v[104:105], v[50:51], v[132:133], v[104:105] op_sel:[0,0,0] op_sel_hi:[1,0,1]
	v_pk_fma_f32 v[106:107], v[50:51], v[132:133], v[106:107] op_sel:[0,1,0] op_sel_hi:[1,1,1]
	v_pk_fma_f32 v[108:109], v[50:51], v[134:135], v[108:109] op_sel:[0,0,0] op_sel_hi:[1,0,1]
	v_pk_fma_f32 v[110:111], v[50:51], v[134:135], v[110:111] op_sel:[0,1,0] op_sel_hi:[1,1,1]
	v_pk_mul_f32 v[48:49], v[96:97], v[136:137] op_sel:[0,0] op_sel_hi:[1,0]
	v_pk_mul_f32 v[50:51], v[96:97], v[156:157] op_sel:[0,0] op_sel_hi:[1,0]
	v_pk_fma_f32 v[48:49], v[98:99], v[136:137], v[48:49] op_sel:[0,1,0] op_sel_hi:[1,1,1]
	v_pk_fma_f32 v[50:51], v[98:99], v[156:157], v[50:51] op_sel:[0,1,0] op_sel_hi:[1,1,1]
	v_pk_fma_f32 v[48:49], v[100:101], v[138:139], v[48:49] op_sel:[0,0,0] op_sel_hi:[1,0,1]
	v_pk_fma_f32 v[50:51], v[100:101], v[158:159], v[50:51] op_sel:[0,0,0] op_sel_hi:[1,0,1]
	v_pk_fma_f32 v[48:49], v[102:103], v[138:139], v[48:49] op_sel:[0,1,0] op_sel_hi:[1,1,1]
	v_pk_fma_f32 v[50:51], v[102:103], v[158:159], v[50:51] op_sel:[0,1,0] op_sel_hi:[1,1,1]
	v_pk_fma_f32 v[48:49], v[104:105], v[140:141], v[48:49] op_sel:[0,0,0] op_sel_hi:[1,0,1]
	v_pk_fma_f32 v[50:51], v[104:105], v[160:161], v[50:51] op_sel:[0,0,0] op_sel_hi:[1,0,1]
	v_pk_fma_f32 v[48:49], v[106:107], v[140:141], v[48:49] op_sel:[0,1,0] op_sel_hi:[1,1,1]
	v_pk_fma_f32 v[50:51], v[106:107], v[160:161], v[50:51] op_sel:[0,1,0] op_sel_hi:[1,1,1]
	v_pk_fma_f32 v[48:49], v[108:109], v[142:143], v[48:49] op_sel:[0,0,0] op_sel_hi:[1,0,1]
	v_pk_fma_f32 v[50:51], v[108:109], v[162:163], v[50:51] op_sel:[0,0,0] op_sel_hi:[1,0,1]
	v_pk_fma_f32 v[48:49], v[110:111], v[142:143], v[48:49] op_sel:[0,1,0] op_sel_hi:[1,1,1]
	v_pk_fma_f32 v[50:51], v[110:111], v[162:163], v[50:51] op_sel:[0,1,0] op_sel_hi:[1,1,1]
	s_waitcnt lgkmcnt(11)
; #define LAS __attribute__((address_space(3)))
; __device__ __forceinline__ float red8(float x) { x += dpp_mov<0xB1>(x); x += dpp_mov<0x4E>(x); x += dpp_mov<0x141>(x); return x; }
; __device__ __forceinline__ void scan_phase(const KP& P, LAS unsigned char* lds, const int tid, const int bx, const int G) {
;     ...
;             for (int s = 0; s < 32; ++s) {
;                 const LAS float* p = cb + s * 384;
;                 const f32x4 w0 = *(const LAS f32x4*)(p), w1 = *(const LAS f32x4*)(p + 4);
;                 const f32x4 k0 = *(const LAS f32x4*)(p + 64), k1 = *(const LAS f32x4*)(p + 68);
;                 const f32x4 a0 = *(const LAS f32x4*)(p + 128), a1 = *(const LAS f32x4*)(p + 132);
;                 const f32x4 b0 = *(const LAS f32x4*)(p + 192), b1 = *(const LAS f32x4*)(p + 196);
;                 const f32x4 r0 = *(const LAS f32x4*)(p + 256), r1 = *(const LAS f32x4*)(p + 260);
;                 const float vv = buf[(c & 1) * 12288 + s * 384 + 320 + v];
;                 f32x2 sa2 = S[0] * (f32x2){a0.x, a0.y};
;                 sa2 += S[1] * (f32x2){a0.z, a0.w}; sa2 += S[2] * (f32x2){a1.x, a1.y}; sa2 += S[3] * (f32x2){a1.z, a1.w};
;                 const float sa = red8(sa2.x + sa2.y);
;                 const f32x2 sav = {sa, sa}, vv2 = {vv, vv};
;                 S[0] = S[0] * (f32x2){w0.x, w0.y} + sav * (f32x2){b0.x, b0.y} + vv2 * (f32x2){k0.x, k0.y};
;                 S[1] = S[1] * (f32x2){w0.z, w0.w} + sav * (f32x2){b0.z, b0.w} + vv2 * (f32x2){k0.z, k0.w};
;                 S[2] = S[2] * (f32x2){w1.x, w1.y} + sav * (f32x2){b1.x, b1.y} + vv2 * (f32x2){k1.x, k1.y};
;                 S[3] = S[3] * (f32x2){w1.z, w1.w} + sav * (f32x2){b1.z, b1.w} + vv2 * (f32x2){k1.z, k1.w};
;                 f32x2 y2 = S[0] * (f32x2){r0.x, r0.y};
;                 y2 += S[1] * (f32x2){r0.z, r0.w}; y2 += S[2] * (f32x2){r1.x, r1.y}; y2 += S[3] * (f32x2){r1.z, r1.w};
;                 const float y = red8(y2.x + y2.y);
;                 if (kc == 0) ybuf[s * 64 + v] = y;
	ds_read_b128 v[120:123], v44 offset:41728
	ds_read_b128 v[124:127], v44 offset:41744
	ds_read_b128 v[128:131], v44 offset:42240
	ds_read_b128 v[132:135], v44 offset:42256
	ds_read_b128 v[136:139], v44 offset:42496
	ds_read_b128 v[140:143], v44 offset:42512
	ds_read_b64 v[144:145], v46 offset:41472
	ds_read_b128 v[156:159], v44 offset:43520
	ds_read_b128 v[160:163], v44 offset:43536
	v_add_f32_dpp v48, v48, v48 quad_perm:[1,0,3,2] row_mask:0xf bank_mask:0xf bound_ctrl:1
	v_add_f32_dpp v49, v49, v49 quad_perm:[1,0,3,2] row_mask:0xf bank_mask:0xf bound_ctrl:1
	v_add_f32_dpp v50, v50, v50 quad_perm:[1,0,3,2] row_mask:0xf bank_mask:0xf bound_ctrl:1
	v_add_f32_dpp v51, v51, v51 quad_perm:[1,0,3,2] row_mask:0xf bank_mask:0xf bound_ctrl:1
	v_pk_fma_f32 v[96:97], v[146:147], v[70:71], v[96:97] op_sel:[0,0,0] op_sel_hi:[1,0,1]
	v_pk_fma_f32 v[98:99], v[146:147], v[70:71], v[98:99] op_sel:[0,1,0] op_sel_hi:[1,1,1]
	v_pk_fma_f32 v[100:101], v[146:147], v[72:73], v[100:101] op_sel:[0,0,0] op_sel_hi:[1,0,1]
	v_add_f32_dpp v48, v48, v48 quad_perm:[2,3,0,1] row_mask:0xf bank_mask:0xf bound_ctrl:1
	v_add_f32_dpp v49, v49, v49 quad_perm:[2,3,0,1] row_mask:0xf bank_mask:0xf bound_ctrl:1
	v_add_f32_dpp v50, v50, v50 quad_perm:[2,3,0,1] row_mask:0xf bank_mask:0xf bound_ctrl:1
	v_add_f32_dpp v51, v51, v51 quad_perm:[2,3,0,1] row_mask:0xf bank_mask:0xf bound_ctrl:1
	v_pk_fma_f32 v[102:103], v[146:147], v[72:73], v[102:103] op_sel:[0,1,0] op_sel_hi:[1,1,1]
	v_pk_fma_f32 v[104:105], v[146:147], v[74:75], v[104:105] op_sel:[0,0,0] op_sel_hi:[1,0,1]
	v_pk_fma_f32 v[106:107], v[146:147], v[74:75], v[106:107] op_sel:[0,1,0] op_sel_hi:[1,1,1]
	v_add_f32_dpp v50, v50, v50 row_half_mirror row_mask:0xf bank_mask:0xf bound_ctrl:1
	v_add_f32_dpp v51, v51, v51 row_half_mirror row_mask:0xf bank_mask:0xf bound_ctrl:1
	v_pk_fma_f32 v[108:109], v[146:147], v[76:77], v[108:109] op_sel:[0,0,0] op_sel_hi:[1,0,1]
	s_mov_b64 exec, s[86:87]
	ds_write_b64 v45, v[48:49] offset:12288
	s_mov_b64 exec, s[0:1]
	v_pk_fma_f32 v[110:111], v[146:147], v[76:77], v[110:111] op_sel:[0,1,0] op_sel_hi:[1,1,1]
	v_pk_fma_f32 v[96:97], v[50:51], v[78:79], v[96:97] op_sel:[0,0,0] op_sel_hi:[1,0,1]
	v_pk_fma_f32 v[98:99], v[50:51], v[78:79], v[98:99] op_sel:[0,1,0] op_sel_hi:[1,1,1]
	v_pk_fma_f32 v[100:101], v[50:51], v[80:81], v[100:101] op_sel:[0,0,0] op_sel_hi:[1,0,1]
	v_pk_fma_f32 v[102:103], v[50:51], v[80:81], v[102:103] op_sel:[0,1,0] op_sel_hi:[1,1,1]
	v_pk_fma_f32 v[104:105], v[50:51], v[82:83], v[104:105] op_sel:[0,0,0] op_sel_hi:[1,0,1]
	v_pk_fma_f32 v[106:107], v[50:51], v[82:83], v[106:107] op_sel:[0,1,0] op_sel_hi:[1,1,1]
	v_pk_fma_f32 v[108:109], v[50:51], v[84:85], v[108:109] op_sel:[0,0,0] op_sel_hi:[1,0,1]
	v_pk_fma_f32 v[110:111], v[50:51], v[84:85], v[110:111] op_sel:[0,1,0] op_sel_hi:[1,1,1]
	v_pk_mul_f32 v[48:49], v[96:97], v[86:87] op_sel:[0,0] op_sel_hi:[1,0]
	v_pk_mul_f32 v[50:51], v[96:97], v[62:63] op_sel:[0,0] op_sel_hi:[1,0]
	v_pk_fma_f32 v[48:49], v[98:99], v[86:87], v[48:49] op_sel:[0,1,0] op_sel_hi:[1,1,1]
	v_pk_fma_f32 v[50:51], v[98:99], v[62:63], v[50:51] op_sel:[0,1,0] op_sel_hi:[1,1,1]
	v_pk_fma_f32 v[48:49], v[100:101], v[88:89], v[48:49] op_sel:[0,0,0] op_sel_hi:[1,0,1]
	v_pk_fma_f32 v[50:51], v[100:101], v[64:65], v[50:51] op_sel:[0,0,0] op_sel_hi:[1,0,1]
	v_pk_fma_f32 v[48:49], v[102:103], v[88:89], v[48:49] op_sel:[0,1,0] op_sel_hi:[1,1,1]
	v_pk_fma_f32 v[50:51], v[102:103], v[64:65], v[50:51] op_sel:[0,1,0] op_sel_hi:[1,1,1]
	v_pk_fma_f32 v[48:49], v[104:105], v[90:91], v[48:49] op_sel:[0,0,0] op_sel_hi:[1,0,1]
	v_pk_fma_f32 v[50:51], v[104:105], v[66:67], v[50:51] op_sel:[0,0,0] op_sel_hi:[1,0,1]
	v_pk_fma_f32 v[48:49], v[106:107], v[90:91], v[48:49] op_sel:[0,1,0] op_sel_hi:[1,1,1]
	v_pk_fma_f32 v[50:51], v[106:107], v[66:67], v[50:51] op_sel:[0,1,0] op_sel_hi:[1,1,1]
	v_pk_fma_f32 v[48:49], v[108:109], v[92:93], v[48:49] op_sel:[0,0,0] op_sel_hi:[1,0,1]
	v_pk_fma_f32 v[50:51], v[108:109], v[68:69], v[50:51] op_sel:[0,0,0] op_sel_hi:[1,0,1]
	v_pk_fma_f32 v[48:49], v[110:111], v[92:93], v[48:49] op_sel:[0,1,0] op_sel_hi:[1,1,1]
	v_pk_fma_f32 v[50:51], v[110:111], v[68:69], v[50:51] op_sel:[0,1,0] op_sel_hi:[1,1,1]
	s_waitcnt lgkmcnt(11)
	ds_read_b128 v[70:73], v44 offset:43264
	ds_read_b128 v[74:77], v44 offset:43280
	ds_read_b128 v[78:81], v44 offset:43776
	ds_read_b128 v[82:85], v44 offset:43792
	ds_read_b128 v[86:89], v44 offset:44032
	ds_read_b128 v[90:93], v44 offset:44048
	ds_read_b64 v[146:147], v46 offset:43008
	ds_read_b128 v[62:65], v44 offset:45056
	ds_read_b128 v[66:69], v44 offset:45072
	v_add_f32_dpp v48, v48, v48 quad_perm:[1,0,3,2] row_mask:0xf bank_mask:0xf bound_ctrl:1
	v_add_f32_dpp v49, v49, v49 quad_perm:[1,0,3,2] row_mask:0xf bank_mask:0xf bound_ctrl:1
	v_add_f32_dpp v50, v50, v50 quad_perm:[1,0,3,2] row_mask:0xf bank_mask:0xf bound_ctrl:1
	v_add_f32_dpp v51, v51, v51 quad_perm:[1,0,3,2] row_mask:0xf bank_mask:0xf bound_ctrl:1
	v_pk_fma_f32 v[96:97], v[192:193], v[168:169], v[96:97] op_sel:[0,0,0] op_sel_hi:[1,0,1]
	v_pk_fma_f32 v[98:99], v[192:193], v[168:169], v[98:99] op_sel:[0,1,0] op_sel_hi:[1,1,1]
	v_pk_fma_f32 v[100:101], v[192:193], v[170:171], v[100:101] op_sel:[0,0,0] op_sel_hi:[1,0,1]
	v_add_f32_dpp v48, v48, v48 quad_perm:[2,3,0,1] row_mask:0xf bank_mask:0xf bound_ctrl:1
	v_add_f32_dpp v49, v49, v49 quad_perm:[2,3,0,1] row_mask:0xf bank_mask:0xf bound_ctrl:1
	v_add_f32_dpp v50, v50, v50 quad_perm:[2,3,0,1] row_mask:0xf bank_mask:0xf bound_ctrl:1
	v_add_f32_dpp v51, v51, v51 quad_perm:[2,3,0,1] row_mask:0xf bank_mask:0xf bound_ctrl:1
	v_pk_fma_f32 v[102:103], v[192:193], v[170:171], v[102:103] op_sel:[0,1,0] op_sel_hi:[1,1,1]
; #define LAS __attribute__((address_space(3)))
; __device__ __forceinline__ float red8(float x) { x += dpp_mov<0xB1>(x); x += dpp_mov<0x4E>(x); x += dpp_mov<0x141>(x); return x; }
; __device__ __forceinline__ void scan_phase(const KP& P, LAS unsigned char* lds, const int tid, const int bx, const int G) {
;     ...
;             for (int s = 0; s < 32; ++s) {
;                 const LAS float* p = cb + s * 384;
;                 const f32x4 w0 = *(const LAS f32x4*)(p), w1 = *(const LAS f32x4*)(p + 4);
;                 const f32x4 k0 = *(const LAS f32x4*)(p + 64), k1 = *(const LAS f32x4*)(p + 68);
;                 const f32x4 a0 = *(const LAS f32x4*)(p + 128), a1 = *(const LAS f32x4*)(p + 132);
;                 const f32x4 b0 = *(const LAS f32x4*)(p + 192), b1 = *(const LAS f32x4*)(p + 196);
;                 const f32x4 r0 = *(const LAS f32x4*)(p + 256), r1 = *(const LAS f32x4*)(p + 260);
;                 const float vv = buf[(c & 1) * 12288 + s * 384 + 320 + v];
;                 f32x2 sa2 = S[0] * (f32x2){a0.x, a0.y};
;                 sa2 += S[1] * (f32x2){a0.z, a0.w}; sa2 += S[2] * (f32x2){a1.x, a1.y}; sa2 += S[3] * (f32x2){a1.z, a1.w};
;                 const float sa = red8(sa2.x + sa2.y);
;                 const f32x2 sav = {sa, sa}, vv2 = {vv, vv};
;                 S[0] = S[0] * (f32x2){w0.x, w0.y} + sav * (f32x2){b0.x, b0.y} + vv2 * (f32x2){k0.x, k0.y};
;                 S[1] = S[1] * (f32x2){w0.z, w0.w} + sav * (f32x2){b0.z, b0.w} + vv2 * (f32x2){k0.z, k0.w};
;                 S[2] = S[2] * (f32x2){w1.x, w1.y} + sav * (f32x2){b1.x, b1.y} + vv2 * (f32x2){k1.x, k1.y};
;                 S[3] = S[3] * (f32x2){w1.z, w1.w} + sav * (f32x2){b1.z, b1.w} + vv2 * (f32x2){k1.z, k1.w};
;                 f32x2 y2 = S[0] * (f32x2){r0.x, r0.y};
;                 y2 += S[1] * (f32x2){r0.z, r0.w}; y2 += S[2] * (f32x2){r1.x, r1.y}; y2 += S[3] * (f32x2){r1.z, r1.w};
;                 const float y = red8(y2.x + y2.y);
;                 if (kc == 0) ybuf[s * 64 + v] = y;
	v_pk_fma_f32 v[104:105], v[192:193], v[172:173], v[104:105] op_sel:[0,0,0] op_sel_hi:[1,0,1]
	v_pk_fma_f32 v[106:107], v[192:193], v[172:173], v[106:107] op_sel:[0,1,0] op_sel_hi:[1,1,1]
	v_add_f32_dpp v50, v50, v50 row_half_mirror row_mask:0xf bank_mask:0xf bound_ctrl:1
	v_add_f32_dpp v51, v51, v51 row_half_mirror row_mask:0xf bank_mask:0xf bound_ctrl:1
	v_pk_fma_f32 v[108:109], v[192:193], v[174:175], v[108:109] op_sel:[0,0,0] op_sel_hi:[1,0,1]
	s_mov_b64 exec, s[86:87]
	ds_write_b64 v45, v[48:49] offset:12800
	s_mov_b64 exec, s[0:1]
	v_pk_fma_f32 v[110:111], v[192:193], v[174:175], v[110:111] op_sel:[0,1,0] op_sel_hi:[1,1,1]
	v_pk_fma_f32 v[96:97], v[50:51], v[176:177], v[96:97] op_sel:[0,0,0] op_sel_hi:[1,0,1]
	v_pk_fma_f32 v[98:99], v[50:51], v[176:177], v[98:99] op_sel:[0,1,0] op_sel_hi:[1,1,1]
	v_pk_fma_f32 v[100:101], v[50:51], v[178:179], v[100:101] op_sel:[0,0,0] op_sel_hi:[1,0,1]
	v_pk_fma_f32 v[102:103], v[50:51], v[178:179], v[102:103] op_sel:[0,1,0] op_sel_hi:[1,1,1]
	v_pk_fma_f32 v[104:105], v[50:51], v[180:181], v[104:105] op_sel:[0,0,0] op_sel_hi:[1,0,1]
	v_pk_fma_f32 v[106:107], v[50:51], v[180:181], v[106:107] op_sel:[0,1,0] op_sel_hi:[1,1,1]
	v_pk_fma_f32 v[108:109], v[50:51], v[182:183], v[108:109] op_sel:[0,0,0] op_sel_hi:[1,0,1]
	v_pk_fma_f32 v[110:111], v[50:51], v[182:183], v[110:111] op_sel:[0,1,0] op_sel_hi:[1,1,1]
	v_pk_mul_f32 v[48:49], v[96:97], v[184:185] op_sel:[0,0] op_sel_hi:[1,0]
	v_pk_mul_f32 v[50:51], v[96:97], v[148:149] op_sel:[0,0] op_sel_hi:[1,0]
	v_pk_fma_f32 v[48:49], v[98:99], v[184:185], v[48:49] op_sel:[0,1,0] op_sel_hi:[1,1,1]
	v_pk_fma_f32 v[50:51], v[98:99], v[148:149], v[50:51] op_sel:[0,1,0] op_sel_hi:[1,1,1]
	v_pk_fma_f32 v[48:49], v[100:101], v[186:187], v[48:49] op_sel:[0,0,0] op_sel_hi:[1,0,1]
	v_pk_fma_f32 v[50:51], v[100:101], v[150:151], v[50:51] op_sel:[0,0,0] op_sel_hi:[1,0,1]
	v_pk_fma_f32 v[48:49], v[102:103], v[186:187], v[48:49] op_sel:[0,1,0] op_sel_hi:[1,1,1]
	v_pk_fma_f32 v[50:51], v[102:103], v[150:151], v[50:51] op_sel:[0,1,0] op_sel_hi:[1,1,1]
	v_pk_fma_f32 v[48:49], v[104:105], v[188:189], v[48:49] op_sel:[0,0,0] op_sel_hi:[1,0,1]
	v_pk_fma_f32 v[50:51], v[104:105], v[152:153], v[50:51] op_sel:[0,0,0] op_sel_hi:[1,0,1]
	v_pk_fma_f32 v[48:49], v[106:107], v[188:189], v[48:49] op_sel:[0,1,0] op_sel_hi:[1,1,1]
	v_pk_fma_f32 v[50:51], v[106:107], v[152:153], v[50:51] op_sel:[0,1,0] op_sel_hi:[1,1,1]
	v_pk_fma_f32 v[48:49], v[108:109], v[190:191], v[48:49] op_sel:[0,0,0] op_sel_hi:[1,0,1]
	v_pk_fma_f32 v[50:51], v[108:109], v[154:155], v[50:51] op_sel:[0,0,0] op_sel_hi:[1,0,1]
	v_pk_fma_f32 v[48:49], v[110:111], v[190:191], v[48:49] op_sel:[0,1,0] op_sel_hi:[1,1,1]
	v_pk_fma_f32 v[50:51], v[110:111], v[154:155], v[50:51] op_sel:[0,1,0] op_sel_hi:[1,1,1]
	s_waitcnt lgkmcnt(11)
	ds_read_b128 v[168:171], v44 offset:44800
	ds_read_b128 v[172:175], v44 offset:44816
	ds_read_b128 v[176:179], v44 offset:45312
	ds_read_b128 v[180:183], v44 offset:45328
	ds_read_b128 v[184:187], v44 offset:45568
	ds_read_b128 v[188:191], v44 offset:45584
	ds_read_b64 v[192:193], v46 offset:44544
	ds_read_b128 v[148:151], v44 offset:46592
	ds_read_b128 v[152:155], v44 offset:46608
	v_add_f32_dpp v48, v48, v48 quad_perm:[1,0,3,2] row_mask:0xf bank_mask:0xf bound_ctrl:1
	v_add_f32_dpp v49, v49, v49 quad_perm:[1,0,3,2] row_mask:0xf bank_mask:0xf bound_ctrl:1
	v_add_f32_dpp v50, v50, v50 quad_perm:[1,0,3,2] row_mask:0xf bank_mask:0xf bound_ctrl:1
	v_add_f32_dpp v51, v51, v51 quad_perm:[1,0,3,2] row_mask:0xf bank_mask:0xf bound_ctrl:1
	v_pk_fma_f32 v[96:97], v[144:145], v[120:121], v[96:97] op_sel:[0,0,0] op_sel_hi:[1,0,1]
	v_pk_fma_f32 v[98:99], v[144:145], v[120:121], v[98:99] op_sel:[0,1,0] op_sel_hi:[1,1,1]
	v_pk_fma_f32 v[100:101], v[144:145], v[122:123], v[100:101] op_sel:[0,0,0] op_sel_hi:[1,0,1]
	v_add_f32_dpp v48, v48, v48 quad_perm:[2,3,0,1] row_mask:0xf bank_mask:0xf bound_ctrl:1
	v_add_f32_dpp v49, v49, v49 quad_perm:[2,3,0,1] row_mask:0xf bank_mask:0xf bound_ctrl:1
	v_add_f32_dpp v50, v50, v50 quad_perm:[2,3,0,1] row_mask:0xf bank_mask:0xf bound_ctrl:1
	v_add_f32_dpp v51, v51, v51 quad_perm:[2,3,0,1] row_mask:0xf bank_mask:0xf bound_ctrl:1
	v_pk_fma_f32 v[102:103], v[144:145], v[122:123], v[102:103] op_sel:[0,1,0] op_sel_hi:[1,1,1]
	v_pk_fma_f32 v[104:105], v[144:145], v[124:125], v[104:105] op_sel:[0,0,0] op_sel_hi:[1,0,1]
	v_pk_fma_f32 v[106:107], v[144:145], v[124:125], v[106:107] op_sel:[0,1,0] op_sel_hi:[1,1,1]
	v_add_f32_dpp v50, v50, v50 row_half_mirror row_mask:0xf bank_mask:0xf bound_ctrl:1
	v_add_f32_dpp v51, v51, v51 row_half_mirror row_mask:0xf bank_mask:0xf bound_ctrl:1
	v_pk_fma_f32 v[108:109], v[144:145], v[126:127], v[108:109] op_sel:[0,0,0] op_sel_hi:[1,0,1]
	s_mov_b64 exec, s[86:87]
	ds_write_b64 v45, v[48:49] offset:13312
	s_mov_b64 exec, s[0:1]
	v_pk_fma_f32 v[110:111], v[144:145], v[126:127], v[110:111] op_sel:[0,1,0] op_sel_hi:[1,1,1]
	v_pk_fma_f32 v[96:97], v[50:51], v[128:129], v[96:97] op_sel:[0,0,0] op_sel_hi:[1,0,1]
	v_pk_fma_f32 v[98:99], v[50:51], v[128:129], v[98:99] op_sel:[0,1,0] op_sel_hi:[1,1,1]
	v_pk_fma_f32 v[100:101], v[50:51], v[130:131], v[100:101] op_sel:[0,0,0] op_sel_hi:[1,0,1]
	v_pk_fma_f32 v[102:103], v[50:51], v[130:131], v[102:103] op_sel:[0,1,0] op_sel_hi:[1,1,1]
	v_pk_fma_f32 v[104:105], v[50:51], v[132:133], v[104:105] op_sel:[0,0,0] op_sel_hi:[1,0,1]
	v_pk_fma_f32 v[106:107], v[50:51], v[132:133], v[106:107] op_sel:[0,1,0] op_sel_hi:[1,1,1]
	v_pk_fma_f32 v[108:109], v[50:51], v[134:135], v[108:109] op_sel:[0,0,0] op_sel_hi:[1,0,1]
	v_pk_fma_f32 v[110:111], v[50:51], v[134:135], v[110:111] op_sel:[0,1,0] op_sel_hi:[1,1,1]
	v_pk_mul_f32 v[48:49], v[96:97], v[136:137] op_sel:[0,0] op_sel_hi:[1,0]
	v_pk_mul_f32 v[50:51], v[96:97], v[156:157] op_sel:[0,0] op_sel_hi:[1,0]
	v_pk_fma_f32 v[48:49], v[98:99], v[136:137], v[48:49] op_sel:[0,1,0] op_sel_hi:[1,1,1]
	v_pk_fma_f32 v[50:51], v[98:99], v[156:157], v[50:51] op_sel:[0,1,0] op_sel_hi:[1,1,1]
	v_pk_fma_f32 v[48:49], v[100:101], v[138:139], v[48:49] op_sel:[0,0,0] op_sel_hi:[1,0,1]
	v_pk_fma_f32 v[50:51], v[100:101], v[158:159], v[50:51] op_sel:[0,0,0] op_sel_hi:[1,0,1]
	v_pk_fma_f32 v[48:49], v[102:103], v[138:139], v[48:49] op_sel:[0,1,0] op_sel_hi:[1,1,1]
	v_pk_fma_f32 v[50:51], v[102:103], v[158:159], v[50:51] op_sel:[0,1,0] op_sel_hi:[1,1,1]
	v_pk_fma_f32 v[48:49], v[104:105], v[140:141], v[48:49] op_sel:[0,0,0] op_sel_hi:[1,0,1]
	v_pk_fma_f32 v[50:51], v[104:105], v[160:161], v[50:51] op_sel:[0,0,0] op_sel_hi:[1,0,1]
	v_pk_fma_f32 v[48:49], v[106:107], v[140:141], v[48:49] op_sel:[0,1,0] op_sel_hi:[1,1,1]
	v_pk_fma_f32 v[50:51], v[106:107], v[160:161], v[50:51] op_sel:[0,1,0] op_sel_hi:[1,1,1]
	v_pk_fma_f32 v[48:49], v[108:109], v[142:143], v[48:49] op_sel:[0,0,0] op_sel_hi:[1,0,1]
	v_pk_fma_f32 v[50:51], v[108:109], v[162:163], v[50:51] op_sel:[0,0,0] op_sel_hi:[1,0,1]
	v_pk_fma_f32 v[48:49], v[110:111], v[142:143], v[48:49] op_sel:[0,1,0] op_sel_hi:[1,1,1]
	v_pk_fma_f32 v[50:51], v[110:111], v[162:163], v[50:51] op_sel:[0,1,0] op_sel_hi:[1,1,1]
	s_waitcnt lgkmcnt(11)
; #define LAS __attribute__((address_space(3)))
; __device__ __forceinline__ float red8(float x) { x += dpp_mov<0xB1>(x); x += dpp_mov<0x4E>(x); x += dpp_mov<0x141>(x); return x; }
; __device__ __forceinline__ void scan_phase(const KP& P, LAS unsigned char* lds, const int tid, const int bx, const int G) {
;     ...
;             for (int s = 0; s < 32; ++s) {
;                 const LAS float* p = cb + s * 384;
;                 const f32x4 w0 = *(const LAS f32x4*)(p), w1 = *(const LAS f32x4*)(p + 4);
;                 const f32x4 k0 = *(const LAS f32x4*)(p + 64), k1 = *(const LAS f32x4*)(p + 68);
;                 const f32x4 a0 = *(const LAS f32x4*)(p + 128), a1 = *(const LAS f32x4*)(p + 132);
;                 const f32x4 b0 = *(const LAS f32x4*)(p + 192), b1 = *(const LAS f32x4*)(p + 196);
;                 const f32x4 r0 = *(const LAS f32x4*)(p + 256), r1 = *(const LAS f32x4*)(p + 260);
;                 const float vv = buf[(c & 1) * 12288 + s * 384 + 320 + v];
;                 f32x2 sa2 = S[0] * (f32x2){a0.x, a0.y};
;                 sa2 += S[1] * (f32x2){a0.z, a0.w}; sa2 += S[2] * (f32x2){a1.x, a1.y}; sa2 += S[3] * (f32x2){a1.z, a1.w};
;                 const float sa = red8(sa2.x + sa2.y);
;                 const f32x2 sav = {sa, sa}, vv2 = {vv, vv};
;                 S[0] = S[0] * (f32x2){w0.x, w0.y} + sav * (f32x2){b0.x, b0.y} + vv2 * (f32x2){k0.x, k0.y};
;                 S[1] = S[1] * (f32x2){w0.z, w0.w} + sav * (f32x2){b0.z, b0.w} + vv2 * (f32x2){k0.z, k0.w};
;                 S[2] = S[2] * (f32x2){w1.x, w1.y} + sav * (f32x2){b1.x, b1.y} + vv2 * (f32x2){k1.x, k1.y};
;                 S[3] = S[3] * (f32x2){w1.z, w1.w} + sav * (f32x2){b1.z, b1.w} + vv2 * (f32x2){k1.z, k1.w};
;                 f32x2 y2 = S[0] * (f32x2){r0.x, r0.y};
;                 y2 += S[1] * (f32x2){r0.z, r0.w}; y2 += S[2] * (f32x2){r1.x, r1.y}; y2 += S[3] * (f32x2){r1.z, r1.w};
;                 const float y = red8(y2.x + y2.y);
;                 if (kc == 0) ybuf[s * 64 + v] = y;
	ds_read_b128 v[120:123], v44 offset:46336
	ds_read_b128 v[124:127], v44 offset:46352
	ds_read_b128 v[128:131], v44 offset:46848
	ds_read_b128 v[132:135], v44 offset:46864
	ds_read_b128 v[136:139], v44 offset:47104
	ds_read_b128 v[140:143], v44 offset:47120
	ds_read_b64 v[144:145], v46 offset:46080
	ds_read_b128 v[156:159], v44 offset:48128
	ds_read_b128 v[160:163], v44 offset:48144
	v_add_f32_dpp v48, v48, v48 quad_perm:[1,0,3,2] row_mask:0xf bank_mask:0xf bound_ctrl:1
	v_add_f32_dpp v49, v49, v49 quad_perm:[1,0,3,2] row_mask:0xf bank_mask:0xf bound_ctrl:1
	v_add_f32_dpp v50, v50, v50 quad_perm:[1,0,3,2] row_mask:0xf bank_mask:0xf bound_ctrl:1
	v_add_f32_dpp v51, v51, v51 quad_perm:[1,0,3,2] row_mask:0xf bank_mask:0xf bound_ctrl:1
	v_pk_fma_f32 v[96:97], v[146:147], v[70:71], v[96:97] op_sel:[0,0,0] op_sel_hi:[1,0,1]
	v_pk_fma_f32 v[98:99], v[146:147], v[70:71], v[98:99] op_sel:[0,1,0] op_sel_hi:[1,1,1]
	v_pk_fma_f32 v[100:101], v[146:147], v[72:73], v[100:101] op_sel:[0,0,0] op_sel_hi:[1,0,1]
	v_add_f32_dpp v48, v48, v48 quad_perm:[2,3,0,1] row_mask:0xf bank_mask:0xf bound_ctrl:1
	v_add_f32_dpp v49, v49, v49 quad_perm:[2,3,0,1] row_mask:0xf bank_mask:0xf bound_ctrl:1
	v_add_f32_dpp v50, v50, v50 quad_perm:[2,3,0,1] row_mask:0xf bank_mask:0xf bound_ctrl:1
	v_add_f32_dpp v51, v51, v51 quad_perm:[2,3,0,1] row_mask:0xf bank_mask:0xf bound_ctrl:1
	v_pk_fma_f32 v[102:103], v[146:147], v[72:73], v[102:103] op_sel:[0,1,0] op_sel_hi:[1,1,1]
	v_pk_fma_f32 v[104:105], v[146:147], v[74:75], v[104:105] op_sel:[0,0,0] op_sel_hi:[1,0,1]
	v_pk_fma_f32 v[106:107], v[146:147], v[74:75], v[106:107] op_sel:[0,1,0] op_sel_hi:[1,1,1]
	v_add_f32_dpp v50, v50, v50 row_half_mirror row_mask:0xf bank_mask:0xf bound_ctrl:1
	v_add_f32_dpp v51, v51, v51 row_half_mirror row_mask:0xf bank_mask:0xf bound_ctrl:1
	v_pk_fma_f32 v[108:109], v[146:147], v[76:77], v[108:109] op_sel:[0,0,0] op_sel_hi:[1,0,1]
	s_mov_b64 exec, s[86:87]
	ds_write_b64 v45, v[48:49] offset:13824
	s_mov_b64 exec, s[0:1]
	v_pk_fma_f32 v[110:111], v[146:147], v[76:77], v[110:111] op_sel:[0,1,0] op_sel_hi:[1,1,1]
	v_pk_fma_f32 v[96:97], v[50:51], v[78:79], v[96:97] op_sel:[0,0,0] op_sel_hi:[1,0,1]
	v_pk_fma_f32 v[98:99], v[50:51], v[78:79], v[98:99] op_sel:[0,1,0] op_sel_hi:[1,1,1]
	v_pk_fma_f32 v[100:101], v[50:51], v[80:81], v[100:101] op_sel:[0,0,0] op_sel_hi:[1,0,1]
	v_pk_fma_f32 v[102:103], v[50:51], v[80:81], v[102:103] op_sel:[0,1,0] op_sel_hi:[1,1,1]
	v_pk_fma_f32 v[104:105], v[50:51], v[82:83], v[104:105] op_sel:[0,0,0] op_sel_hi:[1,0,1]
	v_pk_fma_f32 v[106:107], v[50:51], v[82:83], v[106:107] op_sel:[0,1,0] op_sel_hi:[1,1,1]
	v_pk_fma_f32 v[108:109], v[50:51], v[84:85], v[108:109] op_sel:[0,0,0] op_sel_hi:[1,0,1]
	v_pk_fma_f32 v[110:111], v[50:51], v[84:85], v[110:111] op_sel:[0,1,0] op_sel_hi:[1,1,1]
	v_pk_mul_f32 v[48:49], v[96:97], v[86:87] op_sel:[0,0] op_sel_hi:[1,0]
	v_pk_mul_f32 v[50:51], v[96:97], v[62:63] op_sel:[0,0] op_sel_hi:[1,0]
	v_pk_fma_f32 v[48:49], v[98:99], v[86:87], v[48:49] op_sel:[0,1,0] op_sel_hi:[1,1,1]
	v_pk_fma_f32 v[50:51], v[98:99], v[62:63], v[50:51] op_sel:[0,1,0] op_sel_hi:[1,1,1]
	v_pk_fma_f32 v[48:49], v[100:101], v[88:89], v[48:49] op_sel:[0,0,0] op_sel_hi:[1,0,1]
	v_pk_fma_f32 v[50:51], v[100:101], v[64:65], v[50:51] op_sel:[0,0,0] op_sel_hi:[1,0,1]
	v_pk_fma_f32 v[48:49], v[102:103], v[88:89], v[48:49] op_sel:[0,1,0] op_sel_hi:[1,1,1]
	v_pk_fma_f32 v[50:51], v[102:103], v[64:65], v[50:51] op_sel:[0,1,0] op_sel_hi:[1,1,1]
	v_pk_fma_f32 v[48:49], v[104:105], v[90:91], v[48:49] op_sel:[0,0,0] op_sel_hi:[1,0,1]
	v_pk_fma_f32 v[50:51], v[104:105], v[66:67], v[50:51] op_sel:[0,0,0] op_sel_hi:[1,0,1]
	v_pk_fma_f32 v[48:49], v[106:107], v[90:91], v[48:49] op_sel:[0,1,0] op_sel_hi:[1,1,1]
	v_pk_fma_f32 v[50:51], v[106:107], v[66:67], v[50:51] op_sel:[0,1,0] op_sel_hi:[1,1,1]
	v_pk_fma_f32 v[48:49], v[108:109], v[92:93], v[48:49] op_sel:[0,0,0] op_sel_hi:[1,0,1]
	v_pk_fma_f32 v[50:51], v[108:109], v[68:69], v[50:51] op_sel:[0,0,0] op_sel_hi:[1,0,1]
	v_pk_fma_f32 v[48:49], v[110:111], v[92:93], v[48:49] op_sel:[0,1,0] op_sel_hi:[1,1,1]
	v_pk_fma_f32 v[50:51], v[110:111], v[68:69], v[50:51] op_sel:[0,1,0] op_sel_hi:[1,1,1]
	s_waitcnt lgkmcnt(11)
	ds_read_b128 v[70:73], v44 offset:47872
	ds_read_b128 v[74:77], v44 offset:47888
	ds_read_b128 v[78:81], v44 offset:48384
	ds_read_b128 v[82:85], v44 offset:48400
	ds_read_b128 v[86:89], v44 offset:48640
	ds_read_b128 v[90:93], v44 offset:48656
	ds_read_b64 v[146:147], v46 offset:47616
	v_add_f32_dpp v48, v48, v48 quad_perm:[1,0,3,2] row_mask:0xf bank_mask:0xf bound_ctrl:1
	v_add_f32_dpp v49, v49, v49 quad_perm:[1,0,3,2] row_mask:0xf bank_mask:0xf bound_ctrl:1
	v_add_f32_dpp v50, v50, v50 quad_perm:[1,0,3,2] row_mask:0xf bank_mask:0xf bound_ctrl:1
	v_add_f32_dpp v51, v51, v51 quad_perm:[1,0,3,2] row_mask:0xf bank_mask:0xf bound_ctrl:1
	v_pk_fma_f32 v[96:97], v[192:193], v[168:169], v[96:97] op_sel:[0,0,0] op_sel_hi:[1,0,1]
	v_pk_fma_f32 v[98:99], v[192:193], v[168:169], v[98:99] op_sel:[0,1,0] op_sel_hi:[1,1,1]
	v_pk_fma_f32 v[100:101], v[192:193], v[170:171], v[100:101] op_sel:[0,0,0] op_sel_hi:[1,0,1]
	v_add_f32_dpp v48, v48, v48 quad_perm:[2,3,0,1] row_mask:0xf bank_mask:0xf bound_ctrl:1
	v_add_f32_dpp v49, v49, v49 quad_perm:[2,3,0,1] row_mask:0xf bank_mask:0xf bound_ctrl:1
	v_add_f32_dpp v50, v50, v50 quad_perm:[2,3,0,1] row_mask:0xf bank_mask:0xf bound_ctrl:1
	v_add_f32_dpp v51, v51, v51 quad_perm:[2,3,0,1] row_mask:0xf bank_mask:0xf bound_ctrl:1
	v_pk_fma_f32 v[102:103], v[192:193], v[170:171], v[102:103] op_sel:[0,1,0] op_sel_hi:[1,1,1]
	v_pk_fma_f32 v[104:105], v[192:193], v[172:173], v[104:105] op_sel:[0,0,0] op_sel_hi:[1,0,1]
; #define LAS __attribute__((address_space(3)))
; __device__ __forceinline__ float red8(float x) { x += dpp_mov<0xB1>(x); x += dpp_mov<0x4E>(x); x += dpp_mov<0x141>(x); return x; }
; __device__ __forceinline__ void scan_phase(const KP& P, LAS unsigned char* lds, const int tid, const int bx, const int G) {
;     ...
;             for (int s = 0; s < 32; ++s) {
;                 const LAS float* p = cb + s * 384;
;                 const f32x4 w0 = *(const LAS f32x4*)(p), w1 = *(const LAS f32x4*)(p + 4);
;                 const f32x4 k0 = *(const LAS f32x4*)(p + 64), k1 = *(const LAS f32x4*)(p + 68);
;                 const f32x4 a0 = *(const LAS f32x4*)(p + 128), a1 = *(const LAS f32x4*)(p + 132);
;                 const f32x4 b0 = *(const LAS f32x4*)(p + 192), b1 = *(const LAS f32x4*)(p + 196);
;                 const f32x4 r0 = *(const LAS f32x4*)(p + 256), r1 = *(const LAS f32x4*)(p + 260);
;                 const float vv = buf[(c & 1) * 12288 + s * 384 + 320 + v];
;                 f32x2 sa2 = S[0] * (f32x2){a0.x, a0.y};
;                 sa2 += S[1] * (f32x2){a0.z, a0.w}; sa2 += S[2] * (f32x2){a1.x, a1.y}; sa2 += S[3] * (f32x2){a1.z, a1.w};
;                 const float sa = red8(sa2.x + sa2.y);
;                 const f32x2 sav = {sa, sa}, vv2 = {vv, vv};
;                 S[0] = S[0] * (f32x2){w0.x, w0.y} + sav * (f32x2){b0.x, b0.y} + vv2 * (f32x2){k0.x, k0.y};
;                 S[1] = S[1] * (f32x2){w0.z, w0.w} + sav * (f32x2){b0.z, b0.w} + vv2 * (f32x2){k0.z, k0.w};
;                 S[2] = S[2] * (f32x2){w1.x, w1.y} + sav * (f32x2){b1.x, b1.y} + vv2 * (f32x2){k1.x, k1.y};
;                 S[3] = S[3] * (f32x2){w1.z, w1.w} + sav * (f32x2){b1.z, b1.w} + vv2 * (f32x2){k1.z, k1.w};
;                 f32x2 y2 = S[0] * (f32x2){r0.x, r0.y};
;                 y2 += S[1] * (f32x2){r0.z, r0.w}; y2 += S[2] * (f32x2){r1.x, r1.y}; y2 += S[3] * (f32x2){r1.z, r1.w};
;                 const float y = red8(y2.x + y2.y);
;                 if (kc == 0) ybuf[s * 64 + v] = y;
	v_pk_fma_f32 v[106:107], v[192:193], v[172:173], v[106:107] op_sel:[0,1,0] op_sel_hi:[1,1,1]
	v_add_f32_dpp v50, v50, v50 row_half_mirror row_mask:0xf bank_mask:0xf bound_ctrl:1
	v_add_f32_dpp v51, v51, v51 row_half_mirror row_mask:0xf bank_mask:0xf bound_ctrl:1
	v_pk_fma_f32 v[108:109], v[192:193], v[174:175], v[108:109] op_sel:[0,0,0] op_sel_hi:[1,0,1]
	s_mov_b64 exec, s[86:87]
	ds_write_b64 v45, v[48:49] offset:14336
	s_mov_b64 exec, s[0:1]
	v_pk_fma_f32 v[110:111], v[192:193], v[174:175], v[110:111] op_sel:[0,1,0] op_sel_hi:[1,1,1]
	v_pk_fma_f32 v[96:97], v[50:51], v[176:177], v[96:97] op_sel:[0,0,0] op_sel_hi:[1,0,1]
	v_pk_fma_f32 v[98:99], v[50:51], v[176:177], v[98:99] op_sel:[0,1,0] op_sel_hi:[1,1,1]
	v_pk_fma_f32 v[100:101], v[50:51], v[178:179], v[100:101] op_sel:[0,0,0] op_sel_hi:[1,0,1]
	v_pk_fma_f32 v[102:103], v[50:51], v[178:179], v[102:103] op_sel:[0,1,0] op_sel_hi:[1,1,1]
	v_pk_fma_f32 v[104:105], v[50:51], v[180:181], v[104:105] op_sel:[0,0,0] op_sel_hi:[1,0,1]
	v_pk_fma_f32 v[106:107], v[50:51], v[180:181], v[106:107] op_sel:[0,1,0] op_sel_hi:[1,1,1]
	v_pk_fma_f32 v[108:109], v[50:51], v[182:183], v[108:109] op_sel:[0,0,0] op_sel_hi:[1,0,1]
	v_pk_fma_f32 v[110:111], v[50:51], v[182:183], v[110:111] op_sel:[0,1,0] op_sel_hi:[1,1,1]
	v_pk_mul_f32 v[48:49], v[96:97], v[184:185] op_sel:[0,0] op_sel_hi:[1,0]
	v_pk_mul_f32 v[50:51], v[96:97], v[148:149] op_sel:[0,0] op_sel_hi:[1,0]
	v_pk_fma_f32 v[48:49], v[98:99], v[184:185], v[48:49] op_sel:[0,1,0] op_sel_hi:[1,1,1]
	v_pk_fma_f32 v[50:51], v[98:99], v[148:149], v[50:51] op_sel:[0,1,0] op_sel_hi:[1,1,1]
	v_pk_fma_f32 v[48:49], v[100:101], v[186:187], v[48:49] op_sel:[0,0,0] op_sel_hi:[1,0,1]
	v_pk_fma_f32 v[50:51], v[100:101], v[150:151], v[50:51] op_sel:[0,0,0] op_sel_hi:[1,0,1]
	v_pk_fma_f32 v[48:49], v[102:103], v[186:187], v[48:49] op_sel:[0,1,0] op_sel_hi:[1,1,1]
	v_pk_fma_f32 v[50:51], v[102:103], v[150:151], v[50:51] op_sel:[0,1,0] op_sel_hi:[1,1,1]
	v_pk_fma_f32 v[48:49], v[104:105], v[188:189], v[48:49] op_sel:[0,0,0] op_sel_hi:[1,0,1]
	v_pk_fma_f32 v[50:51], v[104:105], v[152:153], v[50:51] op_sel:[0,0,0] op_sel_hi:[1,0,1]
	v_pk_fma_f32 v[48:49], v[106:107], v[188:189], v[48:49] op_sel:[0,1,0] op_sel_hi:[1,1,1]
	v_pk_fma_f32 v[50:51], v[106:107], v[152:153], v[50:51] op_sel:[0,1,0] op_sel_hi:[1,1,1]
	v_pk_fma_f32 v[48:49], v[108:109], v[190:191], v[48:49] op_sel:[0,0,0] op_sel_hi:[1,0,1]
	v_pk_fma_f32 v[50:51], v[108:109], v[154:155], v[50:51] op_sel:[0,0,0] op_sel_hi:[1,0,1]
	v_pk_fma_f32 v[48:49], v[110:111], v[190:191], v[48:49] op_sel:[0,1,0] op_sel_hi:[1,1,1]
	v_pk_fma_f32 v[50:51], v[110:111], v[154:155], v[50:51] op_sel:[0,1,0] op_sel_hi:[1,1,1]
	s_waitcnt lgkmcnt(9)
	s_nop 1
	v_add_f32_dpp v48, v48, v48 quad_perm:[1,0,3,2] row_mask:0xf bank_mask:0xf bound_ctrl:1
	v_add_f32_dpp v49, v49, v49 quad_perm:[1,0,3,2] row_mask:0xf bank_mask:0xf bound_ctrl:1
	v_add_f32_dpp v50, v50, v50 quad_perm:[1,0,3,2] row_mask:0xf bank_mask:0xf bound_ctrl:1
	v_add_f32_dpp v51, v51, v51 quad_perm:[1,0,3,2] row_mask:0xf bank_mask:0xf bound_ctrl:1
	v_pk_fma_f32 v[96:97], v[144:145], v[120:121], v[96:97] op_sel:[0,0,0] op_sel_hi:[1,0,1]
	v_pk_fma_f32 v[98:99], v[144:145], v[120:121], v[98:99] op_sel:[0,1,0] op_sel_hi:[1,1,1]
	v_pk_fma_f32 v[100:101], v[144:145], v[122:123], v[100:101] op_sel:[0,0,0] op_sel_hi:[1,0,1]
	v_add_f32_dpp v48, v48, v48 quad_perm:[2,3,0,1] row_mask:0xf bank_mask:0xf bound_ctrl:1
	v_add_f32_dpp v49, v49, v49 quad_perm:[2,3,0,1] row_mask:0xf bank_mask:0xf bound_ctrl:1
	v_add_f32_dpp v50, v50, v50 quad_perm:[2,3,0,1] row_mask:0xf bank_mask:0xf bound_ctrl:1
	v_add_f32_dpp v51, v51, v51 quad_perm:[2,3,0,1] row_mask:0xf bank_mask:0xf bound_ctrl:1
	v_pk_fma_f32 v[102:103], v[144:145], v[122:123], v[102:103] op_sel:[0,1,0] op_sel_hi:[1,1,1]
	v_pk_fma_f32 v[104:105], v[144:145], v[124:125], v[104:105] op_sel:[0,0,0] op_sel_hi:[1,0,1]
	v_pk_fma_f32 v[106:107], v[144:145], v[124:125], v[106:107] op_sel:[0,1,0] op_sel_hi:[1,1,1]
	v_add_f32_dpp v50, v50, v50 row_half_mirror row_mask:0xf bank_mask:0xf bound_ctrl:1
	v_add_f32_dpp v51, v51, v51 row_half_mirror row_mask:0xf bank_mask:0xf bound_ctrl:1
	v_pk_fma_f32 v[108:109], v[144:145], v[126:127], v[108:109] op_sel:[0,0,0] op_sel_hi:[1,0,1]
	s_mov_b64 exec, s[86:87]
	ds_write_b64 v45, v[48:49] offset:14848
	s_mov_b64 exec, s[0:1]
	v_pk_fma_f32 v[110:111], v[144:145], v[126:127], v[110:111] op_sel:[0,1,0] op_sel_hi:[1,1,1]
	v_pk_fma_f32 v[96:97], v[50:51], v[128:129], v[96:97] op_sel:[0,0,0] op_sel_hi:[1,0,1]
	v_pk_fma_f32 v[98:99], v[50:51], v[128:129], v[98:99] op_sel:[0,1,0] op_sel_hi:[1,1,1]
	v_pk_fma_f32 v[100:101], v[50:51], v[130:131], v[100:101] op_sel:[0,0,0] op_sel_hi:[1,0,1]
	v_pk_fma_f32 v[102:103], v[50:51], v[130:131], v[102:103] op_sel:[0,1,0] op_sel_hi:[1,1,1]
	v_pk_fma_f32 v[104:105], v[50:51], v[132:133], v[104:105] op_sel:[0,0,0] op_sel_hi:[1,0,1]
	v_pk_fma_f32 v[106:107], v[50:51], v[132:133], v[106:107] op_sel:[0,1,0] op_sel_hi:[1,1,1]
	v_pk_fma_f32 v[108:109], v[50:51], v[134:135], v[108:109] op_sel:[0,0,0] op_sel_hi:[1,0,1]
	v_pk_fma_f32 v[110:111], v[50:51], v[134:135], v[110:111] op_sel:[0,1,0] op_sel_hi:[1,1,1]
	v_pk_mul_f32 v[48:49], v[96:97], v[136:137] op_sel:[0,0] op_sel_hi:[1,0]
	v_pk_mul_f32 v[50:51], v[96:97], v[156:157] op_sel:[0,0] op_sel_hi:[1,0]
	v_pk_fma_f32 v[48:49], v[98:99], v[136:137], v[48:49] op_sel:[0,1,0] op_sel_hi:[1,1,1]
	v_pk_fma_f32 v[50:51], v[98:99], v[156:157], v[50:51] op_sel:[0,1,0] op_sel_hi:[1,1,1]
	v_pk_fma_f32 v[48:49], v[100:101], v[138:139], v[48:49] op_sel:[0,0,0] op_sel_hi:[1,0,1]
	v_pk_fma_f32 v[50:51], v[100:101], v[158:159], v[50:51] op_sel:[0,0,0] op_sel_hi:[1,0,1]
	v_pk_fma_f32 v[48:49], v[102:103], v[138:139], v[48:49] op_sel:[0,1,0] op_sel_hi:[1,1,1]
	v_pk_fma_f32 v[50:51], v[102:103], v[158:159], v[50:51] op_sel:[0,1,0] op_sel_hi:[1,1,1]
	v_pk_fma_f32 v[48:49], v[104:105], v[140:141], v[48:49] op_sel:[0,0,0] op_sel_hi:[1,0,1]
	v_pk_fma_f32 v[50:51], v[104:105], v[160:161], v[50:51] op_sel:[0,0,0] op_sel_hi:[1,0,1]
	v_pk_fma_f32 v[48:49], v[106:107], v[140:141], v[48:49] op_sel:[0,1,0] op_sel_hi:[1,1,1]
	v_pk_fma_f32 v[50:51], v[106:107], v[160:161], v[50:51] op_sel:[0,1,0] op_sel_hi:[1,1,1]
	v_pk_fma_f32 v[48:49], v[108:109], v[142:143], v[48:49] op_sel:[0,0,0] op_sel_hi:[1,0,1]
	v_pk_fma_f32 v[50:51], v[108:109], v[162:163], v[50:51] op_sel:[0,0,0] op_sel_hi:[1,0,1]
	v_pk_fma_f32 v[48:49], v[110:111], v[142:143], v[48:49] op_sel:[0,1,0] op_sel_hi:[1,1,1]
	v_pk_fma_f32 v[50:51], v[110:111], v[162:163], v[50:51] op_sel:[0,1,0] op_sel_hi:[1,1,1]
	s_waitcnt lgkmcnt(2)
; __device__ __forceinline__ float red8(float x) { x += dpp_mov<0xB1>(x); x += dpp_mov<0x4E>(x); x += dpp_mov<0x141>(x); return x; }
; __device__ __forceinline__ void scan_phase(const KP& P, LAS unsigned char* lds, const int tid, const int bx, const int G) {
;     ...
;                 f32x2 sa2 = S[0] * (f32x2){a0.x, a0.y};
;                 sa2 += S[1] * (f32x2){a0.z, a0.w}; sa2 += S[2] * (f32x2){a1.x, a1.y}; sa2 += S[3] * (f32x2){a1.z, a1.w};
;                 const float sa = red8(sa2.x + sa2.y);
;                 const f32x2 sav = {sa, sa}, vv2 = {vv, vv};
;                 S[0] = S[0] * (f32x2){w0.x, w0.y} + sav * (f32x2){b0.x, b0.y} + vv2 * (f32x2){k0.x, k0.y};
;                 S[1] = S[1] * (f32x2){w0.z, w0.w} + sav * (f32x2){b0.z, b0.w} + vv2 * (f32x2){k0.z, k0.w};
;                 S[2] = S[2] * (f32x2){w1.x, w1.y} + sav * (f32x2){b1.x, b1.y} + vv2 * (f32x2){k1.x, k1.y};
;                 S[3] = S[3] * (f32x2){w1.z, w1.w} + sav * (f32x2){b1.z, b1.w} + vv2 * (f32x2){k1.z, k1.w};
;                 f32x2 y2 = S[0] * (f32x2){r0.x, r0.y};
;                 y2 += S[1] * (f32x2){r0.z, r0.w}; y2 += S[2] * (f32x2){r1.x, r1.y}; y2 += S[3] * (f32x2){r1.z, r1.w};
;                 const float y = red8(y2.x + y2.y);
;                 if (kc == 0) ybuf[s * 64 + v] = y;
	s_nop 1
	v_add_f32_dpp v48, v48, v48 quad_perm:[1,0,3,2] row_mask:0xf bank_mask:0xf bound_ctrl:1
	v_add_f32_dpp v49, v49, v49 quad_perm:[1,0,3,2] row_mask:0xf bank_mask:0xf bound_ctrl:1
	v_add_f32_dpp v50, v50, v50 quad_perm:[1,0,3,2] row_mask:0xf bank_mask:0xf bound_ctrl:1
	v_add_f32_dpp v51, v51, v51 quad_perm:[1,0,3,2] row_mask:0xf bank_mask:0xf bound_ctrl:1
	v_pk_fma_f32 v[96:97], v[146:147], v[70:71], v[96:97] op_sel:[0,0,0] op_sel_hi:[1,0,1]
	v_pk_fma_f32 v[98:99], v[146:147], v[70:71], v[98:99] op_sel:[0,1,0] op_sel_hi:[1,1,1]
	v_pk_fma_f32 v[100:101], v[146:147], v[72:73], v[100:101] op_sel:[0,0,0] op_sel_hi:[1,0,1]
	v_add_f32_dpp v48, v48, v48 quad_perm:[2,3,0,1] row_mask:0xf bank_mask:0xf bound_ctrl:1
	v_add_f32_dpp v49, v49, v49 quad_perm:[2,3,0,1] row_mask:0xf bank_mask:0xf bound_ctrl:1
	v_add_f32_dpp v50, v50, v50 quad_perm:[2,3,0,1] row_mask:0xf bank_mask:0xf bound_ctrl:1
	v_add_f32_dpp v51, v51, v51 quad_perm:[2,3,0,1] row_mask:0xf bank_mask:0xf bound_ctrl:1
	v_pk_fma_f32 v[102:103], v[146:147], v[72:73], v[102:103] op_sel:[0,1,0] op_sel_hi:[1,1,1]
	v_pk_fma_f32 v[104:105], v[146:147], v[74:75], v[104:105] op_sel:[0,0,0] op_sel_hi:[1,0,1]
	v_pk_fma_f32 v[106:107], v[146:147], v[74:75], v[106:107] op_sel:[0,1,0] op_sel_hi:[1,1,1]
	v_add_f32_dpp v50, v50, v50 row_half_mirror row_mask:0xf bank_mask:0xf bound_ctrl:1
	v_add_f32_dpp v51, v51, v51 row_half_mirror row_mask:0xf bank_mask:0xf bound_ctrl:1
	v_pk_fma_f32 v[108:109], v[146:147], v[76:77], v[108:109] op_sel:[0,0,0] op_sel_hi:[1,0,1]
	s_mov_b64 exec, s[86:87]
	ds_write_b64 v45, v[48:49] offset:15360
	s_mov_b64 exec, s[0:1]
	v_pk_fma_f32 v[110:111], v[146:147], v[76:77], v[110:111] op_sel:[0,1,0] op_sel_hi:[1,1,1]
	v_pk_fma_f32 v[96:97], v[50:51], v[78:79], v[96:97] op_sel:[0,0,0] op_sel_hi:[1,0,1]
	v_pk_fma_f32 v[98:99], v[50:51], v[78:79], v[98:99] op_sel:[0,1,0] op_sel_hi:[1,1,1]
	v_pk_fma_f32 v[100:101], v[50:51], v[80:81], v[100:101] op_sel:[0,0,0] op_sel_hi:[1,0,1]
	v_pk_fma_f32 v[102:103], v[50:51], v[80:81], v[102:103] op_sel:[0,1,0] op_sel_hi:[1,1,1]
	v_pk_fma_f32 v[104:105], v[50:51], v[82:83], v[104:105] op_sel:[0,0,0] op_sel_hi:[1,0,1]
	v_pk_fma_f32 v[106:107], v[50:51], v[82:83], v[106:107] op_sel:[0,1,0] op_sel_hi:[1,1,1]
	v_pk_fma_f32 v[108:109], v[50:51], v[84:85], v[108:109] op_sel:[0,0,0] op_sel_hi:[1,0,1]
	v_pk_fma_f32 v[110:111], v[50:51], v[84:85], v[110:111] op_sel:[0,1,0] op_sel_hi:[1,1,1]
	v_pk_mul_f32 v[48:49], v[96:97], v[86:87] op_sel:[0,0] op_sel_hi:[1,0]
	s_nop 0
	v_pk_fma_f32 v[48:49], v[98:99], v[86:87], v[48:49] op_sel:[0,1,0] op_sel_hi:[1,1,1]
	s_nop 0
	v_pk_fma_f32 v[48:49], v[100:101], v[88:89], v[48:49] op_sel:[0,0,0] op_sel_hi:[1,0,1]
	s_nop 0
	v_pk_fma_f32 v[48:49], v[102:103], v[88:89], v[48:49] op_sel:[0,1,0] op_sel_hi:[1,1,1]
	s_nop 0
	v_pk_fma_f32 v[48:49], v[104:105], v[90:91], v[48:49] op_sel:[0,0,0] op_sel_hi:[1,0,1]
	s_nop 0
	v_pk_fma_f32 v[48:49], v[106:107], v[90:91], v[48:49] op_sel:[0,1,0] op_sel_hi:[1,1,1]
	s_nop 0
	v_pk_fma_f32 v[48:49], v[108:109], v[92:93], v[48:49] op_sel:[0,0,0] op_sel_hi:[1,0,1]
	s_nop 0
	v_pk_fma_f32 v[48:49], v[110:111], v[92:93], v[48:49] op_sel:[0,1,0] op_sel_hi:[1,1,1]
	s_nop 0
	v_pk_mul_f32 v[96:97], v[96:97], v[112:113] op_sel:[0,0] op_sel_hi:[1,0]
	v_pk_mul_f32 v[98:99], v[98:99], v[112:113] op_sel:[0,1] op_sel_hi:[1,1]
	v_pk_mul_f32 v[100:101], v[100:101], v[114:115] op_sel:[0,0] op_sel_hi:[1,0]
	v_pk_mul_f32 v[102:103], v[102:103], v[114:115] op_sel:[0,1] op_sel_hi:[1,1]
	v_pk_mul_f32 v[104:105], v[104:105], v[116:117] op_sel:[0,0] op_sel_hi:[1,0]
	v_pk_mul_f32 v[106:107], v[106:107], v[116:117] op_sel:[0,1] op_sel_hi:[1,1]
	v_pk_mul_f32 v[108:109], v[108:109], v[118:119] op_sel:[0,0] op_sel_hi:[1,0]
	v_pk_mul_f32 v[110:111], v[110:111], v[118:119] op_sel:[0,1] op_sel_hi:[1,1]
	v_add_f32_dpp v48, v48, v48 quad_perm:[1,0,3,2] row_mask:0xf bank_mask:0xf bound_ctrl:1
	v_add_f32_dpp v49, v49, v49 quad_perm:[1,0,3,2] row_mask:0xf bank_mask:0xf bound_ctrl:1
	s_nop 1
	v_add_f32_dpp v48, v48, v48 quad_perm:[2,3,0,1] row_mask:0xf bank_mask:0xf bound_ctrl:1
	v_add_f32_dpp v49, v49, v49 quad_perm:[2,3,0,1] row_mask:0xf bank_mask:0xf bound_ctrl:1
	s_nop 1
	s_mov_b64 exec, s[86:87]
	ds_write_b64 v45, v[48:49] offset:15872
	s_mov_b64 exec, s[0:1]
